# phase-0 mod_item k-loop hand-scheduled (16 loads in flight, straight FMA) + straight-line silu staging; LRU gate math uses bare v_sqrt_f32 instead of hipcc IEEE sqrt expansion
# speedup vs baseline: 1.0108x; 1.0108x over previous
; DEVI float sigmoidf_(float x) { return __builtin_amdgcn_rcpf(1.f + __expf(-x)); }
; #define otid() otid_(p.wv)
; DEVI void mod_item(const Params& p, int item) {
;   float* sv = (float*)smem;
;   float* red = sv + 9 * 1024;
;   const int tid = otid(), l = item / 144, n0 = (item % 144) * 64;
;   for (int i = tid; i < 9 * 1024; i += NTHREADS) { const int r = i >> 10, k = i & 1023; const float cv = r < 8 ? p.in[1][r * 1024 + k] : p.in[3][k]; sv[i] = cv * sigmoidf_(cv); }
;   __syncthreads();
.LBB0_25:
	s_andn2_b64 vcc, exec, s[0:1]
	s_cbranch_vccnz .LBB0_35
	v_mbcnt_lo_u32_b32 v4, -1, 0
	v_mbcnt_hi_u32_b32 v4, -1, v4
	s_movk_i32 s0, 0x2400
	v_or_b32_e32 v120, s33, v4
	v_cmp_gt_i32_e32 vcc, s0, v120
	s_and_saveexec_b64 s[0:1], vcc
	v_readlane_b32 s36, v252, 14
	v_readlane_b32 s38, v252, 16
	v_readlane_b32 s39, v252, 17
	v_readlane_b32 s42, v252, 20
	v_readlane_b32 s43, v252, 21
	v_readlane_b32 s37, v252, 15
	v_readlane_b32 s40, v252, 18
	v_readlane_b32 s41, v252, 19
	v_readlane_b32 s44, v252, 22
	v_readlane_b32 s45, v252, 23
	v_readlane_b32 s46, v252, 24
	v_readlane_b32 s47, v252, 25
	v_readlane_b32 s48, v252, 26
	v_readlane_b32 s49, v252, 27
	v_readlane_b32 s50, v252, 28
	v_readlane_b32 s51, v252, 29
	s_cbranch_execz .LBB0_29
	v_lshlrev_b32_e32 v5, 2, v120
	s_mov_b64 s[4:5], s[38:39]
	global_load_dword v6, v5, s[4:5]
	global_load_dword v7, v5, s[4:5] offset:2048
	s_add_u32 s4, s4, 0x1000
	s_addc_u32 s5, s5, 0
	global_load_dword v8, v5, s[4:5]
	global_load_dword v9, v5, s[4:5] offset:2048
	s_add_u32 s4, s4, 0x1000
	s_addc_u32 s5, s5, 0
	global_load_dword v10, v5, s[4:5]
	global_load_dword v11, v5, s[4:5] offset:2048
	s_add_u32 s4, s4, 0x1000
	s_addc_u32 s5, s5, 0
	global_load_dword v12, v5, s[4:5]
	global_load_dword v13, v5, s[4:5] offset:2048
	s_add_u32 s4, s4, 0x1000
	s_addc_u32 s5, s5, 0
	global_load_dword v14, v5, s[4:5]
	global_load_dword v15, v5, s[4:5] offset:2048
	s_add_u32 s4, s4, 0x1000
	s_addc_u32 s5, s5, 0
	global_load_dword v16, v5, s[4:5]
	global_load_dword v17, v5, s[4:5] offset:2048
	s_add_u32 s4, s4, 0x1000
	s_addc_u32 s5, s5, 0
	global_load_dword v18, v5, s[4:5]
	global_load_dword v19, v5, s[4:5] offset:2048
	s_add_u32 s4, s4, 0x1000
	s_addc_u32 s5, s5, 0
	global_load_dword v20, v5, s[4:5]
	global_load_dword v21, v5, s[4:5] offset:2048
	s_add_u32 s4, s4, 0x1000
	s_addc_u32 s5, s5, 0
	global_load_dword v22, v5, s[42:43]
	global_load_dword v23, v5, s[42:43] offset:2048
	s_waitcnt vmcnt(12)
	v_mul_f32_e32 v24, 0xbfb8aa3b, v6
	v_mul_f32_e32 v25, 0xbfb8aa3b, v7
	v_mul_f32_e32 v26, 0xbfb8aa3b, v8
	v_mul_f32_e32 v27, 0xbfb8aa3b, v9
	v_mul_f32_e32 v28, 0xbfb8aa3b, v10
	v_mul_f32_e32 v29, 0xbfb8aa3b, v11
	v_exp_f32_e32 v24, v24
	v_exp_f32_e32 v25, v25
	v_exp_f32_e32 v26, v26
	v_exp_f32_e32 v27, v27
	v_exp_f32_e32 v28, v28
	v_exp_f32_e32 v29, v29
	v_add_f32_e32 v24, 1.0, v24
	v_add_f32_e32 v25, 1.0, v25
	v_add_f32_e32 v26, 1.0, v26
	v_add_f32_e32 v27, 1.0, v27
	v_add_f32_e32 v28, 1.0, v28
	v_add_f32_e32 v29, 1.0, v29
	v_rcp_f32_e32 v24, v24
	v_rcp_f32_e32 v25, v25
	v_rcp_f32_e32 v26, v26
	v_rcp_f32_e32 v27, v27
	v_rcp_f32_e32 v28, v28
	v_rcp_f32_e32 v29, v29
	v_mul_f32_e32 v6, v6, v24
	v_mul_f32_e32 v7, v7, v25
	v_mul_f32_e32 v8, v8, v26
	v_mul_f32_e32 v9, v9, v27
	v_mul_f32_e32 v10, v10, v28
	v_mul_f32_e32 v11, v11, v29
	ds_write_b32 v5, v6
	ds_write_b32 v5, v7 offset:2048
	ds_write_b32 v5, v8 offset:4096
	ds_write_b32 v5, v9 offset:6144
	ds_write_b32 v5, v10 offset:8192
	ds_write_b32 v5, v11 offset:10240
	s_waitcnt vmcnt(6)
	v_mul_f32_e32 v30, 0xbfb8aa3b, v12
	v_mul_f32_e32 v31, 0xbfb8aa3b, v13
	v_mul_f32_e32 v32, 0xbfb8aa3b, v14
	v_mul_f32_e32 v33, 0xbfb8aa3b, v15
	v_mul_f32_e32 v34, 0xbfb8aa3b, v16
	v_mul_f32_e32 v35, 0xbfb8aa3b, v17
	v_exp_f32_e32 v30, v30
	v_exp_f32_e32 v31, v31
	v_exp_f32_e32 v32, v32
	v_exp_f32_e32 v33, v33
	v_exp_f32_e32 v34, v34
	v_exp_f32_e32 v35, v35
	v_add_f32_e32 v30, 1.0, v30
	v_add_f32_e32 v31, 1.0, v31
	v_add_f32_e32 v32, 1.0, v32
	v_add_f32_e32 v33, 1.0, v33
	v_add_f32_e32 v34, 1.0, v34
	v_add_f32_e32 v35, 1.0, v35
	v_rcp_f32_e32 v30, v30
	v_rcp_f32_e32 v31, v31
	v_rcp_f32_e32 v32, v32
	v_rcp_f32_e32 v33, v33
	v_rcp_f32_e32 v34, v34
	v_rcp_f32_e32 v35, v35
	v_mul_f32_e32 v12, v12, v30
	v_mul_f32_e32 v13, v13, v31
	v_mul_f32_e32 v14, v14, v32
	v_mul_f32_e32 v15, v15, v33
	v_mul_f32_e32 v16, v16, v34
	v_mul_f32_e32 v17, v17, v35
	ds_write_b32 v5, v12 offset:12288
	ds_write_b32 v5, v13 offset:14336
	ds_write_b32 v5, v14 offset:16384
	ds_write_b32 v5, v15 offset:18432
	ds_write_b32 v5, v16 offset:20480
	ds_write_b32 v5, v17 offset:22528
	s_waitcnt vmcnt(0)
	v_mul_f32_e32 v36, 0xbfb8aa3b, v18
	v_mul_f32_e32 v37, 0xbfb8aa3b, v19
	v_mul_f32_e32 v38, 0xbfb8aa3b, v20
	v_mul_f32_e32 v39, 0xbfb8aa3b, v21
	v_mul_f32_e32 v40, 0xbfb8aa3b, v22
	v_mul_f32_e32 v41, 0xbfb8aa3b, v23
	v_exp_f32_e32 v36, v36
	v_exp_f32_e32 v37, v37
	v_exp_f32_e32 v38, v38
	v_exp_f32_e32 v39, v39
	v_exp_f32_e32 v40, v40
	v_exp_f32_e32 v41, v41
	v_add_f32_e32 v36, 1.0, v36
	v_add_f32_e32 v37, 1.0, v37
	v_add_f32_e32 v38, 1.0, v38
	v_add_f32_e32 v39, 1.0, v39
	v_add_f32_e32 v40, 1.0, v40
	v_add_f32_e32 v41, 1.0, v41
	v_rcp_f32_e32 v36, v36
	v_rcp_f32_e32 v37, v37
	v_rcp_f32_e32 v38, v38
	v_rcp_f32_e32 v39, v39
	v_rcp_f32_e32 v40, v40
	v_rcp_f32_e32 v41, v41
	v_mul_f32_e32 v18, v18, v36
	v_mul_f32_e32 v19, v19, v37
	v_mul_f32_e32 v20, v20, v38
	v_mul_f32_e32 v21, v21, v39
	v_mul_f32_e32 v22, v22, v40
	v_mul_f32_e32 v23, v23, v41
	ds_write_b32 v5, v18 offset:24576
	ds_write_b32 v5, v19 offset:26624
	ds_write_b32 v5, v20 offset:28672
	ds_write_b32 v5, v21 offset:30720
	ds_write_b32 v5, v22 offset:32768
	ds_write_b32 v5, v23 offset:34816

; DEVI void mod_item(const Params& p, int item) {
;     ...
;   for (int k4 = 0; k4 < 32; ++k4) {
;     const int k = kq * 128 + k4 * 4;
;     const float w0 = w[(size_t)k * 9216], w1 = w[(size_t)(k + 1) * 9216], w2 = w[(size_t)(k + 2) * 9216], w3 = w[(size_t)(k + 3) * 9216];
; #pragma unroll
;     for (int r = 0; r < 9; ++r) { const float4 s4 = *(const float4*)(sv + r * 1024 + k); acc[r] += s4.x * w0 + s4.y * w1 + s4.z * w2 + s4.w * w3; }
;   }
.LBB0_30:
	s_mov_b64 s[40:41], 0x9000
	global_load_dword v2, v[124:125], off
	v_lshl_add_u64 v[124:125], v[124:125], 0, s[40:41]
	global_load_dword v3, v[124:125], off
	v_lshl_add_u64 v[124:125], v[124:125], 0, s[40:41]
	global_load_dword v4, v[124:125], off
	v_lshl_add_u64 v[124:125], v[124:125], 0, s[40:41]
	global_load_dword v5, v[124:125], off
	v_lshl_add_u64 v[124:125], v[124:125], 0, s[40:41]
	global_load_dword v6, v[124:125], off
	v_lshl_add_u64 v[124:125], v[124:125], 0, s[40:41]
	global_load_dword v7, v[124:125], off
	v_lshl_add_u64 v[124:125], v[124:125], 0, s[40:41]
	global_load_dword v8, v[124:125], off
	v_lshl_add_u64 v[124:125], v[124:125], 0, s[40:41]
	global_load_dword v9, v[124:125], off
	v_lshl_add_u64 v[124:125], v[124:125], 0, s[40:41]
	global_load_dword v10, v[124:125], off
	v_lshl_add_u64 v[124:125], v[124:125], 0, s[40:41]
	global_load_dword v11, v[124:125], off
	v_lshl_add_u64 v[124:125], v[124:125], 0, s[40:41]
	global_load_dword v12, v[124:125], off
	v_lshl_add_u64 v[124:125], v[124:125], 0, s[40:41]
	global_load_dword v13, v[124:125], off
	v_lshl_add_u64 v[124:125], v[124:125], 0, s[40:41]
	global_load_dword v14, v[124:125], off
	v_lshl_add_u64 v[124:125], v[124:125], 0, s[40:41]
	global_load_dword v15, v[124:125], off
	v_lshl_add_u64 v[124:125], v[124:125], 0, s[40:41]
	global_load_dword v16, v[124:125], off
	v_lshl_add_u64 v[124:125], v[124:125], 0, s[40:41]
	global_load_dword v17, v[124:125], off
	v_lshl_add_u64 v[124:125], v[124:125], 0, s[40:41]
	ds_read_b128 v[34:37], v121
	ds_read_b128 v[38:41], v121 offset:4096
	ds_read_b128 v[42:45], v121 offset:8192
	ds_read_b128 v[46:49], v121 offset:12288
	ds_read_b128 v[50:53], v121 offset:16384
	ds_read_b128 v[54:57], v121 offset:20480
	ds_read_b128 v[58:61], v121 offset:24576
	ds_read_b128 v[62:65], v121 offset:28672
	ds_read_b128 v[66:69], v121 offset:32768
	global_load_dword v18, v[124:125], off
	v_lshl_add_u64 v[124:125], v[124:125], 0, s[40:41]
	global_load_dword v19, v[124:125], off
	v_lshl_add_u64 v[124:125], v[124:125], 0, s[40:41]
	global_load_dword v20, v[124:125], off
	v_lshl_add_u64 v[124:125], v[124:125], 0, s[40:41]
	global_load_dword v21, v[124:125], off
	v_lshl_add_u64 v[124:125], v[124:125], 0, s[40:41]
	global_load_dword v22, v[124:125], off
	v_lshl_add_u64 v[124:125], v[124:125], 0, s[40:41]
	global_load_dword v23, v[124:125], off
	v_lshl_add_u64 v[124:125], v[124:125], 0, s[40:41]
	global_load_dword v24, v[124:125], off
	v_lshl_add_u64 v[124:125], v[124:125], 0, s[40:41]
	global_load_dword v25, v[124:125], off
	v_lshl_add_u64 v[124:125], v[124:125], 0, s[40:41]
	global_load_dword v26, v[124:125], off
	v_lshl_add_u64 v[124:125], v[124:125], 0, s[40:41]
	global_load_dword v27, v[124:125], off
	v_lshl_add_u64 v[124:125], v[124:125], 0, s[40:41]
	global_load_dword v28, v[124:125], off
	v_lshl_add_u64 v[124:125], v[124:125], 0, s[40:41]
	global_load_dword v29, v[124:125], off
	v_lshl_add_u64 v[124:125], v[124:125], 0, s[40:41]
	global_load_dword v30, v[124:125], off
	v_lshl_add_u64 v[124:125], v[124:125], 0, s[40:41]
	global_load_dword v31, v[124:125], off
	v_lshl_add_u64 v[124:125], v[124:125], 0, s[40:41]
	global_load_dword v32, v[124:125], off
	v_lshl_add_u64 v[124:125], v[124:125], 0, s[40:41]
	global_load_dword v33, v[124:125], off
	v_lshl_add_u64 v[124:125], v[124:125], 0, s[40:41]
	ds_read_b128 v[70:73], v121 offset:16
	ds_read_b128 v[74:77], v121 offset:4112
	ds_read_b128 v[78:81], v121 offset:8208
	ds_read_b128 v[82:85], v121 offset:12304
	ds_read_b128 v[86:89], v121 offset:16400
	ds_read_b128 v[90:93], v121 offset:20496
	ds_read_b128 v[94:97], v121 offset:24592
	ds_read_b128 v[98:101], v121 offset:28688
	ds_read_b128 v[102:105], v121 offset:32784
	s_waitcnt lgkmcnt(9)
	s_waitcnt vmcnt(28)
	v_fmac_f32_e32 v126, v34, v2
	v_fmac_f32_e32 v127, v38, v2
	v_fmac_f32_e32 v128, v42, v2
	v_fmac_f32_e32 v129, v46, v2
	v_fmac_f32_e32 v130, v50, v2
	v_fmac_f32_e32 v131, v54, v2
	v_fmac_f32_e32 v132, v58, v2
	v_fmac_f32_e32 v133, v62, v2
	v_fmac_f32_e32 v151, v66, v2
	v_fmac_f32_e32 v126, v35, v3
	v_fmac_f32_e32 v127, v39, v3
	v_fmac_f32_e32 v128, v43, v3
	v_fmac_f32_e32 v129, v47, v3
	v_fmac_f32_e32 v130, v51, v3
	v_fmac_f32_e32 v131, v55, v3
	v_fmac_f32_e32 v132, v59, v3
	v_fmac_f32_e32 v133, v63, v3
	v_fmac_f32_e32 v151, v67, v3
	v_fmac_f32_e32 v126, v36, v4
	v_fmac_f32_e32 v127, v40, v4
	v_fmac_f32_e32 v128, v44, v4
	v_fmac_f32_e32 v129, v48, v4
	v_fmac_f32_e32 v130, v52, v4
	v_fmac_f32_e32 v131, v56, v4
	v_fmac_f32_e32 v132, v60, v4
	v_fmac_f32_e32 v133, v64, v4
	v_fmac_f32_e32 v151, v68, v4
	v_fmac_f32_e32 v126, v37, v5
	v_fmac_f32_e32 v127, v41, v5
	v_fmac_f32_e32 v128, v45, v5
	v_fmac_f32_e32 v129, v49, v5
	v_fmac_f32_e32 v130, v53, v5
	v_fmac_f32_e32 v131, v57, v5
	v_fmac_f32_e32 v132, v61, v5
	v_fmac_f32_e32 v133, v65, v5
	v_fmac_f32_e32 v151, v69, v5
	ds_read_b128 v[34:37], v121 offset:32
	ds_read_b128 v[38:41], v121 offset:4128
	ds_read_b128 v[42:45], v121 offset:8224
	ds_read_b128 v[46:49], v121 offset:12320
	ds_read_b128 v[50:53], v121 offset:16416
	ds_read_b128 v[54:57], v121 offset:20512
	ds_read_b128 v[58:61], v121 offset:24608
	ds_read_b128 v[62:65], v121 offset:28704
	ds_read_b128 v[66:69], v121 offset:32800
	s_waitcnt lgkmcnt(9)
	s_waitcnt vmcnt(24)
; DEVI void mod_item(const Params& p, int item) {
;     ...
;   for (int k4 = 0; k4 < 32; ++k4) {
;     const int k = kq * 128 + k4 * 4;
;     const float w0 = w[(size_t)k * 9216], w1 = w[(size_t)(k + 1) * 9216], w2 = w[(size_t)(k + 2) * 9216], w3 = w[(size_t)(k + 3) * 9216];
; #pragma unroll
;     for (int r = 0; r < 9; ++r) { const float4 s4 = *(const float4*)(sv + r * 1024 + k); acc[r] += s4.x * w0 + s4.y * w1 + s4.z * w2 + s4.w * w3; }
;   }
	v_fmac_f32_e32 v126, v70, v6
	v_fmac_f32_e32 v127, v74, v6
	v_fmac_f32_e32 v128, v78, v6
	v_fmac_f32_e32 v129, v82, v6
	v_fmac_f32_e32 v130, v86, v6
	v_fmac_f32_e32 v131, v90, v6
	v_fmac_f32_e32 v132, v94, v6
	v_fmac_f32_e32 v133, v98, v6
	v_fmac_f32_e32 v151, v102, v6
	v_fmac_f32_e32 v126, v71, v7
	v_fmac_f32_e32 v127, v75, v7
	v_fmac_f32_e32 v128, v79, v7
	v_fmac_f32_e32 v129, v83, v7
	v_fmac_f32_e32 v130, v87, v7
	v_fmac_f32_e32 v131, v91, v7
	v_fmac_f32_e32 v132, v95, v7
	v_fmac_f32_e32 v133, v99, v7
	v_fmac_f32_e32 v151, v103, v7
	v_fmac_f32_e32 v126, v72, v8
	v_fmac_f32_e32 v127, v76, v8
	v_fmac_f32_e32 v128, v80, v8
	v_fmac_f32_e32 v129, v84, v8
	v_fmac_f32_e32 v130, v88, v8
	v_fmac_f32_e32 v131, v92, v8
	v_fmac_f32_e32 v132, v96, v8
	v_fmac_f32_e32 v133, v100, v8
	v_fmac_f32_e32 v151, v104, v8
	v_fmac_f32_e32 v126, v73, v9
	v_fmac_f32_e32 v127, v77, v9
	v_fmac_f32_e32 v128, v81, v9
	v_fmac_f32_e32 v129, v85, v9
	v_fmac_f32_e32 v130, v89, v9
	v_fmac_f32_e32 v131, v93, v9
	v_fmac_f32_e32 v132, v97, v9
	v_fmac_f32_e32 v133, v101, v9
	v_fmac_f32_e32 v151, v105, v9
	ds_read_b128 v[70:73], v121 offset:48
	ds_read_b128 v[74:77], v121 offset:4144
	ds_read_b128 v[78:81], v121 offset:8240
	ds_read_b128 v[82:85], v121 offset:12336
	ds_read_b128 v[86:89], v121 offset:16432
	ds_read_b128 v[90:93], v121 offset:20528
	ds_read_b128 v[94:97], v121 offset:24624
	ds_read_b128 v[98:101], v121 offset:28720
	ds_read_b128 v[102:105], v121 offset:32816
	s_waitcnt lgkmcnt(9)
	s_waitcnt vmcnt(20)
	v_fmac_f32_e32 v126, v34, v10
	v_fmac_f32_e32 v127, v38, v10
	v_fmac_f32_e32 v128, v42, v10
	v_fmac_f32_e32 v129, v46, v10
	v_fmac_f32_e32 v130, v50, v10
	v_fmac_f32_e32 v131, v54, v10
	v_fmac_f32_e32 v132, v58, v10
	v_fmac_f32_e32 v133, v62, v10
	v_fmac_f32_e32 v151, v66, v10
	v_fmac_f32_e32 v126, v35, v11
	v_fmac_f32_e32 v127, v39, v11
	v_fmac_f32_e32 v128, v43, v11
	v_fmac_f32_e32 v129, v47, v11
	v_fmac_f32_e32 v130, v51, v11
	v_fmac_f32_e32 v131, v55, v11
	v_fmac_f32_e32 v132, v59, v11
	v_fmac_f32_e32 v133, v63, v11
	v_fmac_f32_e32 v151, v67, v11
	v_fmac_f32_e32 v126, v36, v12
	v_fmac_f32_e32 v127, v40, v12
	v_fmac_f32_e32 v128, v44, v12
	v_fmac_f32_e32 v129, v48, v12
	v_fmac_f32_e32 v130, v52, v12
	v_fmac_f32_e32 v131, v56, v12
	v_fmac_f32_e32 v132, v60, v12
	v_fmac_f32_e32 v133, v64, v12
	v_fmac_f32_e32 v151, v68, v12
	v_fmac_f32_e32 v126, v37, v13
	v_fmac_f32_e32 v127, v41, v13
	v_fmac_f32_e32 v128, v45, v13
	v_fmac_f32_e32 v129, v49, v13
	v_fmac_f32_e32 v130, v53, v13
	v_fmac_f32_e32 v131, v57, v13
	v_fmac_f32_e32 v132, v61, v13
	v_fmac_f32_e32 v133, v65, v13
	v_fmac_f32_e32 v151, v69, v13
	ds_read_b128 v[34:37], v121 offset:64
	ds_read_b128 v[38:41], v121 offset:4160
	ds_read_b128 v[42:45], v121 offset:8256
	ds_read_b128 v[46:49], v121 offset:12352
	ds_read_b128 v[50:53], v121 offset:16448
	ds_read_b128 v[54:57], v121 offset:20544
	ds_read_b128 v[58:61], v121 offset:24640
	ds_read_b128 v[62:65], v121 offset:28736
	ds_read_b128 v[66:69], v121 offset:32832
	s_waitcnt lgkmcnt(9)
	s_waitcnt vmcnt(16)
	v_fmac_f32_e32 v126, v70, v14
	v_fmac_f32_e32 v127, v74, v14
	v_fmac_f32_e32 v128, v78, v14
	v_fmac_f32_e32 v129, v82, v14
	v_fmac_f32_e32 v130, v86, v14
	v_fmac_f32_e32 v131, v90, v14
	v_fmac_f32_e32 v132, v94, v14
	v_fmac_f32_e32 v133, v98, v14
	v_fmac_f32_e32 v151, v102, v14
	v_fmac_f32_e32 v126, v71, v15
	v_fmac_f32_e32 v127, v75, v15
	v_fmac_f32_e32 v128, v79, v15
	v_fmac_f32_e32 v129, v83, v15
	v_fmac_f32_e32 v130, v87, v15
	v_fmac_f32_e32 v131, v91, v15
	v_fmac_f32_e32 v132, v95, v15
	v_fmac_f32_e32 v133, v99, v15
	v_fmac_f32_e32 v151, v103, v15
	v_fmac_f32_e32 v126, v72, v16
	v_fmac_f32_e32 v127, v76, v16
	v_fmac_f32_e32 v128, v80, v16
	v_fmac_f32_e32 v129, v84, v16
	v_fmac_f32_e32 v130, v88, v16
	v_fmac_f32_e32 v131, v92, v16
	v_fmac_f32_e32 v132, v96, v16
	v_fmac_f32_e32 v133, v100, v16
	v_fmac_f32_e32 v151, v104, v16
	v_fmac_f32_e32 v126, v73, v17
	v_fmac_f32_e32 v127, v77, v17
	v_fmac_f32_e32 v128, v81, v17
	v_fmac_f32_e32 v129, v85, v17
	v_fmac_f32_e32 v130, v89, v17
	v_fmac_f32_e32 v131, v93, v17
	v_fmac_f32_e32 v132, v97, v17
	v_fmac_f32_e32 v133, v101, v17
	v_fmac_f32_e32 v151, v105, v17
	global_load_dword v2, v[124:125], off
	v_lshl_add_u64 v[124:125], v[124:125], 0, s[40:41]
	global_load_dword v3, v[124:125], off
	v_lshl_add_u64 v[124:125], v[124:125], 0, s[40:41]
	global_load_dword v4, v[124:125], off
	v_lshl_add_u64 v[124:125], v[124:125], 0, s[40:41]
	global_load_dword v5, v[124:125], off
	v_lshl_add_u64 v[124:125], v[124:125], 0, s[40:41]
	global_load_dword v6, v[124:125], off
	v_lshl_add_u64 v[124:125], v[124:125], 0, s[40:41]
	global_load_dword v7, v[124:125], off
	v_lshl_add_u64 v[124:125], v[124:125], 0, s[40:41]
	global_load_dword v8, v[124:125], off
	v_lshl_add_u64 v[124:125], v[124:125], 0, s[40:41]
	global_load_dword v9, v[124:125], off
	v_lshl_add_u64 v[124:125], v[124:125], 0, s[40:41]
	global_load_dword v10, v[124:125], off
	v_lshl_add_u64 v[124:125], v[124:125], 0, s[40:41]
	global_load_dword v11, v[124:125], off
	v_lshl_add_u64 v[124:125], v[124:125], 0, s[40:41]
	global_load_dword v12, v[124:125], off
	v_lshl_add_u64 v[124:125], v[124:125], 0, s[40:41]
	global_load_dword v13, v[124:125], off
	v_lshl_add_u64 v[124:125], v[124:125], 0, s[40:41]
	global_load_dword v14, v[124:125], off
	v_lshl_add_u64 v[124:125], v[124:125], 0, s[40:41]
	global_load_dword v15, v[124:125], off
	v_lshl_add_u64 v[124:125], v[124:125], 0, s[40:41]
	global_load_dword v16, v[124:125], off
	v_lshl_add_u64 v[124:125], v[124:125], 0, s[40:41]
	global_load_dword v17, v[124:125], off
	v_lshl_add_u64 v[124:125], v[124:125], 0, s[40:41]
	ds_read_b128 v[70:73], v121 offset:80
	ds_read_b128 v[74:77], v121 offset:4176
	ds_read_b128 v[78:81], v121 offset:8272
	ds_read_b128 v[82:85], v121 offset:12368
	ds_read_b128 v[86:89], v121 offset:16464
	ds_read_b128 v[90:93], v121 offset:20560
	ds_read_b128 v[94:97], v121 offset:24656
	ds_read_b128 v[98:101], v121 offset:28752
	ds_read_b128 v[102:105], v121 offset:32848
	s_waitcnt lgkmcnt(9)
; DEVI void mod_item(const Params& p, int item) {
;     ...
;   for (int k4 = 0; k4 < 32; ++k4) {
;     const int k = kq * 128 + k4 * 4;
;     const float w0 = w[(size_t)k * 9216], w1 = w[(size_t)(k + 1) * 9216], w2 = w[(size_t)(k + 2) * 9216], w3 = w[(size_t)(k + 3) * 9216];
; #pragma unroll
;     for (int r = 0; r < 9; ++r) { const float4 s4 = *(const float4*)(sv + r * 1024 + k); acc[r] += s4.x * w0 + s4.y * w1 + s4.z * w2 + s4.w * w3; }
;   }
	s_waitcnt vmcnt(28)
	v_fmac_f32_e32 v126, v34, v18
	v_fmac_f32_e32 v127, v38, v18
	v_fmac_f32_e32 v128, v42, v18
	v_fmac_f32_e32 v129, v46, v18
	v_fmac_f32_e32 v130, v50, v18
	v_fmac_f32_e32 v131, v54, v18
	v_fmac_f32_e32 v132, v58, v18
	v_fmac_f32_e32 v133, v62, v18
	v_fmac_f32_e32 v151, v66, v18
	v_fmac_f32_e32 v126, v35, v19
	v_fmac_f32_e32 v127, v39, v19
	v_fmac_f32_e32 v128, v43, v19
	v_fmac_f32_e32 v129, v47, v19
	v_fmac_f32_e32 v130, v51, v19
	v_fmac_f32_e32 v131, v55, v19
	v_fmac_f32_e32 v132, v59, v19
	v_fmac_f32_e32 v133, v63, v19
	v_fmac_f32_e32 v151, v67, v19
	v_fmac_f32_e32 v126, v36, v20
	v_fmac_f32_e32 v127, v40, v20
	v_fmac_f32_e32 v128, v44, v20
	v_fmac_f32_e32 v129, v48, v20
	v_fmac_f32_e32 v130, v52, v20
	v_fmac_f32_e32 v131, v56, v20
	v_fmac_f32_e32 v132, v60, v20
	v_fmac_f32_e32 v133, v64, v20
	v_fmac_f32_e32 v151, v68, v20
	v_fmac_f32_e32 v126, v37, v21
	v_fmac_f32_e32 v127, v41, v21
	v_fmac_f32_e32 v128, v45, v21
	v_fmac_f32_e32 v129, v49, v21
	v_fmac_f32_e32 v130, v53, v21
	v_fmac_f32_e32 v131, v57, v21
	v_fmac_f32_e32 v132, v61, v21
	v_fmac_f32_e32 v133, v65, v21
	v_fmac_f32_e32 v151, v69, v21
	ds_read_b128 v[34:37], v121 offset:96
	ds_read_b128 v[38:41], v121 offset:4192
	ds_read_b128 v[42:45], v121 offset:8288
	ds_read_b128 v[46:49], v121 offset:12384
	ds_read_b128 v[50:53], v121 offset:16480
	ds_read_b128 v[54:57], v121 offset:20576
	ds_read_b128 v[58:61], v121 offset:24672
	ds_read_b128 v[62:65], v121 offset:28768
	ds_read_b128 v[66:69], v121 offset:32864
	s_waitcnt lgkmcnt(9)
	s_waitcnt vmcnt(24)
	v_fmac_f32_e32 v126, v70, v22
	v_fmac_f32_e32 v127, v74, v22
	v_fmac_f32_e32 v128, v78, v22
	v_fmac_f32_e32 v129, v82, v22
	v_fmac_f32_e32 v130, v86, v22
	v_fmac_f32_e32 v131, v90, v22
	v_fmac_f32_e32 v132, v94, v22
	v_fmac_f32_e32 v133, v98, v22
	v_fmac_f32_e32 v151, v102, v22
	v_fmac_f32_e32 v126, v71, v23
	v_fmac_f32_e32 v127, v75, v23
	v_fmac_f32_e32 v128, v79, v23
	v_fmac_f32_e32 v129, v83, v23
	v_fmac_f32_e32 v130, v87, v23
	v_fmac_f32_e32 v131, v91, v23
	v_fmac_f32_e32 v132, v95, v23
	v_fmac_f32_e32 v133, v99, v23
	v_fmac_f32_e32 v151, v103, v23
	v_fmac_f32_e32 v126, v72, v24
	v_fmac_f32_e32 v127, v76, v24
	v_fmac_f32_e32 v128, v80, v24
	v_fmac_f32_e32 v129, v84, v24
	v_fmac_f32_e32 v130, v88, v24
	v_fmac_f32_e32 v131, v92, v24
	v_fmac_f32_e32 v132, v96, v24
	v_fmac_f32_e32 v133, v100, v24
	v_fmac_f32_e32 v151, v104, v24
	v_fmac_f32_e32 v126, v73, v25
	v_fmac_f32_e32 v127, v77, v25
	v_fmac_f32_e32 v128, v81, v25
	v_fmac_f32_e32 v129, v85, v25
	v_fmac_f32_e32 v130, v89, v25
	v_fmac_f32_e32 v131, v93, v25
	v_fmac_f32_e32 v132, v97, v25
	v_fmac_f32_e32 v133, v101, v25
	v_fmac_f32_e32 v151, v105, v25
	ds_read_b128 v[70:73], v121 offset:112
	ds_read_b128 v[74:77], v121 offset:4208
	ds_read_b128 v[78:81], v121 offset:8304
	ds_read_b128 v[82:85], v121 offset:12400
	ds_read_b128 v[86:89], v121 offset:16496
	ds_read_b128 v[90:93], v121 offset:20592
	ds_read_b128 v[94:97], v121 offset:24688
	ds_read_b128 v[98:101], v121 offset:28784
	ds_read_b128 v[102:105], v121 offset:32880
	s_waitcnt lgkmcnt(9)
	s_waitcnt vmcnt(20)
	v_fmac_f32_e32 v126, v34, v26
	v_fmac_f32_e32 v127, v38, v26
	v_fmac_f32_e32 v128, v42, v26
	v_fmac_f32_e32 v129, v46, v26
	v_fmac_f32_e32 v130, v50, v26
	v_fmac_f32_e32 v131, v54, v26
	v_fmac_f32_e32 v132, v58, v26
	v_fmac_f32_e32 v133, v62, v26
	v_fmac_f32_e32 v151, v66, v26
	v_fmac_f32_e32 v126, v35, v27
	v_fmac_f32_e32 v127, v39, v27
	v_fmac_f32_e32 v128, v43, v27
	v_fmac_f32_e32 v129, v47, v27
	v_fmac_f32_e32 v130, v51, v27
	v_fmac_f32_e32 v131, v55, v27
	v_fmac_f32_e32 v132, v59, v27
	v_fmac_f32_e32 v133, v63, v27
	v_fmac_f32_e32 v151, v67, v27
	v_fmac_f32_e32 v126, v36, v28
	v_fmac_f32_e32 v127, v40, v28
	v_fmac_f32_e32 v128, v44, v28
	v_fmac_f32_e32 v129, v48, v28
	v_fmac_f32_e32 v130, v52, v28
	v_fmac_f32_e32 v131, v56, v28
	v_fmac_f32_e32 v132, v60, v28
	v_fmac_f32_e32 v133, v64, v28
	v_fmac_f32_e32 v151, v68, v28
	v_fmac_f32_e32 v126, v37, v29
	v_fmac_f32_e32 v127, v41, v29
	v_fmac_f32_e32 v128, v45, v29
	v_fmac_f32_e32 v129, v49, v29
	v_fmac_f32_e32 v130, v53, v29
	v_fmac_f32_e32 v131, v57, v29
	v_fmac_f32_e32 v132, v61, v29
	v_fmac_f32_e32 v133, v65, v29
	v_fmac_f32_e32 v151, v69, v29
	ds_read_b128 v[34:37], v121 offset:128
	ds_read_b128 v[38:41], v121 offset:4224
	ds_read_b128 v[42:45], v121 offset:8320
	ds_read_b128 v[46:49], v121 offset:12416
	ds_read_b128 v[50:53], v121 offset:16512
	ds_read_b128 v[54:57], v121 offset:20608
	ds_read_b128 v[58:61], v121 offset:24704
	ds_read_b128 v[62:65], v121 offset:28800
	ds_read_b128 v[66:69], v121 offset:32896
	s_waitcnt lgkmcnt(9)
	s_waitcnt vmcnt(16)
; DEVI void mod_item(const Params& p, int item) {
;     ...
;   for (int k4 = 0; k4 < 32; ++k4) {
;     const int k = kq * 128 + k4 * 4;
;     const float w0 = w[(size_t)k * 9216], w1 = w[(size_t)(k + 1) * 9216], w2 = w[(size_t)(k + 2) * 9216], w3 = w[(size_t)(k + 3) * 9216];
; #pragma unroll
;     for (int r = 0; r < 9; ++r) { const float4 s4 = *(const float4*)(sv + r * 1024 + k); acc[r] += s4.x * w0 + s4.y * w1 + s4.z * w2 + s4.w * w3; }
;   }
	v_fmac_f32_e32 v126, v70, v30
	v_fmac_f32_e32 v127, v74, v30
	v_fmac_f32_e32 v128, v78, v30
	v_fmac_f32_e32 v129, v82, v30
	v_fmac_f32_e32 v130, v86, v30
	v_fmac_f32_e32 v131, v90, v30
	v_fmac_f32_e32 v132, v94, v30
	v_fmac_f32_e32 v133, v98, v30
	v_fmac_f32_e32 v151, v102, v30
	v_fmac_f32_e32 v126, v71, v31
	v_fmac_f32_e32 v127, v75, v31
	v_fmac_f32_e32 v128, v79, v31
	v_fmac_f32_e32 v129, v83, v31
	v_fmac_f32_e32 v130, v87, v31
	v_fmac_f32_e32 v131, v91, v31
	v_fmac_f32_e32 v132, v95, v31
	v_fmac_f32_e32 v133, v99, v31
	v_fmac_f32_e32 v151, v103, v31
	v_fmac_f32_e32 v126, v72, v32
	v_fmac_f32_e32 v127, v76, v32
	v_fmac_f32_e32 v128, v80, v32
	v_fmac_f32_e32 v129, v84, v32
	v_fmac_f32_e32 v130, v88, v32
	v_fmac_f32_e32 v131, v92, v32
	v_fmac_f32_e32 v132, v96, v32
	v_fmac_f32_e32 v133, v100, v32
	v_fmac_f32_e32 v151, v104, v32
	v_fmac_f32_e32 v126, v73, v33
	v_fmac_f32_e32 v127, v77, v33
	v_fmac_f32_e32 v128, v81, v33
	v_fmac_f32_e32 v129, v85, v33
	v_fmac_f32_e32 v130, v89, v33
	v_fmac_f32_e32 v131, v93, v33
	v_fmac_f32_e32 v132, v97, v33
	v_fmac_f32_e32 v133, v101, v33
	v_fmac_f32_e32 v151, v105, v33
	global_load_dword v18, v[124:125], off
	v_lshl_add_u64 v[124:125], v[124:125], 0, s[40:41]
	global_load_dword v19, v[124:125], off
	v_lshl_add_u64 v[124:125], v[124:125], 0, s[40:41]
	global_load_dword v20, v[124:125], off
	v_lshl_add_u64 v[124:125], v[124:125], 0, s[40:41]
	global_load_dword v21, v[124:125], off
	v_lshl_add_u64 v[124:125], v[124:125], 0, s[40:41]
	global_load_dword v22, v[124:125], off
	v_lshl_add_u64 v[124:125], v[124:125], 0, s[40:41]
	global_load_dword v23, v[124:125], off
	v_lshl_add_u64 v[124:125], v[124:125], 0, s[40:41]
	global_load_dword v24, v[124:125], off
	v_lshl_add_u64 v[124:125], v[124:125], 0, s[40:41]
	global_load_dword v25, v[124:125], off
	v_lshl_add_u64 v[124:125], v[124:125], 0, s[40:41]
	global_load_dword v26, v[124:125], off
	v_lshl_add_u64 v[124:125], v[124:125], 0, s[40:41]
	global_load_dword v27, v[124:125], off
	v_lshl_add_u64 v[124:125], v[124:125], 0, s[40:41]
	global_load_dword v28, v[124:125], off
	v_lshl_add_u64 v[124:125], v[124:125], 0, s[40:41]
	global_load_dword v29, v[124:125], off
	v_lshl_add_u64 v[124:125], v[124:125], 0, s[40:41]
	global_load_dword v30, v[124:125], off
	v_lshl_add_u64 v[124:125], v[124:125], 0, s[40:41]
	global_load_dword v31, v[124:125], off
	v_lshl_add_u64 v[124:125], v[124:125], 0, s[40:41]
	global_load_dword v32, v[124:125], off
	v_lshl_add_u64 v[124:125], v[124:125], 0, s[40:41]
	global_load_dword v33, v[124:125], off
	v_lshl_add_u64 v[124:125], v[124:125], 0, s[40:41]
	ds_read_b128 v[70:73], v121 offset:144
	ds_read_b128 v[74:77], v121 offset:4240
	ds_read_b128 v[78:81], v121 offset:8336
	ds_read_b128 v[82:85], v121 offset:12432
	ds_read_b128 v[86:89], v121 offset:16528
	ds_read_b128 v[90:93], v121 offset:20624
	ds_read_b128 v[94:97], v121 offset:24720
	ds_read_b128 v[98:101], v121 offset:28816
	ds_read_b128 v[102:105], v121 offset:32912
	s_waitcnt lgkmcnt(9)
	s_waitcnt vmcnt(28)
	v_fmac_f32_e32 v126, v34, v2
	v_fmac_f32_e32 v127, v38, v2
	v_fmac_f32_e32 v128, v42, v2
	v_fmac_f32_e32 v129, v46, v2
	v_fmac_f32_e32 v130, v50, v2
	v_fmac_f32_e32 v131, v54, v2
	v_fmac_f32_e32 v132, v58, v2
	v_fmac_f32_e32 v133, v62, v2
	v_fmac_f32_e32 v151, v66, v2
	v_fmac_f32_e32 v126, v35, v3
	v_fmac_f32_e32 v127, v39, v3
	v_fmac_f32_e32 v128, v43, v3
	v_fmac_f32_e32 v129, v47, v3
	v_fmac_f32_e32 v130, v51, v3
	v_fmac_f32_e32 v131, v55, v3
	v_fmac_f32_e32 v132, v59, v3
	v_fmac_f32_e32 v133, v63, v3
	v_fmac_f32_e32 v151, v67, v3
	v_fmac_f32_e32 v126, v36, v4
	v_fmac_f32_e32 v127, v40, v4
	v_fmac_f32_e32 v128, v44, v4
	v_fmac_f32_e32 v129, v48, v4
	v_fmac_f32_e32 v130, v52, v4
	v_fmac_f32_e32 v131, v56, v4
	v_fmac_f32_e32 v132, v60, v4
	v_fmac_f32_e32 v133, v64, v4
	v_fmac_f32_e32 v151, v68, v4
	v_fmac_f32_e32 v126, v37, v5
	v_fmac_f32_e32 v127, v41, v5
	v_fmac_f32_e32 v128, v45, v5
	v_fmac_f32_e32 v129, v49, v5
	v_fmac_f32_e32 v130, v53, v5
	v_fmac_f32_e32 v131, v57, v5
	v_fmac_f32_e32 v132, v61, v5
	v_fmac_f32_e32 v133, v65, v5
	v_fmac_f32_e32 v151, v69, v5
	ds_read_b128 v[34:37], v121 offset:160
	ds_read_b128 v[38:41], v121 offset:4256
	ds_read_b128 v[42:45], v121 offset:8352
	ds_read_b128 v[46:49], v121 offset:12448
	ds_read_b128 v[50:53], v121 offset:16544
	ds_read_b128 v[54:57], v121 offset:20640
	ds_read_b128 v[58:61], v121 offset:24736
	ds_read_b128 v[62:65], v121 offset:28832
	ds_read_b128 v[66:69], v121 offset:32928
	s_waitcnt lgkmcnt(9)
	s_waitcnt vmcnt(24)
	v_fmac_f32_e32 v126, v70, v6
	v_fmac_f32_e32 v127, v74, v6
	v_fmac_f32_e32 v128, v78, v6
	v_fmac_f32_e32 v129, v82, v6
	v_fmac_f32_e32 v130, v86, v6
	v_fmac_f32_e32 v131, v90, v6
	v_fmac_f32_e32 v132, v94, v6
	v_fmac_f32_e32 v133, v98, v6
	v_fmac_f32_e32 v151, v102, v6
	v_fmac_f32_e32 v126, v71, v7
	v_fmac_f32_e32 v127, v75, v7
	v_fmac_f32_e32 v128, v79, v7
	v_fmac_f32_e32 v129, v83, v7
	v_fmac_f32_e32 v130, v87, v7
	v_fmac_f32_e32 v131, v91, v7
	v_fmac_f32_e32 v132, v95, v7
	v_fmac_f32_e32 v133, v99, v7
	v_fmac_f32_e32 v151, v103, v7
	v_fmac_f32_e32 v126, v72, v8
	v_fmac_f32_e32 v127, v76, v8
	v_fmac_f32_e32 v128, v80, v8
	v_fmac_f32_e32 v129, v84, v8
	v_fmac_f32_e32 v130, v88, v8
	v_fmac_f32_e32 v131, v92, v8
	v_fmac_f32_e32 v132, v96, v8
	v_fmac_f32_e32 v133, v100, v8
	v_fmac_f32_e32 v151, v104, v8
	v_fmac_f32_e32 v126, v73, v9
	v_fmac_f32_e32 v127, v77, v9
	v_fmac_f32_e32 v128, v81, v9
	v_fmac_f32_e32 v129, v85, v9
	v_fmac_f32_e32 v130, v89, v9
	v_fmac_f32_e32 v131, v93, v9
	v_fmac_f32_e32 v132, v97, v9
	v_fmac_f32_e32 v133, v101, v9
	v_fmac_f32_e32 v151, v105, v9
	ds_read_b128 v[70:73], v121 offset:176
	ds_read_b128 v[74:77], v121 offset:4272
	ds_read_b128 v[78:81], v121 offset:8368
	ds_read_b128 v[82:85], v121 offset:12464
	ds_read_b128 v[86:89], v121 offset:16560
	ds_read_b128 v[90:93], v121 offset:20656
	ds_read_b128 v[94:97], v121 offset:24752
	ds_read_b128 v[98:101], v121 offset:28848
	ds_read_b128 v[102:105], v121 offset:32944
	s_waitcnt lgkmcnt(9)
; DEVI void mod_item(const Params& p, int item) {
;     ...
;   for (int k4 = 0; k4 < 32; ++k4) {
;     const int k = kq * 128 + k4 * 4;
;     const float w0 = w[(size_t)k * 9216], w1 = w[(size_t)(k + 1) * 9216], w2 = w[(size_t)(k + 2) * 9216], w3 = w[(size_t)(k + 3) * 9216];
; #pragma unroll
;     for (int r = 0; r < 9; ++r) { const float4 s4 = *(const float4*)(sv + r * 1024 + k); acc[r] += s4.x * w0 + s4.y * w1 + s4.z * w2 + s4.w * w3; }
;   }
	s_waitcnt vmcnt(20)
	v_fmac_f32_e32 v126, v34, v10
	v_fmac_f32_e32 v127, v38, v10
	v_fmac_f32_e32 v128, v42, v10
	v_fmac_f32_e32 v129, v46, v10
	v_fmac_f32_e32 v130, v50, v10
	v_fmac_f32_e32 v131, v54, v10
	v_fmac_f32_e32 v132, v58, v10
	v_fmac_f32_e32 v133, v62, v10
	v_fmac_f32_e32 v151, v66, v10
	v_fmac_f32_e32 v126, v35, v11
	v_fmac_f32_e32 v127, v39, v11
	v_fmac_f32_e32 v128, v43, v11
	v_fmac_f32_e32 v129, v47, v11
	v_fmac_f32_e32 v130, v51, v11
	v_fmac_f32_e32 v131, v55, v11
	v_fmac_f32_e32 v132, v59, v11
	v_fmac_f32_e32 v133, v63, v11
	v_fmac_f32_e32 v151, v67, v11
	v_fmac_f32_e32 v126, v36, v12
	v_fmac_f32_e32 v127, v40, v12
	v_fmac_f32_e32 v128, v44, v12
	v_fmac_f32_e32 v129, v48, v12
	v_fmac_f32_e32 v130, v52, v12
	v_fmac_f32_e32 v131, v56, v12
	v_fmac_f32_e32 v132, v60, v12
	v_fmac_f32_e32 v133, v64, v12
	v_fmac_f32_e32 v151, v68, v12
	v_fmac_f32_e32 v126, v37, v13
	v_fmac_f32_e32 v127, v41, v13
	v_fmac_f32_e32 v128, v45, v13
	v_fmac_f32_e32 v129, v49, v13
	v_fmac_f32_e32 v130, v53, v13
	v_fmac_f32_e32 v131, v57, v13
	v_fmac_f32_e32 v132, v61, v13
	v_fmac_f32_e32 v133, v65, v13
	v_fmac_f32_e32 v151, v69, v13
	ds_read_b128 v[34:37], v121 offset:192
	ds_read_b128 v[38:41], v121 offset:4288
	ds_read_b128 v[42:45], v121 offset:8384
	ds_read_b128 v[46:49], v121 offset:12480
	ds_read_b128 v[50:53], v121 offset:16576
	ds_read_b128 v[54:57], v121 offset:20672
	ds_read_b128 v[58:61], v121 offset:24768
	ds_read_b128 v[62:65], v121 offset:28864
	ds_read_b128 v[66:69], v121 offset:32960
	s_waitcnt lgkmcnt(9)
	s_waitcnt vmcnt(16)
	v_fmac_f32_e32 v126, v70, v14
	v_fmac_f32_e32 v127, v74, v14
	v_fmac_f32_e32 v128, v78, v14
	v_fmac_f32_e32 v129, v82, v14
	v_fmac_f32_e32 v130, v86, v14
	v_fmac_f32_e32 v131, v90, v14
	v_fmac_f32_e32 v132, v94, v14
	v_fmac_f32_e32 v133, v98, v14
	v_fmac_f32_e32 v151, v102, v14
	v_fmac_f32_e32 v126, v71, v15
	v_fmac_f32_e32 v127, v75, v15
	v_fmac_f32_e32 v128, v79, v15
	v_fmac_f32_e32 v129, v83, v15
	v_fmac_f32_e32 v130, v87, v15
	v_fmac_f32_e32 v131, v91, v15
	v_fmac_f32_e32 v132, v95, v15
	v_fmac_f32_e32 v133, v99, v15
	v_fmac_f32_e32 v151, v103, v15
	v_fmac_f32_e32 v126, v72, v16
	v_fmac_f32_e32 v127, v76, v16
	v_fmac_f32_e32 v128, v80, v16
	v_fmac_f32_e32 v129, v84, v16
	v_fmac_f32_e32 v130, v88, v16
	v_fmac_f32_e32 v131, v92, v16
	v_fmac_f32_e32 v132, v96, v16
	v_fmac_f32_e32 v133, v100, v16
	v_fmac_f32_e32 v151, v104, v16
	v_fmac_f32_e32 v126, v73, v17
	v_fmac_f32_e32 v127, v77, v17
	v_fmac_f32_e32 v128, v81, v17
	v_fmac_f32_e32 v129, v85, v17
	v_fmac_f32_e32 v130, v89, v17
	v_fmac_f32_e32 v131, v93, v17
	v_fmac_f32_e32 v132, v97, v17
	v_fmac_f32_e32 v133, v101, v17
	v_fmac_f32_e32 v151, v105, v17
	global_load_dword v2, v[124:125], off
	v_lshl_add_u64 v[124:125], v[124:125], 0, s[40:41]
	global_load_dword v3, v[124:125], off
	v_lshl_add_u64 v[124:125], v[124:125], 0, s[40:41]
	global_load_dword v4, v[124:125], off
	v_lshl_add_u64 v[124:125], v[124:125], 0, s[40:41]
	global_load_dword v5, v[124:125], off
	v_lshl_add_u64 v[124:125], v[124:125], 0, s[40:41]
	global_load_dword v6, v[124:125], off
	v_lshl_add_u64 v[124:125], v[124:125], 0, s[40:41]
	global_load_dword v7, v[124:125], off
	v_lshl_add_u64 v[124:125], v[124:125], 0, s[40:41]
	global_load_dword v8, v[124:125], off
	v_lshl_add_u64 v[124:125], v[124:125], 0, s[40:41]
	global_load_dword v9, v[124:125], off
	v_lshl_add_u64 v[124:125], v[124:125], 0, s[40:41]
	global_load_dword v10, v[124:125], off
	v_lshl_add_u64 v[124:125], v[124:125], 0, s[40:41]
	global_load_dword v11, v[124:125], off
	v_lshl_add_u64 v[124:125], v[124:125], 0, s[40:41]
	global_load_dword v12, v[124:125], off
	v_lshl_add_u64 v[124:125], v[124:125], 0, s[40:41]
	global_load_dword v13, v[124:125], off
	v_lshl_add_u64 v[124:125], v[124:125], 0, s[40:41]
	global_load_dword v14, v[124:125], off
	v_lshl_add_u64 v[124:125], v[124:125], 0, s[40:41]
	global_load_dword v15, v[124:125], off
	v_lshl_add_u64 v[124:125], v[124:125], 0, s[40:41]
	global_load_dword v16, v[124:125], off
	v_lshl_add_u64 v[124:125], v[124:125], 0, s[40:41]
	global_load_dword v17, v[124:125], off
	v_lshl_add_u64 v[124:125], v[124:125], 0, s[40:41]
	ds_read_b128 v[70:73], v121 offset:208
	ds_read_b128 v[74:77], v121 offset:4304
	ds_read_b128 v[78:81], v121 offset:8400
	ds_read_b128 v[82:85], v121 offset:12496
	ds_read_b128 v[86:89], v121 offset:16592
	ds_read_b128 v[90:93], v121 offset:20688
	ds_read_b128 v[94:97], v121 offset:24784
	ds_read_b128 v[98:101], v121 offset:28880
	ds_read_b128 v[102:105], v121 offset:32976
	s_waitcnt lgkmcnt(9)
	s_waitcnt vmcnt(28)
	v_fmac_f32_e32 v126, v34, v18
	v_fmac_f32_e32 v127, v38, v18
	v_fmac_f32_e32 v128, v42, v18
	v_fmac_f32_e32 v129, v46, v18
	v_fmac_f32_e32 v130, v50, v18
	v_fmac_f32_e32 v131, v54, v18
	v_fmac_f32_e32 v132, v58, v18
	v_fmac_f32_e32 v133, v62, v18
	v_fmac_f32_e32 v151, v66, v18
	v_fmac_f32_e32 v126, v35, v19
	v_fmac_f32_e32 v127, v39, v19
	v_fmac_f32_e32 v128, v43, v19
	v_fmac_f32_e32 v129, v47, v19
	v_fmac_f32_e32 v130, v51, v19
	v_fmac_f32_e32 v131, v55, v19
	v_fmac_f32_e32 v132, v59, v19
	v_fmac_f32_e32 v133, v63, v19
	v_fmac_f32_e32 v151, v67, v19
	v_fmac_f32_e32 v126, v36, v20
	v_fmac_f32_e32 v127, v40, v20
	v_fmac_f32_e32 v128, v44, v20
	v_fmac_f32_e32 v129, v48, v20
	v_fmac_f32_e32 v130, v52, v20
	v_fmac_f32_e32 v131, v56, v20
	v_fmac_f32_e32 v132, v60, v20
	v_fmac_f32_e32 v133, v64, v20
	v_fmac_f32_e32 v151, v68, v20
	v_fmac_f32_e32 v126, v37, v21
	v_fmac_f32_e32 v127, v41, v21
	v_fmac_f32_e32 v128, v45, v21
	v_fmac_f32_e32 v129, v49, v21
	v_fmac_f32_e32 v130, v53, v21
	v_fmac_f32_e32 v131, v57, v21
	v_fmac_f32_e32 v132, v61, v21
	v_fmac_f32_e32 v133, v65, v21
	v_fmac_f32_e32 v151, v69, v21
	ds_read_b128 v[34:37], v121 offset:224
	ds_read_b128 v[38:41], v121 offset:4320
	ds_read_b128 v[42:45], v121 offset:8416
	ds_read_b128 v[46:49], v121 offset:12512
	ds_read_b128 v[50:53], v121 offset:16608
	ds_read_b128 v[54:57], v121 offset:20704
	ds_read_b128 v[58:61], v121 offset:24800
	ds_read_b128 v[62:65], v121 offset:28896
	ds_read_b128 v[66:69], v121 offset:32992
	s_waitcnt lgkmcnt(9)
; DEVI void mod_item(const Params& p, int item) {
;     ...
;   for (int k4 = 0; k4 < 32; ++k4) {
;     const int k = kq * 128 + k4 * 4;
;     const float w0 = w[(size_t)k * 9216], w1 = w[(size_t)(k + 1) * 9216], w2 = w[(size_t)(k + 2) * 9216], w3 = w[(size_t)(k + 3) * 9216];
; #pragma unroll
;     for (int r = 0; r < 9; ++r) { const float4 s4 = *(const float4*)(sv + r * 1024 + k); acc[r] += s4.x * w0 + s4.y * w1 + s4.z * w2 + s4.w * w3; }
;   }
	s_waitcnt vmcnt(24)
	v_fmac_f32_e32 v126, v70, v22
	v_fmac_f32_e32 v127, v74, v22
	v_fmac_f32_e32 v128, v78, v22
	v_fmac_f32_e32 v129, v82, v22
	v_fmac_f32_e32 v130, v86, v22
	v_fmac_f32_e32 v131, v90, v22
	v_fmac_f32_e32 v132, v94, v22
	v_fmac_f32_e32 v133, v98, v22
	v_fmac_f32_e32 v151, v102, v22
	v_fmac_f32_e32 v126, v71, v23
	v_fmac_f32_e32 v127, v75, v23
	v_fmac_f32_e32 v128, v79, v23
	v_fmac_f32_e32 v129, v83, v23
	v_fmac_f32_e32 v130, v87, v23
	v_fmac_f32_e32 v131, v91, v23
	v_fmac_f32_e32 v132, v95, v23
	v_fmac_f32_e32 v133, v99, v23
	v_fmac_f32_e32 v151, v103, v23
	v_fmac_f32_e32 v126, v72, v24
	v_fmac_f32_e32 v127, v76, v24
	v_fmac_f32_e32 v128, v80, v24
	v_fmac_f32_e32 v129, v84, v24
	v_fmac_f32_e32 v130, v88, v24
	v_fmac_f32_e32 v131, v92, v24
	v_fmac_f32_e32 v132, v96, v24
	v_fmac_f32_e32 v133, v100, v24
	v_fmac_f32_e32 v151, v104, v24
	v_fmac_f32_e32 v126, v73, v25
	v_fmac_f32_e32 v127, v77, v25
	v_fmac_f32_e32 v128, v81, v25
	v_fmac_f32_e32 v129, v85, v25
	v_fmac_f32_e32 v130, v89, v25
	v_fmac_f32_e32 v131, v93, v25
	v_fmac_f32_e32 v132, v97, v25
	v_fmac_f32_e32 v133, v101, v25
	v_fmac_f32_e32 v151, v105, v25
	ds_read_b128 v[70:73], v121 offset:240
	ds_read_b128 v[74:77], v121 offset:4336
	ds_read_b128 v[78:81], v121 offset:8432
	ds_read_b128 v[82:85], v121 offset:12528
	ds_read_b128 v[86:89], v121 offset:16624
	ds_read_b128 v[90:93], v121 offset:20720
	ds_read_b128 v[94:97], v121 offset:24816
	ds_read_b128 v[98:101], v121 offset:28912
	ds_read_b128 v[102:105], v121 offset:33008
	s_waitcnt lgkmcnt(9)
	s_waitcnt vmcnt(20)
	v_fmac_f32_e32 v126, v34, v26
	v_fmac_f32_e32 v127, v38, v26
	v_fmac_f32_e32 v128, v42, v26
	v_fmac_f32_e32 v129, v46, v26
	v_fmac_f32_e32 v130, v50, v26
	v_fmac_f32_e32 v131, v54, v26
	v_fmac_f32_e32 v132, v58, v26
	v_fmac_f32_e32 v133, v62, v26
	v_fmac_f32_e32 v151, v66, v26
	v_fmac_f32_e32 v126, v35, v27
	v_fmac_f32_e32 v127, v39, v27
	v_fmac_f32_e32 v128, v43, v27
	v_fmac_f32_e32 v129, v47, v27
	v_fmac_f32_e32 v130, v51, v27
	v_fmac_f32_e32 v131, v55, v27
	v_fmac_f32_e32 v132, v59, v27
	v_fmac_f32_e32 v133, v63, v27
	v_fmac_f32_e32 v151, v67, v27
	v_fmac_f32_e32 v126, v36, v28
	v_fmac_f32_e32 v127, v40, v28
	v_fmac_f32_e32 v128, v44, v28
	v_fmac_f32_e32 v129, v48, v28
	v_fmac_f32_e32 v130, v52, v28
	v_fmac_f32_e32 v131, v56, v28
	v_fmac_f32_e32 v132, v60, v28
	v_fmac_f32_e32 v133, v64, v28
	v_fmac_f32_e32 v151, v68, v28
	v_fmac_f32_e32 v126, v37, v29
	v_fmac_f32_e32 v127, v41, v29
	v_fmac_f32_e32 v128, v45, v29
	v_fmac_f32_e32 v129, v49, v29
	v_fmac_f32_e32 v130, v53, v29
	v_fmac_f32_e32 v131, v57, v29
	v_fmac_f32_e32 v132, v61, v29
	v_fmac_f32_e32 v133, v65, v29
	v_fmac_f32_e32 v151, v69, v29
	ds_read_b128 v[34:37], v121 offset:256
	ds_read_b128 v[38:41], v121 offset:4352
	ds_read_b128 v[42:45], v121 offset:8448
	ds_read_b128 v[46:49], v121 offset:12544
	ds_read_b128 v[50:53], v121 offset:16640
	ds_read_b128 v[54:57], v121 offset:20736
	ds_read_b128 v[58:61], v121 offset:24832
	ds_read_b128 v[62:65], v121 offset:28928
	ds_read_b128 v[66:69], v121 offset:33024
	s_waitcnt lgkmcnt(9)
	s_waitcnt vmcnt(16)
	v_fmac_f32_e32 v126, v70, v30
	v_fmac_f32_e32 v127, v74, v30
	v_fmac_f32_e32 v128, v78, v30
	v_fmac_f32_e32 v129, v82, v30
	v_fmac_f32_e32 v130, v86, v30
	v_fmac_f32_e32 v131, v90, v30
	v_fmac_f32_e32 v132, v94, v30
	v_fmac_f32_e32 v133, v98, v30
	v_fmac_f32_e32 v151, v102, v30
	v_fmac_f32_e32 v126, v71, v31
	v_fmac_f32_e32 v127, v75, v31
	v_fmac_f32_e32 v128, v79, v31
	v_fmac_f32_e32 v129, v83, v31
	v_fmac_f32_e32 v130, v87, v31
	v_fmac_f32_e32 v131, v91, v31
	v_fmac_f32_e32 v132, v95, v31
	v_fmac_f32_e32 v133, v99, v31
	v_fmac_f32_e32 v151, v103, v31
	v_fmac_f32_e32 v126, v72, v32
	v_fmac_f32_e32 v127, v76, v32
	v_fmac_f32_e32 v128, v80, v32
	v_fmac_f32_e32 v129, v84, v32
	v_fmac_f32_e32 v130, v88, v32
	v_fmac_f32_e32 v131, v92, v32
	v_fmac_f32_e32 v132, v96, v32
	v_fmac_f32_e32 v133, v100, v32
	v_fmac_f32_e32 v151, v104, v32
	v_fmac_f32_e32 v126, v73, v33
	v_fmac_f32_e32 v127, v77, v33
	v_fmac_f32_e32 v128, v81, v33
	v_fmac_f32_e32 v129, v85, v33
	v_fmac_f32_e32 v130, v89, v33
	v_fmac_f32_e32 v131, v93, v33
	v_fmac_f32_e32 v132, v97, v33
	v_fmac_f32_e32 v133, v101, v33
	v_fmac_f32_e32 v151, v105, v33
	global_load_dword v18, v[124:125], off
	v_lshl_add_u64 v[124:125], v[124:125], 0, s[40:41]
	global_load_dword v19, v[124:125], off
	v_lshl_add_u64 v[124:125], v[124:125], 0, s[40:41]
	global_load_dword v20, v[124:125], off
	v_lshl_add_u64 v[124:125], v[124:125], 0, s[40:41]
	global_load_dword v21, v[124:125], off
	v_lshl_add_u64 v[124:125], v[124:125], 0, s[40:41]
	global_load_dword v22, v[124:125], off
	v_lshl_add_u64 v[124:125], v[124:125], 0, s[40:41]
	global_load_dword v23, v[124:125], off
	v_lshl_add_u64 v[124:125], v[124:125], 0, s[40:41]
	global_load_dword v24, v[124:125], off
	v_lshl_add_u64 v[124:125], v[124:125], 0, s[40:41]
	global_load_dword v25, v[124:125], off
	v_lshl_add_u64 v[124:125], v[124:125], 0, s[40:41]
	global_load_dword v26, v[124:125], off
	v_lshl_add_u64 v[124:125], v[124:125], 0, s[40:41]
	global_load_dword v27, v[124:125], off
	v_lshl_add_u64 v[124:125], v[124:125], 0, s[40:41]
	global_load_dword v28, v[124:125], off
	v_lshl_add_u64 v[124:125], v[124:125], 0, s[40:41]
	global_load_dword v29, v[124:125], off
	v_lshl_add_u64 v[124:125], v[124:125], 0, s[40:41]
	global_load_dword v30, v[124:125], off
	v_lshl_add_u64 v[124:125], v[124:125], 0, s[40:41]
	global_load_dword v31, v[124:125], off
	v_lshl_add_u64 v[124:125], v[124:125], 0, s[40:41]
	global_load_dword v32, v[124:125], off
	v_lshl_add_u64 v[124:125], v[124:125], 0, s[40:41]
	global_load_dword v33, v[124:125], off
	v_lshl_add_u64 v[124:125], v[124:125], 0, s[40:41]
	ds_read_b128 v[70:73], v121 offset:272
	ds_read_b128 v[74:77], v121 offset:4368
	ds_read_b128 v[78:81], v121 offset:8464
	ds_read_b128 v[82:85], v121 offset:12560
	ds_read_b128 v[86:89], v121 offset:16656
	ds_read_b128 v[90:93], v121 offset:20752
	ds_read_b128 v[94:97], v121 offset:24848
	ds_read_b128 v[98:101], v121 offset:28944
	ds_read_b128 v[102:105], v121 offset:33040
	s_waitcnt lgkmcnt(9)
; DEVI void mod_item(const Params& p, int item) {
;     ...
;   for (int k4 = 0; k4 < 32; ++k4) {
;     const int k = kq * 128 + k4 * 4;
;     const float w0 = w[(size_t)k * 9216], w1 = w[(size_t)(k + 1) * 9216], w2 = w[(size_t)(k + 2) * 9216], w3 = w[(size_t)(k + 3) * 9216];
; #pragma unroll
;     for (int r = 0; r < 9; ++r) { const float4 s4 = *(const float4*)(sv + r * 1024 + k); acc[r] += s4.x * w0 + s4.y * w1 + s4.z * w2 + s4.w * w3; }
;   }
	s_waitcnt vmcnt(28)
	v_fmac_f32_e32 v126, v34, v2
	v_fmac_f32_e32 v127, v38, v2
	v_fmac_f32_e32 v128, v42, v2
	v_fmac_f32_e32 v129, v46, v2
	v_fmac_f32_e32 v130, v50, v2
	v_fmac_f32_e32 v131, v54, v2
	v_fmac_f32_e32 v132, v58, v2
	v_fmac_f32_e32 v133, v62, v2
	v_fmac_f32_e32 v151, v66, v2
	v_fmac_f32_e32 v126, v35, v3
	v_fmac_f32_e32 v127, v39, v3
	v_fmac_f32_e32 v128, v43, v3
	v_fmac_f32_e32 v129, v47, v3
	v_fmac_f32_e32 v130, v51, v3
	v_fmac_f32_e32 v131, v55, v3
	v_fmac_f32_e32 v132, v59, v3
	v_fmac_f32_e32 v133, v63, v3
	v_fmac_f32_e32 v151, v67, v3
	v_fmac_f32_e32 v126, v36, v4
	v_fmac_f32_e32 v127, v40, v4
	v_fmac_f32_e32 v128, v44, v4
	v_fmac_f32_e32 v129, v48, v4
	v_fmac_f32_e32 v130, v52, v4
	v_fmac_f32_e32 v131, v56, v4
	v_fmac_f32_e32 v132, v60, v4
	v_fmac_f32_e32 v133, v64, v4
	v_fmac_f32_e32 v151, v68, v4
	v_fmac_f32_e32 v126, v37, v5
	v_fmac_f32_e32 v127, v41, v5
	v_fmac_f32_e32 v128, v45, v5
	v_fmac_f32_e32 v129, v49, v5
	v_fmac_f32_e32 v130, v53, v5
	v_fmac_f32_e32 v131, v57, v5
	v_fmac_f32_e32 v132, v61, v5
	v_fmac_f32_e32 v133, v65, v5
	v_fmac_f32_e32 v151, v69, v5
	ds_read_b128 v[34:37], v121 offset:288
	ds_read_b128 v[38:41], v121 offset:4384
	ds_read_b128 v[42:45], v121 offset:8480
	ds_read_b128 v[46:49], v121 offset:12576
	ds_read_b128 v[50:53], v121 offset:16672
	ds_read_b128 v[54:57], v121 offset:20768
	ds_read_b128 v[58:61], v121 offset:24864
	ds_read_b128 v[62:65], v121 offset:28960
	ds_read_b128 v[66:69], v121 offset:33056
	s_waitcnt lgkmcnt(9)
	s_waitcnt vmcnt(24)
	v_fmac_f32_e32 v126, v70, v6
	v_fmac_f32_e32 v127, v74, v6
	v_fmac_f32_e32 v128, v78, v6
	v_fmac_f32_e32 v129, v82, v6
	v_fmac_f32_e32 v130, v86, v6
	v_fmac_f32_e32 v131, v90, v6
	v_fmac_f32_e32 v132, v94, v6
	v_fmac_f32_e32 v133, v98, v6
	v_fmac_f32_e32 v151, v102, v6
	v_fmac_f32_e32 v126, v71, v7
	v_fmac_f32_e32 v127, v75, v7
	v_fmac_f32_e32 v128, v79, v7
	v_fmac_f32_e32 v129, v83, v7
	v_fmac_f32_e32 v130, v87, v7
	v_fmac_f32_e32 v131, v91, v7
	v_fmac_f32_e32 v132, v95, v7
	v_fmac_f32_e32 v133, v99, v7
	v_fmac_f32_e32 v151, v103, v7
	v_fmac_f32_e32 v126, v72, v8
	v_fmac_f32_e32 v127, v76, v8
	v_fmac_f32_e32 v128, v80, v8
	v_fmac_f32_e32 v129, v84, v8
	v_fmac_f32_e32 v130, v88, v8
	v_fmac_f32_e32 v131, v92, v8
	v_fmac_f32_e32 v132, v96, v8
	v_fmac_f32_e32 v133, v100, v8
	v_fmac_f32_e32 v151, v104, v8
	v_fmac_f32_e32 v126, v73, v9
	v_fmac_f32_e32 v127, v77, v9
	v_fmac_f32_e32 v128, v81, v9
	v_fmac_f32_e32 v129, v85, v9
	v_fmac_f32_e32 v130, v89, v9
	v_fmac_f32_e32 v131, v93, v9
	v_fmac_f32_e32 v132, v97, v9
	v_fmac_f32_e32 v133, v101, v9
	v_fmac_f32_e32 v151, v105, v9
	ds_read_b128 v[70:73], v121 offset:304
	ds_read_b128 v[74:77], v121 offset:4400
	ds_read_b128 v[78:81], v121 offset:8496
	ds_read_b128 v[82:85], v121 offset:12592
	ds_read_b128 v[86:89], v121 offset:16688
	ds_read_b128 v[90:93], v121 offset:20784
	ds_read_b128 v[94:97], v121 offset:24880
	ds_read_b128 v[98:101], v121 offset:28976
	ds_read_b128 v[102:105], v121 offset:33072
	s_waitcnt lgkmcnt(9)
	s_waitcnt vmcnt(20)
	v_fmac_f32_e32 v126, v34, v10
	v_fmac_f32_e32 v127, v38, v10
	v_fmac_f32_e32 v128, v42, v10
	v_fmac_f32_e32 v129, v46, v10
	v_fmac_f32_e32 v130, v50, v10
	v_fmac_f32_e32 v131, v54, v10
	v_fmac_f32_e32 v132, v58, v10
	v_fmac_f32_e32 v133, v62, v10
	v_fmac_f32_e32 v151, v66, v10
	v_fmac_f32_e32 v126, v35, v11
	v_fmac_f32_e32 v127, v39, v11
	v_fmac_f32_e32 v128, v43, v11
	v_fmac_f32_e32 v129, v47, v11
	v_fmac_f32_e32 v130, v51, v11
	v_fmac_f32_e32 v131, v55, v11
	v_fmac_f32_e32 v132, v59, v11
	v_fmac_f32_e32 v133, v63, v11
	v_fmac_f32_e32 v151, v67, v11
	v_fmac_f32_e32 v126, v36, v12
	v_fmac_f32_e32 v127, v40, v12
	v_fmac_f32_e32 v128, v44, v12
	v_fmac_f32_e32 v129, v48, v12
	v_fmac_f32_e32 v130, v52, v12
	v_fmac_f32_e32 v131, v56, v12
	v_fmac_f32_e32 v132, v60, v12
	v_fmac_f32_e32 v133, v64, v12
	v_fmac_f32_e32 v151, v68, v12
	v_fmac_f32_e32 v126, v37, v13
	v_fmac_f32_e32 v127, v41, v13
	v_fmac_f32_e32 v128, v45, v13
	v_fmac_f32_e32 v129, v49, v13
	v_fmac_f32_e32 v130, v53, v13
	v_fmac_f32_e32 v131, v57, v13
	v_fmac_f32_e32 v132, v61, v13
	v_fmac_f32_e32 v133, v65, v13
	v_fmac_f32_e32 v151, v69, v13
	ds_read_b128 v[34:37], v121 offset:320
	ds_read_b128 v[38:41], v121 offset:4416
	ds_read_b128 v[42:45], v121 offset:8512
	ds_read_b128 v[46:49], v121 offset:12608
	ds_read_b128 v[50:53], v121 offset:16704
	ds_read_b128 v[54:57], v121 offset:20800
	ds_read_b128 v[58:61], v121 offset:24896
	ds_read_b128 v[62:65], v121 offset:28992
	ds_read_b128 v[66:69], v121 offset:33088
	s_waitcnt lgkmcnt(9)
	s_waitcnt vmcnt(16)
; DEVI void mod_item(const Params& p, int item) {
;     ...
;   for (int k4 = 0; k4 < 32; ++k4) {
;     const int k = kq * 128 + k4 * 4;
;     const float w0 = w[(size_t)k * 9216], w1 = w[(size_t)(k + 1) * 9216], w2 = w[(size_t)(k + 2) * 9216], w3 = w[(size_t)(k + 3) * 9216];
; #pragma unroll
;     for (int r = 0; r < 9; ++r) { const float4 s4 = *(const float4*)(sv + r * 1024 + k); acc[r] += s4.x * w0 + s4.y * w1 + s4.z * w2 + s4.w * w3; }
;   }
	v_fmac_f32_e32 v126, v70, v14
	v_fmac_f32_e32 v127, v74, v14
	v_fmac_f32_e32 v128, v78, v14
	v_fmac_f32_e32 v129, v82, v14
	v_fmac_f32_e32 v130, v86, v14
	v_fmac_f32_e32 v131, v90, v14
	v_fmac_f32_e32 v132, v94, v14
	v_fmac_f32_e32 v133, v98, v14
	v_fmac_f32_e32 v151, v102, v14
	v_fmac_f32_e32 v126, v71, v15
	v_fmac_f32_e32 v127, v75, v15
	v_fmac_f32_e32 v128, v79, v15
	v_fmac_f32_e32 v129, v83, v15
	v_fmac_f32_e32 v130, v87, v15
	v_fmac_f32_e32 v131, v91, v15
	v_fmac_f32_e32 v132, v95, v15
	v_fmac_f32_e32 v133, v99, v15
	v_fmac_f32_e32 v151, v103, v15
	v_fmac_f32_e32 v126, v72, v16
	v_fmac_f32_e32 v127, v76, v16
	v_fmac_f32_e32 v128, v80, v16
	v_fmac_f32_e32 v129, v84, v16
	v_fmac_f32_e32 v130, v88, v16
	v_fmac_f32_e32 v131, v92, v16
	v_fmac_f32_e32 v132, v96, v16
	v_fmac_f32_e32 v133, v100, v16
	v_fmac_f32_e32 v151, v104, v16
	v_fmac_f32_e32 v126, v73, v17
	v_fmac_f32_e32 v127, v77, v17
	v_fmac_f32_e32 v128, v81, v17
	v_fmac_f32_e32 v129, v85, v17
	v_fmac_f32_e32 v130, v89, v17
	v_fmac_f32_e32 v131, v93, v17
	v_fmac_f32_e32 v132, v97, v17
	v_fmac_f32_e32 v133, v101, v17
	v_fmac_f32_e32 v151, v105, v17
	global_load_dword v2, v[124:125], off
	v_lshl_add_u64 v[124:125], v[124:125], 0, s[40:41]
	global_load_dword v3, v[124:125], off
	v_lshl_add_u64 v[124:125], v[124:125], 0, s[40:41]
	global_load_dword v4, v[124:125], off
	v_lshl_add_u64 v[124:125], v[124:125], 0, s[40:41]
	global_load_dword v5, v[124:125], off
	v_lshl_add_u64 v[124:125], v[124:125], 0, s[40:41]
	global_load_dword v6, v[124:125], off
	v_lshl_add_u64 v[124:125], v[124:125], 0, s[40:41]
	global_load_dword v7, v[124:125], off
	v_lshl_add_u64 v[124:125], v[124:125], 0, s[40:41]
	global_load_dword v8, v[124:125], off
	v_lshl_add_u64 v[124:125], v[124:125], 0, s[40:41]
	global_load_dword v9, v[124:125], off
	v_lshl_add_u64 v[124:125], v[124:125], 0, s[40:41]
	global_load_dword v10, v[124:125], off
	v_lshl_add_u64 v[124:125], v[124:125], 0, s[40:41]
	global_load_dword v11, v[124:125], off
	v_lshl_add_u64 v[124:125], v[124:125], 0, s[40:41]
	global_load_dword v12, v[124:125], off
	v_lshl_add_u64 v[124:125], v[124:125], 0, s[40:41]
	global_load_dword v13, v[124:125], off
	v_lshl_add_u64 v[124:125], v[124:125], 0, s[40:41]
	global_load_dword v14, v[124:125], off
	v_lshl_add_u64 v[124:125], v[124:125], 0, s[40:41]
	global_load_dword v15, v[124:125], off
	v_lshl_add_u64 v[124:125], v[124:125], 0, s[40:41]
	global_load_dword v16, v[124:125], off
	v_lshl_add_u64 v[124:125], v[124:125], 0, s[40:41]
	global_load_dword v17, v[124:125], off
	v_lshl_add_u64 v[124:125], v[124:125], 0, s[40:41]
	ds_read_b128 v[70:73], v121 offset:336
	ds_read_b128 v[74:77], v121 offset:4432
	ds_read_b128 v[78:81], v121 offset:8528
	ds_read_b128 v[82:85], v121 offset:12624
	ds_read_b128 v[86:89], v121 offset:16720
	ds_read_b128 v[90:93], v121 offset:20816
	ds_read_b128 v[94:97], v121 offset:24912
	ds_read_b128 v[98:101], v121 offset:29008
	ds_read_b128 v[102:105], v121 offset:33104
	s_waitcnt lgkmcnt(9)
	s_waitcnt vmcnt(28)
	v_fmac_f32_e32 v126, v34, v18
	v_fmac_f32_e32 v127, v38, v18
	v_fmac_f32_e32 v128, v42, v18
	v_fmac_f32_e32 v129, v46, v18
	v_fmac_f32_e32 v130, v50, v18
	v_fmac_f32_e32 v131, v54, v18
	v_fmac_f32_e32 v132, v58, v18
	v_fmac_f32_e32 v133, v62, v18
	v_fmac_f32_e32 v151, v66, v18
	v_fmac_f32_e32 v126, v35, v19
	v_fmac_f32_e32 v127, v39, v19
	v_fmac_f32_e32 v128, v43, v19
	v_fmac_f32_e32 v129, v47, v19
	v_fmac_f32_e32 v130, v51, v19
	v_fmac_f32_e32 v131, v55, v19
	v_fmac_f32_e32 v132, v59, v19
	v_fmac_f32_e32 v133, v63, v19
	v_fmac_f32_e32 v151, v67, v19
	v_fmac_f32_e32 v126, v36, v20
	v_fmac_f32_e32 v127, v40, v20
	v_fmac_f32_e32 v128, v44, v20
	v_fmac_f32_e32 v129, v48, v20
	v_fmac_f32_e32 v130, v52, v20
	v_fmac_f32_e32 v131, v56, v20
	v_fmac_f32_e32 v132, v60, v20
	v_fmac_f32_e32 v133, v64, v20
	v_fmac_f32_e32 v151, v68, v20
	v_fmac_f32_e32 v126, v37, v21
	v_fmac_f32_e32 v127, v41, v21
	v_fmac_f32_e32 v128, v45, v21
	v_fmac_f32_e32 v129, v49, v21
	v_fmac_f32_e32 v130, v53, v21
	v_fmac_f32_e32 v131, v57, v21
	v_fmac_f32_e32 v132, v61, v21
	v_fmac_f32_e32 v133, v65, v21
	v_fmac_f32_e32 v151, v69, v21
	ds_read_b128 v[34:37], v121 offset:352
	ds_read_b128 v[38:41], v121 offset:4448
	ds_read_b128 v[42:45], v121 offset:8544
	ds_read_b128 v[46:49], v121 offset:12640
	ds_read_b128 v[50:53], v121 offset:16736
	ds_read_b128 v[54:57], v121 offset:20832
	ds_read_b128 v[58:61], v121 offset:24928
	ds_read_b128 v[62:65], v121 offset:29024
	ds_read_b128 v[66:69], v121 offset:33120
	s_waitcnt lgkmcnt(9)
	s_waitcnt vmcnt(24)
	v_fmac_f32_e32 v126, v70, v22
	v_fmac_f32_e32 v127, v74, v22
	v_fmac_f32_e32 v128, v78, v22
	v_fmac_f32_e32 v129, v82, v22
	v_fmac_f32_e32 v130, v86, v22
	v_fmac_f32_e32 v131, v90, v22
	v_fmac_f32_e32 v132, v94, v22
	v_fmac_f32_e32 v133, v98, v22
	v_fmac_f32_e32 v151, v102, v22
	v_fmac_f32_e32 v126, v71, v23
	v_fmac_f32_e32 v127, v75, v23
	v_fmac_f32_e32 v128, v79, v23
	v_fmac_f32_e32 v129, v83, v23
	v_fmac_f32_e32 v130, v87, v23
	v_fmac_f32_e32 v131, v91, v23
	v_fmac_f32_e32 v132, v95, v23
	v_fmac_f32_e32 v133, v99, v23
	v_fmac_f32_e32 v151, v103, v23
	v_fmac_f32_e32 v126, v72, v24
	v_fmac_f32_e32 v127, v76, v24
	v_fmac_f32_e32 v128, v80, v24
	v_fmac_f32_e32 v129, v84, v24
	v_fmac_f32_e32 v130, v88, v24
	v_fmac_f32_e32 v131, v92, v24
	v_fmac_f32_e32 v132, v96, v24
	v_fmac_f32_e32 v133, v100, v24
	v_fmac_f32_e32 v151, v104, v24
	v_fmac_f32_e32 v126, v73, v25
	v_fmac_f32_e32 v127, v77, v25
	v_fmac_f32_e32 v128, v81, v25
	v_fmac_f32_e32 v129, v85, v25
	v_fmac_f32_e32 v130, v89, v25
	v_fmac_f32_e32 v131, v93, v25
	v_fmac_f32_e32 v132, v97, v25
	v_fmac_f32_e32 v133, v101, v25
	v_fmac_f32_e32 v151, v105, v25
	ds_read_b128 v[70:73], v121 offset:368
	ds_read_b128 v[74:77], v121 offset:4464
	ds_read_b128 v[78:81], v121 offset:8560
	ds_read_b128 v[82:85], v121 offset:12656
	ds_read_b128 v[86:89], v121 offset:16752
	ds_read_b128 v[90:93], v121 offset:20848
	ds_read_b128 v[94:97], v121 offset:24944
	ds_read_b128 v[98:101], v121 offset:29040
	ds_read_b128 v[102:105], v121 offset:33136
	s_waitcnt lgkmcnt(9)
; DEVI void mod_item(const Params& p, int item) {
;     ...
;   for (int k4 = 0; k4 < 32; ++k4) {
;     const int k = kq * 128 + k4 * 4;
;     const float w0 = w[(size_t)k * 9216], w1 = w[(size_t)(k + 1) * 9216], w2 = w[(size_t)(k + 2) * 9216], w3 = w[(size_t)(k + 3) * 9216];
; #pragma unroll
;     for (int r = 0; r < 9; ++r) { const float4 s4 = *(const float4*)(sv + r * 1024 + k); acc[r] += s4.x * w0 + s4.y * w1 + s4.z * w2 + s4.w * w3; }
;   }
	s_waitcnt vmcnt(20)
	v_fmac_f32_e32 v126, v34, v26
	v_fmac_f32_e32 v127, v38, v26
	v_fmac_f32_e32 v128, v42, v26
	v_fmac_f32_e32 v129, v46, v26
	v_fmac_f32_e32 v130, v50, v26
	v_fmac_f32_e32 v131, v54, v26
	v_fmac_f32_e32 v132, v58, v26
	v_fmac_f32_e32 v133, v62, v26
	v_fmac_f32_e32 v151, v66, v26
	v_fmac_f32_e32 v126, v35, v27
	v_fmac_f32_e32 v127, v39, v27
	v_fmac_f32_e32 v128, v43, v27
	v_fmac_f32_e32 v129, v47, v27
	v_fmac_f32_e32 v130, v51, v27
	v_fmac_f32_e32 v131, v55, v27
	v_fmac_f32_e32 v132, v59, v27
	v_fmac_f32_e32 v133, v63, v27
	v_fmac_f32_e32 v151, v67, v27
	v_fmac_f32_e32 v126, v36, v28
	v_fmac_f32_e32 v127, v40, v28
	v_fmac_f32_e32 v128, v44, v28
	v_fmac_f32_e32 v129, v48, v28
	v_fmac_f32_e32 v130, v52, v28
	v_fmac_f32_e32 v131, v56, v28
	v_fmac_f32_e32 v132, v60, v28
	v_fmac_f32_e32 v133, v64, v28
	v_fmac_f32_e32 v151, v68, v28
	v_fmac_f32_e32 v126, v37, v29
	v_fmac_f32_e32 v127, v41, v29
	v_fmac_f32_e32 v128, v45, v29
	v_fmac_f32_e32 v129, v49, v29
	v_fmac_f32_e32 v130, v53, v29
	v_fmac_f32_e32 v131, v57, v29
	v_fmac_f32_e32 v132, v61, v29
	v_fmac_f32_e32 v133, v65, v29
	v_fmac_f32_e32 v151, v69, v29
	ds_read_b128 v[34:37], v121 offset:384
	ds_read_b128 v[38:41], v121 offset:4480
	ds_read_b128 v[42:45], v121 offset:8576
	ds_read_b128 v[46:49], v121 offset:12672
	ds_read_b128 v[50:53], v121 offset:16768
	ds_read_b128 v[54:57], v121 offset:20864
	ds_read_b128 v[58:61], v121 offset:24960
	ds_read_b128 v[62:65], v121 offset:29056
	ds_read_b128 v[66:69], v121 offset:33152
	s_waitcnt lgkmcnt(9)
	s_waitcnt vmcnt(16)
	v_fmac_f32_e32 v126, v70, v30
	v_fmac_f32_e32 v127, v74, v30
	v_fmac_f32_e32 v128, v78, v30
	v_fmac_f32_e32 v129, v82, v30
	v_fmac_f32_e32 v130, v86, v30
	v_fmac_f32_e32 v131, v90, v30
	v_fmac_f32_e32 v132, v94, v30
	v_fmac_f32_e32 v133, v98, v30
	v_fmac_f32_e32 v151, v102, v30
	v_fmac_f32_e32 v126, v71, v31
	v_fmac_f32_e32 v127, v75, v31
	v_fmac_f32_e32 v128, v79, v31
	v_fmac_f32_e32 v129, v83, v31
	v_fmac_f32_e32 v130, v87, v31
	v_fmac_f32_e32 v131, v91, v31
	v_fmac_f32_e32 v132, v95, v31
	v_fmac_f32_e32 v133, v99, v31
	v_fmac_f32_e32 v151, v103, v31
	v_fmac_f32_e32 v126, v72, v32
	v_fmac_f32_e32 v127, v76, v32
	v_fmac_f32_e32 v128, v80, v32
	v_fmac_f32_e32 v129, v84, v32
	v_fmac_f32_e32 v130, v88, v32
	v_fmac_f32_e32 v131, v92, v32
	v_fmac_f32_e32 v132, v96, v32
	v_fmac_f32_e32 v133, v100, v32
	v_fmac_f32_e32 v151, v104, v32
	v_fmac_f32_e32 v126, v73, v33
	v_fmac_f32_e32 v127, v77, v33
	v_fmac_f32_e32 v128, v81, v33
	v_fmac_f32_e32 v129, v85, v33
	v_fmac_f32_e32 v130, v89, v33
	v_fmac_f32_e32 v131, v93, v33
	v_fmac_f32_e32 v132, v97, v33
	v_fmac_f32_e32 v133, v101, v33
	v_fmac_f32_e32 v151, v105, v33
	global_load_dword v18, v[124:125], off
	v_lshl_add_u64 v[124:125], v[124:125], 0, s[40:41]
	global_load_dword v19, v[124:125], off
	v_lshl_add_u64 v[124:125], v[124:125], 0, s[40:41]
	global_load_dword v20, v[124:125], off
	v_lshl_add_u64 v[124:125], v[124:125], 0, s[40:41]
	global_load_dword v21, v[124:125], off
	v_lshl_add_u64 v[124:125], v[124:125], 0, s[40:41]
	global_load_dword v22, v[124:125], off
	v_lshl_add_u64 v[124:125], v[124:125], 0, s[40:41]
	global_load_dword v23, v[124:125], off
	v_lshl_add_u64 v[124:125], v[124:125], 0, s[40:41]
	global_load_dword v24, v[124:125], off
	v_lshl_add_u64 v[124:125], v[124:125], 0, s[40:41]
	global_load_dword v25, v[124:125], off
	v_lshl_add_u64 v[124:125], v[124:125], 0, s[40:41]
	global_load_dword v26, v[124:125], off
	v_lshl_add_u64 v[124:125], v[124:125], 0, s[40:41]
	global_load_dword v27, v[124:125], off
	v_lshl_add_u64 v[124:125], v[124:125], 0, s[40:41]
	global_load_dword v28, v[124:125], off
	v_lshl_add_u64 v[124:125], v[124:125], 0, s[40:41]
	global_load_dword v29, v[124:125], off
	v_lshl_add_u64 v[124:125], v[124:125], 0, s[40:41]
	global_load_dword v30, v[124:125], off
	v_lshl_add_u64 v[124:125], v[124:125], 0, s[40:41]
	global_load_dword v31, v[124:125], off
	v_lshl_add_u64 v[124:125], v[124:125], 0, s[40:41]
	global_load_dword v32, v[124:125], off
	v_lshl_add_u64 v[124:125], v[124:125], 0, s[40:41]
	global_load_dword v33, v[124:125], off
	v_lshl_add_u64 v[124:125], v[124:125], 0, s[40:41]
	ds_read_b128 v[70:73], v121 offset:400
	ds_read_b128 v[74:77], v121 offset:4496
	ds_read_b128 v[78:81], v121 offset:8592
	ds_read_b128 v[82:85], v121 offset:12688
	ds_read_b128 v[86:89], v121 offset:16784
	ds_read_b128 v[90:93], v121 offset:20880
	ds_read_b128 v[94:97], v121 offset:24976
	ds_read_b128 v[98:101], v121 offset:29072
	ds_read_b128 v[102:105], v121 offset:33168
	s_waitcnt lgkmcnt(9)
	s_waitcnt vmcnt(28)
	v_fmac_f32_e32 v126, v34, v2
	v_fmac_f32_e32 v127, v38, v2
	v_fmac_f32_e32 v128, v42, v2
	v_fmac_f32_e32 v129, v46, v2
	v_fmac_f32_e32 v130, v50, v2
	v_fmac_f32_e32 v131, v54, v2
	v_fmac_f32_e32 v132, v58, v2
	v_fmac_f32_e32 v133, v62, v2
	v_fmac_f32_e32 v151, v66, v2
	v_fmac_f32_e32 v126, v35, v3
	v_fmac_f32_e32 v127, v39, v3
	v_fmac_f32_e32 v128, v43, v3
	v_fmac_f32_e32 v129, v47, v3
	v_fmac_f32_e32 v130, v51, v3
	v_fmac_f32_e32 v131, v55, v3
	v_fmac_f32_e32 v132, v59, v3
	v_fmac_f32_e32 v133, v63, v3
	v_fmac_f32_e32 v151, v67, v3
	v_fmac_f32_e32 v126, v36, v4
	v_fmac_f32_e32 v127, v40, v4
	v_fmac_f32_e32 v128, v44, v4
	v_fmac_f32_e32 v129, v48, v4
	v_fmac_f32_e32 v130, v52, v4
	v_fmac_f32_e32 v131, v56, v4
	v_fmac_f32_e32 v132, v60, v4
	v_fmac_f32_e32 v133, v64, v4
	v_fmac_f32_e32 v151, v68, v4
	v_fmac_f32_e32 v126, v37, v5
	v_fmac_f32_e32 v127, v41, v5
	v_fmac_f32_e32 v128, v45, v5
	v_fmac_f32_e32 v129, v49, v5
	v_fmac_f32_e32 v130, v53, v5
	v_fmac_f32_e32 v131, v57, v5
	v_fmac_f32_e32 v132, v61, v5
	v_fmac_f32_e32 v133, v65, v5
	v_fmac_f32_e32 v151, v69, v5
	ds_read_b128 v[34:37], v121 offset:416
	ds_read_b128 v[38:41], v121 offset:4512
	ds_read_b128 v[42:45], v121 offset:8608
	ds_read_b128 v[46:49], v121 offset:12704
	ds_read_b128 v[50:53], v121 offset:16800
	ds_read_b128 v[54:57], v121 offset:20896
	ds_read_b128 v[58:61], v121 offset:24992
	ds_read_b128 v[62:65], v121 offset:29088
	ds_read_b128 v[66:69], v121 offset:33184
	s_waitcnt lgkmcnt(9)
; DEVI void mod_item(const Params& p, int item) {
;     ...
;   for (int k4 = 0; k4 < 32; ++k4) {
;     const int k = kq * 128 + k4 * 4;
;     const float w0 = w[(size_t)k * 9216], w1 = w[(size_t)(k + 1) * 9216], w2 = w[(size_t)(k + 2) * 9216], w3 = w[(size_t)(k + 3) * 9216];
; #pragma unroll
;     for (int r = 0; r < 9; ++r) { const float4 s4 = *(const float4*)(sv + r * 1024 + k); acc[r] += s4.x * w0 + s4.y * w1 + s4.z * w2 + s4.w * w3; }
;   }
	s_waitcnt vmcnt(24)
	v_fmac_f32_e32 v126, v70, v6
	v_fmac_f32_e32 v127, v74, v6
	v_fmac_f32_e32 v128, v78, v6
	v_fmac_f32_e32 v129, v82, v6
	v_fmac_f32_e32 v130, v86, v6
	v_fmac_f32_e32 v131, v90, v6
	v_fmac_f32_e32 v132, v94, v6
	v_fmac_f32_e32 v133, v98, v6
	v_fmac_f32_e32 v151, v102, v6
	v_fmac_f32_e32 v126, v71, v7
	v_fmac_f32_e32 v127, v75, v7
	v_fmac_f32_e32 v128, v79, v7
	v_fmac_f32_e32 v129, v83, v7
	v_fmac_f32_e32 v130, v87, v7
	v_fmac_f32_e32 v131, v91, v7
	v_fmac_f32_e32 v132, v95, v7
	v_fmac_f32_e32 v133, v99, v7
	v_fmac_f32_e32 v151, v103, v7
	v_fmac_f32_e32 v126, v72, v8
	v_fmac_f32_e32 v127, v76, v8
	v_fmac_f32_e32 v128, v80, v8
	v_fmac_f32_e32 v129, v84, v8
	v_fmac_f32_e32 v130, v88, v8
	v_fmac_f32_e32 v131, v92, v8
	v_fmac_f32_e32 v132, v96, v8
	v_fmac_f32_e32 v133, v100, v8
	v_fmac_f32_e32 v151, v104, v8
	v_fmac_f32_e32 v126, v73, v9
	v_fmac_f32_e32 v127, v77, v9
	v_fmac_f32_e32 v128, v81, v9
	v_fmac_f32_e32 v129, v85, v9
	v_fmac_f32_e32 v130, v89, v9
	v_fmac_f32_e32 v131, v93, v9
	v_fmac_f32_e32 v132, v97, v9
	v_fmac_f32_e32 v133, v101, v9
	v_fmac_f32_e32 v151, v105, v9
	ds_read_b128 v[70:73], v121 offset:432
	ds_read_b128 v[74:77], v121 offset:4528
	ds_read_b128 v[78:81], v121 offset:8624
	ds_read_b128 v[82:85], v121 offset:12720
	ds_read_b128 v[86:89], v121 offset:16816
	ds_read_b128 v[90:93], v121 offset:20912
	ds_read_b128 v[94:97], v121 offset:25008
	ds_read_b128 v[98:101], v121 offset:29104
	ds_read_b128 v[102:105], v121 offset:33200
	s_waitcnt lgkmcnt(9)
	s_waitcnt vmcnt(20)
	v_fmac_f32_e32 v126, v34, v10
	v_fmac_f32_e32 v127, v38, v10
	v_fmac_f32_e32 v128, v42, v10
	v_fmac_f32_e32 v129, v46, v10
	v_fmac_f32_e32 v130, v50, v10
	v_fmac_f32_e32 v131, v54, v10
	v_fmac_f32_e32 v132, v58, v10
	v_fmac_f32_e32 v133, v62, v10
	v_fmac_f32_e32 v151, v66, v10
	v_fmac_f32_e32 v126, v35, v11
	v_fmac_f32_e32 v127, v39, v11
	v_fmac_f32_e32 v128, v43, v11
	v_fmac_f32_e32 v129, v47, v11
	v_fmac_f32_e32 v130, v51, v11
	v_fmac_f32_e32 v131, v55, v11
	v_fmac_f32_e32 v132, v59, v11
	v_fmac_f32_e32 v133, v63, v11
	v_fmac_f32_e32 v151, v67, v11
	v_fmac_f32_e32 v126, v36, v12
	v_fmac_f32_e32 v127, v40, v12
	v_fmac_f32_e32 v128, v44, v12
	v_fmac_f32_e32 v129, v48, v12
	v_fmac_f32_e32 v130, v52, v12
	v_fmac_f32_e32 v131, v56, v12
	v_fmac_f32_e32 v132, v60, v12
	v_fmac_f32_e32 v133, v64, v12
	v_fmac_f32_e32 v151, v68, v12
	v_fmac_f32_e32 v126, v37, v13
	v_fmac_f32_e32 v127, v41, v13
	v_fmac_f32_e32 v128, v45, v13
	v_fmac_f32_e32 v129, v49, v13
	v_fmac_f32_e32 v130, v53, v13
	v_fmac_f32_e32 v131, v57, v13
	v_fmac_f32_e32 v132, v61, v13
	v_fmac_f32_e32 v133, v65, v13
	v_fmac_f32_e32 v151, v69, v13
	ds_read_b128 v[34:37], v121 offset:448
	ds_read_b128 v[38:41], v121 offset:4544
	ds_read_b128 v[42:45], v121 offset:8640
	ds_read_b128 v[46:49], v121 offset:12736
	ds_read_b128 v[50:53], v121 offset:16832
	ds_read_b128 v[54:57], v121 offset:20928
	ds_read_b128 v[58:61], v121 offset:25024
	ds_read_b128 v[62:65], v121 offset:29120
	ds_read_b128 v[66:69], v121 offset:33216
	s_waitcnt lgkmcnt(9)
	s_waitcnt vmcnt(16)
	v_fmac_f32_e32 v126, v70, v14
	v_fmac_f32_e32 v127, v74, v14
	v_fmac_f32_e32 v128, v78, v14
	v_fmac_f32_e32 v129, v82, v14
	v_fmac_f32_e32 v130, v86, v14
	v_fmac_f32_e32 v131, v90, v14
	v_fmac_f32_e32 v132, v94, v14
	v_fmac_f32_e32 v133, v98, v14
	v_fmac_f32_e32 v151, v102, v14
	v_fmac_f32_e32 v126, v71, v15
	v_fmac_f32_e32 v127, v75, v15
	v_fmac_f32_e32 v128, v79, v15
	v_fmac_f32_e32 v129, v83, v15
	v_fmac_f32_e32 v130, v87, v15
	v_fmac_f32_e32 v131, v91, v15
	v_fmac_f32_e32 v132, v95, v15
	v_fmac_f32_e32 v133, v99, v15
	v_fmac_f32_e32 v151, v103, v15
	v_fmac_f32_e32 v126, v72, v16
	v_fmac_f32_e32 v127, v76, v16
	v_fmac_f32_e32 v128, v80, v16
	v_fmac_f32_e32 v129, v84, v16
	v_fmac_f32_e32 v130, v88, v16
	v_fmac_f32_e32 v131, v92, v16
	v_fmac_f32_e32 v132, v96, v16
	v_fmac_f32_e32 v133, v100, v16
	v_fmac_f32_e32 v151, v104, v16
	v_fmac_f32_e32 v126, v73, v17
	v_fmac_f32_e32 v127, v77, v17
	v_fmac_f32_e32 v128, v81, v17
	v_fmac_f32_e32 v129, v85, v17
	v_fmac_f32_e32 v130, v89, v17
	v_fmac_f32_e32 v131, v93, v17
	v_fmac_f32_e32 v132, v97, v17
	v_fmac_f32_e32 v133, v101, v17
	v_fmac_f32_e32 v151, v105, v17
	ds_read_b128 v[70:73], v121 offset:464
	ds_read_b128 v[74:77], v121 offset:4560
	ds_read_b128 v[78:81], v121 offset:8656
	ds_read_b128 v[82:85], v121 offset:12752
	ds_read_b128 v[86:89], v121 offset:16848
	ds_read_b128 v[90:93], v121 offset:20944
	ds_read_b128 v[94:97], v121 offset:25040
	ds_read_b128 v[98:101], v121 offset:29136
	ds_read_b128 v[102:105], v121 offset:33232
	s_waitcnt lgkmcnt(9)
	s_waitcnt vmcnt(12)
	v_fmac_f32_e32 v126, v34, v18
	v_fmac_f32_e32 v127, v38, v18
	v_fmac_f32_e32 v128, v42, v18
	v_fmac_f32_e32 v129, v46, v18
	v_fmac_f32_e32 v130, v50, v18
	v_fmac_f32_e32 v131, v54, v18
	v_fmac_f32_e32 v132, v58, v18
	v_fmac_f32_e32 v133, v62, v18
	v_fmac_f32_e32 v151, v66, v18
	v_fmac_f32_e32 v126, v35, v19
	v_fmac_f32_e32 v127, v39, v19
	v_fmac_f32_e32 v128, v43, v19
	v_fmac_f32_e32 v129, v47, v19
	v_fmac_f32_e32 v130, v51, v19
	v_fmac_f32_e32 v131, v55, v19
	v_fmac_f32_e32 v132, v59, v19
	v_fmac_f32_e32 v133, v63, v19
	v_fmac_f32_e32 v151, v67, v19
	v_fmac_f32_e32 v126, v36, v20
	v_fmac_f32_e32 v127, v40, v20
	v_fmac_f32_e32 v128, v44, v20
	v_fmac_f32_e32 v129, v48, v20
	v_fmac_f32_e32 v130, v52, v20
	v_fmac_f32_e32 v131, v56, v20
	v_fmac_f32_e32 v132, v60, v20
	v_fmac_f32_e32 v133, v64, v20
	v_fmac_f32_e32 v151, v68, v20
	v_fmac_f32_e32 v126, v37, v21
	v_fmac_f32_e32 v127, v41, v21
	v_fmac_f32_e32 v128, v45, v21
	v_fmac_f32_e32 v129, v49, v21
	v_fmac_f32_e32 v130, v53, v21
	v_fmac_f32_e32 v131, v57, v21
	v_fmac_f32_e32 v132, v61, v21
	v_fmac_f32_e32 v133, v65, v21
	v_fmac_f32_e32 v151, v69, v21
	ds_read_b128 v[34:37], v121 offset:480
	ds_read_b128 v[38:41], v121 offset:4576
	ds_read_b128 v[42:45], v121 offset:8672
	ds_read_b128 v[46:49], v121 offset:12768
	ds_read_b128 v[50:53], v121 offset:16864
	ds_read_b128 v[54:57], v121 offset:20960
	ds_read_b128 v[58:61], v121 offset:25056
	ds_read_b128 v[62:65], v121 offset:29152
	ds_read_b128 v[66:69], v121 offset:33248
	s_waitcnt lgkmcnt(9)
; DEVI void mod_item(const Params& p, int item) {
;     ...
;   for (int k4 = 0; k4 < 32; ++k4) {
;     const int k = kq * 128 + k4 * 4;
;     const float w0 = w[(size_t)k * 9216], w1 = w[(size_t)(k + 1) * 9216], w2 = w[(size_t)(k + 2) * 9216], w3 = w[(size_t)(k + 3) * 9216];
; #pragma unroll
;     for (int r = 0; r < 9; ++r) { const float4 s4 = *(const float4*)(sv + r * 1024 + k); acc[r] += s4.x * w0 + s4.y * w1 + s4.z * w2 + s4.w * w3; }
;   }
; #pragma unroll
;   for (int r = 0; r < 9; ++r) red[(kq * 9 + r) * 64 + cc] = acc[r];
;   __syncthreads();
	s_waitcnt vmcnt(8)
	v_fmac_f32_e32 v126, v70, v22
	v_fmac_f32_e32 v127, v74, v22
	v_fmac_f32_e32 v128, v78, v22
	v_fmac_f32_e32 v129, v82, v22
	v_fmac_f32_e32 v130, v86, v22
	v_fmac_f32_e32 v131, v90, v22
	v_fmac_f32_e32 v132, v94, v22
	v_fmac_f32_e32 v133, v98, v22
	v_fmac_f32_e32 v151, v102, v22
	v_fmac_f32_e32 v126, v71, v23
	v_fmac_f32_e32 v127, v75, v23
	v_fmac_f32_e32 v128, v79, v23
	v_fmac_f32_e32 v129, v83, v23
	v_fmac_f32_e32 v130, v87, v23
	v_fmac_f32_e32 v131, v91, v23
	v_fmac_f32_e32 v132, v95, v23
	v_fmac_f32_e32 v133, v99, v23
	v_fmac_f32_e32 v151, v103, v23
	v_fmac_f32_e32 v126, v72, v24
	v_fmac_f32_e32 v127, v76, v24
	v_fmac_f32_e32 v128, v80, v24
	v_fmac_f32_e32 v129, v84, v24
	v_fmac_f32_e32 v130, v88, v24
	v_fmac_f32_e32 v131, v92, v24
	v_fmac_f32_e32 v132, v96, v24
	v_fmac_f32_e32 v133, v100, v24
	v_fmac_f32_e32 v151, v104, v24
	v_fmac_f32_e32 v126, v73, v25
	v_fmac_f32_e32 v127, v77, v25
	v_fmac_f32_e32 v128, v81, v25
	v_fmac_f32_e32 v129, v85, v25
	v_fmac_f32_e32 v130, v89, v25
	v_fmac_f32_e32 v131, v93, v25
	v_fmac_f32_e32 v132, v97, v25
	v_fmac_f32_e32 v133, v101, v25
	v_fmac_f32_e32 v151, v105, v25
	ds_read_b128 v[70:73], v121 offset:496
	ds_read_b128 v[74:77], v121 offset:4592
	ds_read_b128 v[78:81], v121 offset:8688
	ds_read_b128 v[82:85], v121 offset:12784
	ds_read_b128 v[86:89], v121 offset:16880
	ds_read_b128 v[90:93], v121 offset:20976
	ds_read_b128 v[94:97], v121 offset:25072
	ds_read_b128 v[98:101], v121 offset:29168
	ds_read_b128 v[102:105], v121 offset:33264
	s_waitcnt lgkmcnt(9)
	s_waitcnt vmcnt(4)
	v_fmac_f32_e32 v126, v34, v26
	v_fmac_f32_e32 v127, v38, v26
	v_fmac_f32_e32 v128, v42, v26
	v_fmac_f32_e32 v129, v46, v26
	v_fmac_f32_e32 v130, v50, v26
	v_fmac_f32_e32 v131, v54, v26
	v_fmac_f32_e32 v132, v58, v26
	v_fmac_f32_e32 v133, v62, v26
	v_fmac_f32_e32 v151, v66, v26
	v_fmac_f32_e32 v126, v35, v27
	v_fmac_f32_e32 v127, v39, v27
	v_fmac_f32_e32 v128, v43, v27
	v_fmac_f32_e32 v129, v47, v27
	v_fmac_f32_e32 v130, v51, v27
	v_fmac_f32_e32 v131, v55, v27
	v_fmac_f32_e32 v132, v59, v27
	v_fmac_f32_e32 v133, v63, v27
	v_fmac_f32_e32 v151, v67, v27
	v_fmac_f32_e32 v126, v36, v28
	v_fmac_f32_e32 v127, v40, v28
	v_fmac_f32_e32 v128, v44, v28
	v_fmac_f32_e32 v129, v48, v28
	v_fmac_f32_e32 v130, v52, v28
	v_fmac_f32_e32 v131, v56, v28
	v_fmac_f32_e32 v132, v60, v28
	v_fmac_f32_e32 v133, v64, v28
	v_fmac_f32_e32 v151, v68, v28
	v_fmac_f32_e32 v126, v37, v29
	v_fmac_f32_e32 v127, v41, v29
	v_fmac_f32_e32 v128, v45, v29
	v_fmac_f32_e32 v129, v49, v29
	v_fmac_f32_e32 v130, v53, v29
	v_fmac_f32_e32 v131, v57, v29
	v_fmac_f32_e32 v132, v61, v29
	v_fmac_f32_e32 v133, v65, v29
	v_fmac_f32_e32 v151, v69, v29
	s_waitcnt lgkmcnt(0)
	s_waitcnt vmcnt(0)
	v_fmac_f32_e32 v126, v70, v30
	v_fmac_f32_e32 v127, v74, v30
	v_fmac_f32_e32 v128, v78, v30
	v_fmac_f32_e32 v129, v82, v30
	v_fmac_f32_e32 v130, v86, v30
	v_fmac_f32_e32 v131, v90, v30
	v_fmac_f32_e32 v132, v94, v30
	v_fmac_f32_e32 v133, v98, v30
	v_fmac_f32_e32 v151, v102, v30
	v_fmac_f32_e32 v126, v71, v31
	v_fmac_f32_e32 v127, v75, v31
	v_fmac_f32_e32 v128, v79, v31
	v_fmac_f32_e32 v129, v83, v31
	v_fmac_f32_e32 v130, v87, v31
	v_fmac_f32_e32 v131, v91, v31
	v_fmac_f32_e32 v132, v95, v31
	v_fmac_f32_e32 v133, v99, v31
	v_fmac_f32_e32 v151, v103, v31
	v_fmac_f32_e32 v126, v72, v32
	v_fmac_f32_e32 v127, v76, v32
	v_fmac_f32_e32 v128, v80, v32
	v_fmac_f32_e32 v129, v84, v32
	v_fmac_f32_e32 v130, v88, v32
	v_fmac_f32_e32 v131, v92, v32
	v_fmac_f32_e32 v132, v96, v32
	v_fmac_f32_e32 v133, v100, v32
	v_fmac_f32_e32 v151, v104, v32
	v_fmac_f32_e32 v126, v73, v33
	v_fmac_f32_e32 v127, v77, v33
	v_fmac_f32_e32 v128, v81, v33
	v_fmac_f32_e32 v129, v85, v33
	v_fmac_f32_e32 v130, v89, v33
	v_fmac_f32_e32 v131, v93, v33
	v_fmac_f32_e32 v132, v97, v33
	v_fmac_f32_e32 v133, v101, v33
	v_fmac_f32_e32 v151, v105, v33
	v_lshl_add_u32 v2, v122, 2, 0
	s_movk_i32 s0, 0x900
	v_mad_u64_u32 v[4:5], s[0:1], v118, s0, v[2:3]
	s_movk_i32 s0, 0x240
	s_nop 0
	v_cmp_gt_i32_e32 vcc, s0, v120
	ds_write2st64_b32 v4, v126, v127 offset0:144 offset1:145
	ds_write2st64_b32 v4, v128, v129 offset0:146 offset1:147
	ds_write2st64_b32 v4, v130, v131 offset0:148 offset1:149
	ds_write2st64_b32 v4, v132, v133 offset0:150 offset1:151
	ds_write_b32 v4, v151 offset:38912
	s_waitcnt lgkmcnt(0)
	s_barrier
	s_and_saveexec_b64 s[0:1], vcc
	s_cbranch_execz .LBB0_34
	s_add_u32 s4, s55, s66
	s_addc_u32 s5, s56, s67
	s_and_b64 s[6:7], s[30:31], exec
	s_cselect_b32 s6, 0x2400, 0
	s_add_i32 s8, s52, s6
	v_readlane_b32 s36, v252, 14
	v_or_b32_e32 v118, s8, v122
	v_readlane_b32 s46, v252, 24
	v_readlane_b32 s47, v252, 25
	s_and_b64 s[6:7], s[30:31], exec
	s_cselect_b32 s6, 9, 0
	v_lshl_add_u64 v[4:5], v[118:119], 2, s[46:47]
	v_lshlrev_b32_e32 v118, 2, v122
	v_lshl_add_u64 v[6:7], s[4:5], 0, v[118:119]
	s_mov_b64 s[4:5], 0
	v_readlane_b32 s37, v252, 15
	v_readlane_b32 s38, v252, 16
	v_readlane_b32 s39, v252, 17
	v_readlane_b32 s40, v252, 18
	v_readlane_b32 s41, v252, 19
	v_readlane_b32 s42, v252, 20
	v_readlane_b32 s43, v252, 21
	v_readlane_b32 s44, v252, 22
	v_readlane_b32 s45, v252, 23
	v_readlane_b32 s48, v252, 26
	v_readlane_b32 s49, v252, 27
	v_readlane_b32 s50, v252, 28
	v_readlane_b32 s51, v252, 29

; DEVI float sigmoidf_(float x) { return __builtin_amdgcn_rcpf(1.f + __expf(-x)); }
; DEVI void lru_item(const Params& p, int l, int item, int pass) {
;     ...
;     const float exl = __expf(-lam); const float sp = exl < 0.03f ? exl * (1.f - exl * (0.5f - exl * (0.33333334f - 0.25f * exl))) : __logf(1.f + exl);
;     float Ap = 1.f, Bp = 0.f;
; #pragma unroll
;     for (int q = 0; q < 16; ++q) {
;       const int tt = d == 0 ? q : 15 - q;
;       const float r = sigmoidf_(pre[0][tt] + ba), ig = sigmoidf_(pre[1][tt] + bx);
;       const float la = -8.f * r * sp;
;       const float a = __expf(la);
;       const float om = fmaxf(1.f - a * a, 0.f);
;       const float bb = sqrtf(om) * (ig * uo[tt]);
;       av[d][tt] = a; bv[d][tt] = bb;
;       Bp = a * Bp + bb; Ap *= a;
;     }
.LBB0_1296:
	s_andn2_saveexec_b64 s[4:5], s[4:5]
	v_mov_b32_e32 v83, 0x3eaaaaab
	v_fmamk_f32 v83, v84, 0xbe800000, v83
	v_fma_f32 v83, -v84, v83, 0.5
	v_fma_f32 v83, -v84, v83, 1.0
	v_mul_f32_e32 v83, v84, v83
	s_or_b64 exec, exec, s[4:5]
	s_waitcnt vmcnt(1) lgkmcnt(14)
	v_add_f32_e32 v48, v48, v31
	v_mul_f32_e32 v48, 0xbfb8aa3b, v48
	v_exp_f32_e32 v48, v48
	v_add_f32_e32 v49, v49, v31
	v_mul_f32_e32 v49, 0xbfb8aa3b, v49
	v_exp_f32_e32 v49, v49
	v_add_f32_e32 v48, 1.0, v48
	v_rcp_f32_e32 v48, v48
	s_waitcnt vmcnt(0) lgkmcnt(7)
	v_add_f32_e32 v50, v50, v33
	v_add_f32_e32 v49, 1.0, v49
	v_mul_f32_e32 v50, 0xbfb8aa3b, v50
	v_mul_f32_e32 v48, 0xc1000000, v48
	v_mul_f32_e32 v48, v48, v83
	v_mul_f32_e32 v48, 0x3fb8aa3b, v48
	v_exp_f32_e32 v48, v48
	v_rcp_f32_e32 v49, v49
	v_exp_f32_e32 v50, v50
	v_add_f32_e32 v44, v44, v31
	v_fma_f32 v84, -v48, v48, 1.0
	v_max_f32_e32 v84, 0, v84
	v_mul_f32_e32 v49, 0xc1000000, v49
	v_add_f32_e32 v50, 1.0, v50
	v_mul_f32_e32 v49, v49, v83
	v_rcp_f32_e32 v50, v50
	v_mul_f32_e32 v49, 0x3fb8aa3b, v49
	v_exp_f32_e32 v49, v49
	v_mul_f32_e32 v44, 0xbfb8aa3b, v44
	v_mul_f32_e32 v50, v56, v50
	v_exp_f32_e32 v44, v44
	v_sqrt_f32_e32 v84, v84
	s_nop 0
	v_mul_f32_e32 v50, v50, v84
	v_fma_f32 v84, -v49, v49, 1.0
	v_max_f32_e32 v84, 0, v84
	v_add_f32_e32 v44, 1.0, v44
	v_rcp_f32_e32 v44, v44
	v_add_f32_e32 v51, v51, v33
	v_mul_f32_e32 v51, 0xbfb8aa3b, v51
	v_exp_f32_e32 v51, v51
	v_mul_f32_e32 v44, 0xc1000000, v44
	v_mul_f32_e32 v44, v44, v83
	v_mul_f32_e32 v44, 0x3fb8aa3b, v44
	v_add_f32_e32 v51, 1.0, v51
	v_exp_f32_e32 v44, v44
	v_rcp_f32_e32 v51, v51
	v_fmac_f32_e32 v50, 0, v48
	v_add_f32_e32 v45, v45, v31
	v_mul_f32_e32 v50, v49, v50
	v_mul_f32_e32 v48, v48, v49
	v_fma_f32 v49, -v44, v44, 1.0
	v_mul_f32_e32 v45, 0xbfb8aa3b, v45
	v_sqrt_f32_e32 v84, v84
	v_mul_f32_e32 v51, v57, v51
	v_max_f32_e32 v49, 0, v49
	v_exp_f32_e32 v45, v45
	v_fmac_f32_e32 v50, v51, v84
	s_waitcnt lgkmcnt(6)
	v_add_f32_e32 v46, v46, v33
	v_add_f32_e32 v45, 1.0, v45
	v_mul_f32_e32 v46, 0xbfb8aa3b, v46
	v_rcp_f32_e32 v45, v45
	v_exp_f32_e32 v46, v46
	v_mul_f32_e32 v45, 0xc1000000, v45
	v_add_f32_e32 v46, 1.0, v46
	v_mul_f32_e32 v45, v45, v83
	v_rcp_f32_e32 v46, v46
	v_mul_f32_e32 v45, 0x3fb8aa3b, v45
	v_exp_f32_e32 v45, v45
	v_add_f32_e32 v40, v40, v31
	v_mul_f32_e32 v46, v58, v46
	v_sqrt_f32_e32 v49, v49
	v_mul_f32_e32 v50, v44, v50
	v_mul_f32_e32 v40, 0xbfb8aa3b, v40
	v_fmac_f32_e32 v50, v46, v49
	v_add_f32_e32 v46, v47, v33
	v_fma_f32 v47, -v45, v45, 1.0
	v_exp_f32_e32 v40, v40
	v_max_f32_e32 v47, 0, v47
	v_mul_f32_e32 v44, v44, v48
	v_add_f32_e32 v40, 1.0, v40
	v_rcp_f32_e32 v40, v40
	v_mul_f32_e32 v46, 0xbfb8aa3b, v46
	v_exp_f32_e32 v46, v46
	v_mul_f32_e32 v40, 0xc1000000, v40
	v_mul_f32_e32 v40, v40, v83
	v_mul_f32_e32 v40, 0x3fb8aa3b, v40
	v_add_f32_e32 v46, 1.0, v46
	v_exp_f32_e32 v40, v40
	v_rcp_f32_e32 v46, v46
	v_add_f32_e32 v41, v41, v31
	v_mul_f32_e32 v44, v45, v44
	v_sqrt_f32_e32 v47, v47
	v_mul_f32_e32 v48, v45, v50
	v_fma_f32 v45, -v40, v40, 1.0
	v_mul_f32_e32 v41, 0xbfb8aa3b, v41
	v_mul_f32_e32 v46, v59, v46
	v_max_f32_e32 v45, 0, v45
	v_exp_f32_e32 v41, v41
	v_fmac_f32_e32 v48, v46, v47
	s_waitcnt lgkmcnt(5)
	v_add_f32_e32 v42, v42, v33
	v_add_f32_e32 v41, 1.0, v41
	v_mul_f32_e32 v42, 0xbfb8aa3b, v42
	v_rcp_f32_e32 v41, v41
	v_exp_f32_e32 v42, v42
	v_mul_f32_e32 v41, 0xc1000000, v41
	v_add_f32_e32 v42, 1.0, v42
	v_mul_f32_e32 v41, v41, v83
	v_rcp_f32_e32 v42, v42
	v_mul_f32_e32 v41, 0x3fb8aa3b, v41
	v_exp_f32_e32 v41, v41
	v_add_f32_e32 v24, v24, v31
	v_mul_f32_e32 v42, v60, v42
	v_sqrt_f32_e32 v45, v45
	v_mul_f32_e32 v46, v40, v48
	v_mul_f32_e32 v24, 0xbfb8aa3b, v24
	v_fmac_f32_e32 v46, v42, v45
	v_add_f32_e32 v42, v43, v33
	v_fma_f32 v43, -v41, v41, 1.0
	v_exp_f32_e32 v24, v24
	v_max_f32_e32 v43, 0, v43
	v_mul_f32_e32 v40, v40, v44
	v_add_f32_e32 v24, 1.0, v24
	v_rcp_f32_e32 v24, v24
	v_mul_f32_e32 v42, 0xbfb8aa3b, v42
	v_exp_f32_e32 v42, v42
	v_mul_f32_e32 v24, 0xc1000000, v24
	v_mul_f32_e32 v24, v24, v83
	v_mul_f32_e32 v24, 0x3fb8aa3b, v24
	v_add_f32_e32 v42, 1.0, v42
	v_exp_f32_e32 v24, v24
	v_rcp_f32_e32 v42, v42
	v_add_f32_e32 v25, v25, v31
	v_mul_f32_e32 v40, v41, v40
	v_sqrt_f32_e32 v43, v43
	v_mul_f32_e32 v44, v41, v46
	v_fma_f32 v41, -v24, v24, 1.0
	v_mul_f32_e32 v25, 0xbfb8aa3b, v25
	v_mul_f32_e32 v42, v61, v42
	v_max_f32_e32 v41, 0, v41
	v_exp_f32_e32 v25, v25
	v_fmac_f32_e32 v44, v42, v43
	s_waitcnt lgkmcnt(4)
	v_add_f32_e32 v26, v26, v33
	v_add_f32_e32 v25, 1.0, v25
	v_mul_f32_e32 v26, 0xbfb8aa3b, v26
	v_rcp_f32_e32 v25, v25
	v_exp_f32_e32 v26, v26
	v_mul_f32_e32 v25, 0xc1000000, v25
	v_add_f32_e32 v26, 1.0, v26
	v_mul_f32_e32 v25, v25, v83
	v_rcp_f32_e32 v26, v26
	v_mul_f32_e32 v25, 0x3fb8aa3b, v25
	v_exp_f32_e32 v25, v25
	v_add_f32_e32 v20, v20, v31
	v_mul_f32_e32 v26, v62, v26
	v_sqrt_f32_e32 v41, v41
	v_mul_f32_e32 v42, v24, v44
	v_mul_f32_e32 v20, 0xbfb8aa3b, v20
	v_fmac_f32_e32 v42, v26, v41
	v_add_f32_e32 v26, v27, v33
	v_fma_f32 v27, -v25, v25, 1.0
	v_exp_f32_e32 v20, v20
	v_max_f32_e32 v27, 0, v27
	v_mul_f32_e32 v24, v24, v40
	v_add_f32_e32 v20, 1.0, v20
	v_rcp_f32_e32 v20, v20
	v_mul_f32_e32 v26, 0xbfb8aa3b, v26
	v_exp_f32_e32 v26, v26
	v_mul_f32_e32 v20, 0xc1000000, v20
	v_mul_f32_e32 v20, v20, v83
	v_mul_f32_e32 v20, 0x3fb8aa3b, v20
	v_add_f32_e32 v26, 1.0, v26
	v_exp_f32_e32 v20, v20
	v_rcp_f32_e32 v26, v26
	v_add_f32_e32 v21, v21, v31
	v_mul_f32_e32 v24, v25, v24
	v_sqrt_f32_e32 v27, v27
	v_mul_f32_e32 v40, v25, v42
	v_fma_f32 v25, -v20, v20, 1.0
	v_mul_f32_e32 v21, 0xbfb8aa3b, v21
	v_mul_f32_e32 v26, v63, v26
	v_max_f32_e32 v25, 0, v25
	v_exp_f32_e32 v21, v21
	v_fmac_f32_e32 v40, v26, v27
	s_waitcnt lgkmcnt(3)
; DEVI float sigmoidf_(float x) { return __builtin_amdgcn_rcpf(1.f + __expf(-x)); }
; DEVI f32x4 mfma16(bf16x8 a, bf16x8 b, f32x4 c) { return __builtin_amdgcn_mfma_f32_16x16x32_bf16(a, b, c, 0, 0, 0); }
; DEVI void lru_item(const Params& p, int l, int item, int pass) {
;     ...
;       const u16* wb = WGT + (size_t)((((l * 2 + d) * 2 + mat) * 4 + n) * 64) * 64 + 8 * g;
;       f32x4 acc[4];
; #pragma unroll
;       for (int nt = 0; nt < 4; ++nt) {
;         const bf16x8 B0 = *(const bf16x8*)(wb + (16 * nt + fr) * 64), B1 = *(const bf16x8*)(wb + (16 * nt + fr) * 64 + 32);
;         f32x4 z = {0.f, 0.f, 0.f, 0.f};
;         z = mfma16(A0, B0, z); z = mfma16(A1, B1, z); acc[nt] = z;
;     ...
;     for (int q = 0; q < 16; ++q) {
;       const int tt = d == 0 ? q : 15 - q;
;       const float r = sigmoidf_(pre[0][tt] + ba), ig = sigmoidf_(pre[1][tt] + bx);
;       const float la = -8.f * r * sp;
;       const float a = __expf(la);
;       const float om = fmaxf(1.f - a * a, 0.f);
;       const float bb = sqrtf(om) * (ig * uo[tt]);
;       av[d][tt] = a; bv[d][tt] = bb;
;       Bp = a * Bp + bb; Ap *= a;
;     }
	v_add_f32_e32 v22, v22, v33
	v_add_f32_e32 v21, 1.0, v21
	v_mul_f32_e32 v22, 0xbfb8aa3b, v22
	v_rcp_f32_e32 v21, v21
	v_exp_f32_e32 v22, v22
	v_mul_f32_e32 v21, 0xc1000000, v21
	v_add_f32_e32 v22, 1.0, v22
	v_mul_f32_e32 v21, v21, v83
	v_rcp_f32_e32 v22, v22
	v_mul_f32_e32 v21, 0x3fb8aa3b, v21
	v_exp_f32_e32 v21, v21
	v_add_f32_e32 v16, v16, v31
	v_mul_f32_e32 v22, v64, v22
	v_sqrt_f32_e32 v25, v25
	v_mul_f32_e32 v26, v20, v40
	v_mul_f32_e32 v16, 0xbfb8aa3b, v16
	v_fmac_f32_e32 v26, v22, v25
	v_add_f32_e32 v22, v23, v33
	v_fma_f32 v23, -v21, v21, 1.0
	v_exp_f32_e32 v16, v16
	v_max_f32_e32 v23, 0, v23
	v_mul_f32_e32 v20, v20, v24
	v_add_f32_e32 v16, 1.0, v16
	v_rcp_f32_e32 v16, v16
	v_mul_f32_e32 v22, 0xbfb8aa3b, v22
	v_exp_f32_e32 v22, v22
	v_mul_f32_e32 v16, 0xc1000000, v16
	v_mul_f32_e32 v16, v16, v83
	v_mul_f32_e32 v16, 0x3fb8aa3b, v16
	v_add_f32_e32 v22, 1.0, v22
	v_exp_f32_e32 v16, v16
	v_rcp_f32_e32 v22, v22
	v_add_f32_e32 v17, v17, v31
	v_mul_f32_e32 v20, v21, v20
	v_sqrt_f32_e32 v23, v23
	v_mul_f32_e32 v24, v21, v26
	v_fma_f32 v21, -v16, v16, 1.0
	v_mul_f32_e32 v17, 0xbfb8aa3b, v17
	v_mul_f32_e32 v22, v65, v22
	v_max_f32_e32 v21, 0, v21
	v_exp_f32_e32 v17, v17
	v_fmac_f32_e32 v24, v22, v23
	s_waitcnt lgkmcnt(2)
	v_add_f32_e32 v18, v18, v33
	v_add_f32_e32 v17, 1.0, v17
	v_mul_f32_e32 v18, 0xbfb8aa3b, v18
	v_rcp_f32_e32 v17, v17
	v_exp_f32_e32 v18, v18
	v_mul_f32_e32 v17, 0xc1000000, v17
	v_add_f32_e32 v18, 1.0, v18
	v_mul_f32_e32 v17, v17, v83
	v_rcp_f32_e32 v18, v18
	v_mul_f32_e32 v17, 0x3fb8aa3b, v17
	v_exp_f32_e32 v17, v17
	v_add_f32_e32 v10, v10, v31
	v_mul_f32_e32 v18, v66, v18
	v_sqrt_f32_e32 v21, v21
	v_mul_f32_e32 v22, v16, v24
	v_mul_f32_e32 v10, 0xbfb8aa3b, v10
	v_fmac_f32_e32 v22, v18, v21
	v_add_f32_e32 v18, v19, v33
	v_fma_f32 v19, -v17, v17, 1.0
	v_exp_f32_e32 v10, v10
	v_max_f32_e32 v19, 0, v19
	v_mul_f32_e32 v16, v16, v20
	v_add_f32_e32 v10, 1.0, v10
	v_rcp_f32_e32 v10, v10
	v_mul_f32_e32 v18, 0xbfb8aa3b, v18
	v_exp_f32_e32 v18, v18
	v_mul_f32_e32 v10, 0xc1000000, v10
	v_mul_f32_e32 v10, v10, v83
	v_mul_f32_e32 v10, 0x3fb8aa3b, v10
	v_add_f32_e32 v18, 1.0, v18
	v_exp_f32_e32 v10, v10
	v_rcp_f32_e32 v18, v18
	v_add_f32_e32 v11, v11, v31
	v_mul_f32_e32 v16, v17, v16
	v_sqrt_f32_e32 v19, v19
	v_mul_f32_e32 v20, v17, v22
	v_fma_f32 v17, -v10, v10, 1.0
	v_mul_f32_e32 v11, 0xbfb8aa3b, v11
	v_mul_f32_e32 v18, v67, v18
	v_max_f32_e32 v17, 0, v17
	v_exp_f32_e32 v11, v11
	v_fmac_f32_e32 v20, v18, v19
	s_waitcnt lgkmcnt(1)
	v_add_f32_e32 v14, v14, v33
	v_add_f32_e32 v11, 1.0, v11
	v_mul_f32_e32 v14, 0xbfb8aa3b, v14
	v_rcp_f32_e32 v11, v11
	v_exp_f32_e32 v14, v14
	v_mul_f32_e32 v11, 0xc1000000, v11
	v_add_f32_e32 v14, 1.0, v14
	v_mul_f32_e32 v11, v11, v83
	v_rcp_f32_e32 v14, v14
	v_mul_f32_e32 v11, 0x3fb8aa3b, v11
	v_exp_f32_e32 v11, v11
	v_add_f32_e32 v8, v8, v31
	v_mul_f32_e32 v14, v68, v14
	v_sqrt_f32_e32 v17, v17
	v_mul_f32_e32 v18, v10, v20
	v_mul_f32_e32 v8, 0xbfb8aa3b, v8
	v_fmac_f32_e32 v18, v14, v17
	v_add_f32_e32 v14, v15, v33
	v_fma_f32 v15, -v11, v11, 1.0
	v_exp_f32_e32 v8, v8
	v_max_f32_e32 v15, 0, v15
	v_mul_f32_e32 v10, v10, v16
	v_add_f32_e32 v8, 1.0, v8
	v_rcp_f32_e32 v8, v8
	v_mul_f32_e32 v14, 0xbfb8aa3b, v14
	v_exp_f32_e32 v14, v14
	v_mul_f32_e32 v8, 0xc1000000, v8
	v_mul_f32_e32 v8, v8, v83
	v_mul_f32_e32 v8, 0x3fb8aa3b, v8
	v_add_f32_e32 v14, 1.0, v14
	v_exp_f32_e32 v8, v8
	v_rcp_f32_e32 v14, v14
	v_mul_f32_e32 v10, v11, v10
	v_mul_f32_e32 v14, v70, v14
	v_sqrt_f32_e32 v15, v15
	v_mul_f32_e32 v16, v11, v18
	s_waitcnt lgkmcnt(0)
	v_add_f32_e32 v11, v12, v33
	v_fma_f32 v12, -v8, v8, 1.0
	v_max_f32_e32 v12, 0, v12
	v_fmac_f32_e32 v16, v14, v15
	v_add_f32_e32 v9, v9, v31
	v_mul_f32_e32 v9, 0xbfb8aa3b, v9
	v_exp_f32_e32 v9, v9
	v_mul_f32_e32 v11, 0xbfb8aa3b, v11
	v_exp_f32_e32 v11, v11
	v_add_f32_e32 v9, 1.0, v9
	v_rcp_f32_e32 v9, v9
	v_add_f32_e32 v11, 1.0, v11
	v_rcp_f32_e32 v11, v11
	v_mul_f32_e32 v9, 0xc1000000, v9
	v_mul_f32_e32 v9, v9, v83
	v_mul_f32_e32 v11, v71, v11
	v_mul_f32_e32 v9, 0x3fb8aa3b, v9
	v_sqrt_f32_e32 v12, v12
	v_mul_f32_e32 v14, v8, v16
	v_fmac_f32_e32 v14, v11, v12
	v_exp_f32_e32 v11, v9
	v_mul_f32_e32 v8, v8, v10
	v_add_f32_e32 v10, v13, v33
	v_mul_f32_e32 v10, 0xbfb8aa3b, v10
	v_fma_f32 v9, -v11, v11, 1.0
	v_max_f32_e32 v9, 0, v9
	v_exp_f32_e32 v10, v10
	s_mov_b64 s[0:1], 0x10000
	v_add_f32_e32 v10, 1.0, v10
	v_rcp_f32_e32 v10, v10
	s_nop 0
	v_mul_f32_e32 v10, v69, v10
	v_mul_f32_e32 v8, v11, v8
	v_lshl_add_u64 v[24:25], v[28:29], 0, s[0:1]
	v_lshlrev_b32_e32 v40, 1, v73
	v_mov_b32_e32 v41, v213
	v_sqrt_f32_e32 v12, v9
	v_mul_f32_e32 v9, v11, v14
	v_fmac_f32_e32 v9, v10, v12
	v_lshlrev_b32_e32 v10, 3, v54
	v_add_u32_e32 v44, 0, v10
	v_add_u32_e32 v10, 0x15b00, v44
	ds_write_b64 v10, v[8:9]
	v_lshl_add_u64 v[12:13], v[24:25], 0, v[40:41]
	global_load_dwordx4 v[8:11], v[12:13], off
	s_nop 0
	global_load_dwordx4 v[12:15], v[12:13], off offset:64
	s_waitcnt vmcnt(1)
	v_mfma_f32_16x16x32_bf16 v[8:11], v[4:7], v[8:11], 0
	v_lshl_add_u64 v[16:17], v[24:25], 0, v[212:213]
	v_mov_b32_e32 v31, v213
	v_lshl_add_u64 v[20:21], v[24:25], 0, v[30:31]
	s_waitcnt vmcnt(0)
	v_mfma_f32_16x16x32_bf16 v[8:11], v[0:3], v[12:15], v[8:11]
	global_load_dwordx4 v[12:15], v[16:17], off
	s_nop 0
	global_load_dwordx4 v[16:19], v[16:17], off offset:64
	v_mov_b32_e32 v33, v213
	v_lshl_add_u64 v[24:25], v[24:25], 0, v[32:33]
	s_waitcnt vmcnt(1)
	v_mfma_f32_16x16x32_bf16 v[12:15], v[4:7], v[12:15], 0
	v_mul_u32_u24_e32 v82, 0x410, v82
	s_mov_b64 s[0:1], 0x18000
	s_waitcnt vmcnt(0)
	v_mfma_f32_16x16x32_bf16 v[12:15], v[0:3], v[16:19], v[12:15]
	global_load_dwordx4 v[16:19], v[20:21], off
	s_nop 0
	global_load_dwordx4 v[20:23], v[20:21], off offset:64
	s_waitcnt vmcnt(1)
; DEVI f32x4 mfma16(bf16x8 a, bf16x8 b, f32x4 c) { return __builtin_amdgcn_mfma_f32_16x16x32_bf16(a, b, c, 0, 0, 0); }
; DEVI void lru_item(const Params& p, int l, int item, int pass) {
;     ...
;       const u16* wb = WGT + (size_t)((((l * 2 + d) * 2 + mat) * 4 + n) * 64) * 64 + 8 * g;
;       f32x4 acc[4];
; #pragma unroll
;       for (int nt = 0; nt < 4; ++nt) {
;         const bf16x8 B0 = *(const bf16x8*)(wb + (16 * nt + fr) * 64), B1 = *(const bf16x8*)(wb + (16 * nt + fr) * 64 + 32);
;         f32x4 z = {0.f, 0.f, 0.f, 0.f};
;         z = mfma16(A0, B0, z); z = mfma16(A1, B1, z); acc[nt] = z;
;       }
;       asm volatile("s_waitcnt lgkmcnt(0)" ::: "memory");
; #pragma unroll
;       for (int nt = 0; nt < 4; ++nt)
; #pragma unroll
;         for (int j = 0; j < 4; ++j) exw[(4 * g + j) * 65 + 16 * nt + fr] = acc[nt][j];
;       asm volatile("s_waitcnt lgkmcnt(0)" ::: "memory");
; #pragma unroll
;       for (int tt = 0; tt < 16; ++tt) pre[mat][tt] = exw[tt * 65 + lane];
;     }
;     const float ba = p.in[14][(l * 2 + d) * 256 + c], bx = p.in[16][(l * 2 + d) * 256 + c];
;     const float lam = p.in[17][(l * 2 + d) * 256 + c];
;     const float exl = __expf(-lam); const float sp = exl < 0.03f ? exl * (1.f - exl * (0.5f - exl * (0.33333334f - 0.25f * exl))) : __logf(1.f + exl);
	v_mfma_f32_16x16x32_bf16 v[16:19], v[4:7], v[16:19], 0
	s_waitcnt vmcnt(0)
	v_mfma_f32_16x16x32_bf16 v[16:19], v[0:3], v[20:23], v[16:19]
	global_load_dwordx4 v[20:23], v[24:25], off
	s_nop 0
	global_load_dwordx4 v[24:27], v[24:25], off offset:64
	s_waitcnt lgkmcnt(0)
	s_waitcnt vmcnt(1)
	v_mfma_f32_16x16x32_bf16 v[20:23], v[4:7], v[20:23], 0
	s_waitcnt vmcnt(0)
	v_mfma_f32_16x16x32_bf16 v[20:23], v[0:3], v[24:27], v[20:23]
	v_add_u32_e32 v24, v72, v82
	v_add_u32_e32 v45, 0xd800, v24
	v_add_u32_e32 v50, 0xdc00, v24
	ds_write2_b32 v45, v8, v12 offset0:64 offset1:80
	ds_write2_b32 v45, v9, v13 offset0:129 offset1:145
	ds_write2_b32 v45, v10, v14 offset0:194 offset1:210
	ds_write2_b32 v50, v11, v15 offset0:3 offset1:19
	s_nop 0
	ds_write2_b32 v45, v16, v20 offset0:96 offset1:112
	ds_write2_b32 v45, v17, v21 offset0:161 offset1:177
	ds_write2_b32 v45, v18, v22 offset0:226 offset1:242
	ds_write2_b32 v50, v19, v23 offset0:35 offset1:51
	v_lshl_add_u64 v[18:19], v[28:29], 0, s[0:1]
	s_waitcnt lgkmcnt(0)
	v_lshl_add_u64 v[22:23], v[18:19], 0, v[40:41]
	ds_read2_b32 v[8:9], v74 offset0:64 offset1:129
	ds_read2_b32 v[10:11], v75 offset0:66 offset1:131
	ds_read2_b32 v[12:13], v76 offset0:68 offset1:133
	ds_read2_b32 v[14:15], v77 offset0:70 offset1:135
	ds_read2_b32 v[16:17], v78 offset0:72 offset1:137
	ds_read2_b32 v[20:21], v79 offset0:74 offset1:139
	ds_read2_b32 v[24:25], v80 offset0:76 offset1:141
	ds_read2_b32 v[42:43], v81 offset0:78 offset1:143
	global_load_dwordx4 v[26:29], v[22:23], off
	global_load_dwordx4 v[46:49], v[22:23], off offset:64
	s_waitcnt vmcnt(1)
	v_mfma_f32_16x16x32_bf16 v[26:29], v[4:7], v[26:29], 0
	v_lshl_add_u64 v[22:23], v[18:19], 0, v[212:213]
	s_mov_b32 s0, 0x3cf5c28f
	s_waitcnt vmcnt(0)
	v_mfma_f32_16x16x32_bf16 v[26:29], v[0:3], v[46:49], v[26:29]
	global_load_dwordx4 v[46:49], v[22:23], off
	global_load_dwordx4 v[82:85], v[22:23], off offset:64
	v_lshl_add_u64 v[22:23], v[18:19], 0, v[30:31]
	v_lshl_add_u64 v[18:19], v[18:19], 0, v[32:33]
	s_waitcnt vmcnt(1)
	v_mfma_f32_16x16x32_bf16 v[46:49], v[4:7], v[46:49], 0
	s_waitcnt vmcnt(0)
	v_mfma_f32_16x16x32_bf16 v[46:49], v[0:3], v[82:85], v[46:49]
	global_load_dwordx4 v[82:85], v[22:23], off
	global_load_dwordx4 v[86:89], v[22:23], off offset:64
	s_waitcnt vmcnt(1)
	v_mfma_f32_16x16x32_bf16 v[82:85], v[4:7], v[82:85], 0
	s_waitcnt vmcnt(0)
	v_mfma_f32_16x16x32_bf16 v[82:85], v[0:3], v[86:89], v[82:85]
	global_load_dwordx4 v[30:33], v[18:19], off
	global_load_dwordx4 v[86:89], v[18:19], off offset:64
	s_waitcnt lgkmcnt(0)
	s_waitcnt vmcnt(1)
	v_mfma_f32_16x16x32_bf16 v[4:7], v[4:7], v[30:33], 0
	s_waitcnt vmcnt(0)
	v_mfma_f32_16x16x32_bf16 v[0:3], v[0:3], v[86:89], v[4:7]
	ds_write2_b32 v45, v26, v46 offset0:64 offset1:80
	ds_write2_b32 v45, v27, v47 offset0:129 offset1:145
	ds_write2_b32 v45, v28, v48 offset0:194 offset1:210
	ds_write2_b32 v50, v29, v49 offset0:3 offset1:19
	s_nop 3
	ds_write2_b32 v45, v82, v0 offset0:96 offset1:112
	ds_write2_b32 v45, v83, v1 offset0:161 offset1:177
	ds_write2_b32 v45, v84, v2 offset0:226 offset1:242
	ds_write2_b32 v50, v85, v3 offset0:35 offset1:51
	s_waitcnt lgkmcnt(0)
	ds_read2_b32 v[0:1], v74 offset0:64 offset1:129
	ds_read2_b32 v[2:3], v75 offset0:66 offset1:131
	ds_read2_b32 v[4:5], v76 offset0:68 offset1:133
	ds_read2_b32 v[6:7], v77 offset0:70 offset1:135
	ds_read2_b32 v[18:19], v78 offset0:72 offset1:137
	ds_read2_b32 v[22:23], v79 offset0:74 offset1:139
	ds_read2_b32 v[26:27], v80 offset0:76 offset1:141
	ds_read2_b32 v[28:29], v81 offset0:78 offset1:143
	global_load_dword v31, v[34:35], off offset:1024
	global_load_dword v30, v[36:37], off offset:1024
	global_load_dword v32, v[38:39], off offset:1024
	s_waitcnt vmcnt(0)
	v_mul_f32_e32 v32, 0xbfb8aa3b, v32
	v_exp_f32_e32 v33, v32
	s_nop 0
	v_cmp_ngt_f32_e64 s[6:7], s0, v33
	s_and_saveexec_b64 s[0:1], s[6:7]
	s_xor_b64 s[4:5], exec, s[0:1]
	s_cbranch_execz .LBB0_1300
	v_add_f32_e32 v32, 1.0, v33
	v_cmp_gt_f32_e64 s[6:7], s63, v32
	s_mov_b32 s0, 0x3f317217
	s_nop 0
	v_cndmask_b32_e64 v33, 0, 32, s[6:7]
	v_ldexp_f32 v32, v32, v33
	v_log_f32_e32 v32, v32
	s_nop 0
	v_mul_f32_e32 v33, 0x3f317217, v32
	v_fma_f32 v33, v32, s0, -v33
	v_fmac_f32_e32 v33, 0x3377d1cf, v32
	s_mov_b32 s0, 0x7f800000
	v_fmac_f32_e32 v33, 0x3f317217, v32
	v_cmp_lt_f32_e64 s[8:9], |v32|, s0
	s_nop 1
	v_cndmask_b32_e64 v32, v32, v33, s[8:9]
	v_cndmask_b32_e64 v33, 0, v225, s[6:7]
	v_sub_f32_e32 v32, v32, v33
; DEVI float sigmoidf_(float x) { return __builtin_amdgcn_rcpf(1.f + __expf(-x)); }
; DEVI void lru_item(const Params& p, int l, int item, int pass) {
;     ...
;     const float ba = p.in[14][(l * 2 + d) * 256 + c], bx = p.in[16][(l * 2 + d) * 256 + c];
;     const float lam = p.in[17][(l * 2 + d) * 256 + c];
;     const float exl = __expf(-lam); const float sp = exl < 0.03f ? exl * (1.f - exl * (0.5f - exl * (0.33333334f - 0.25f * exl))) : __logf(1.f + exl);
;     float Ap = 1.f, Bp = 0.f;
; #pragma unroll
;     for (int q = 0; q < 16; ++q) {
;       const int tt = d == 0 ? q : 15 - q;
;       const float r = sigmoidf_(pre[0][tt] + ba), ig = sigmoidf_(pre[1][tt] + bx);
;       const float la = -8.f * r * sp;
;       const float a = __expf(la);
;       const float om = fmaxf(1.f - a * a, 0.f);
;       const float bb = sqrtf(om) * (ig * uo[tt]);
;       av[d][tt] = a; bv[d][tt] = bb;
;       Bp = a * Bp + bb; Ap *= a;
;     }
;     sm[((d * 8 + tg) * 64 + e) * 2 + 0] = Ap; sm[((d * 8 + tg) * 64 + e) * 2 + 1] = Bp;
.LBB0_1300:
	s_andn2_saveexec_b64 s[4:5], s[4:5]
	v_mov_b32_e32 v32, 0x3eaaaaab
	v_fmamk_f32 v32, v33, 0xbe800000, v32
	v_fma_f32 v32, -v33, v32, 0.5
	v_fma_f32 v32, -v33, v32, 1.0
	v_mul_f32_e32 v32, v33, v32
	s_or_b64 exec, exec, s[4:5]
	s_waitcnt lgkmcnt(14)
	v_add_f32_e32 v33, v43, v31
	v_mul_f32_e32 v33, 0xbfb8aa3b, v33
	v_exp_f32_e32 v33, v33
	s_waitcnt lgkmcnt(0)
	v_add_f32_e32 v29, v29, v30
	v_mul_f32_e32 v29, 0xbfb8aa3b, v29
	v_exp_f32_e32 v29, v29
	v_add_f32_e32 v33, 1.0, v33
	v_rcp_f32_e32 v33, v33
	v_add_f32_e32 v25, v25, v31
	v_add_f32_e32 v29, 1.0, v29
	v_rcp_f32_e32 v29, v29
	v_mul_f32_e32 v33, 0xc1000000, v33
	v_mul_f32_e32 v33, v33, v32
	v_mul_f32_e32 v33, 0x3fb8aa3b, v33
	v_exp_f32_e32 v33, v33
	v_mul_f32_e32 v29, v69, v29
	v_mul_f32_e32 v25, 0xbfb8aa3b, v25
	v_exp_f32_e32 v25, v25
	v_fma_f32 v34, -v33, v33, 1.0
	v_max_f32_e32 v34, 0, v34
	v_add_f32_e32 v28, v28, v30
	v_add_f32_e32 v25, 1.0, v25
	v_mul_f32_e32 v28, 0xbfb8aa3b, v28
	v_rcp_f32_e32 v25, v25
	v_exp_f32_e32 v28, v28
	v_mul_f32_e32 v25, 0xc1000000, v25
	v_add_f32_e32 v28, 1.0, v28
	v_mul_f32_e32 v25, v25, v32
	v_rcp_f32_e32 v28, v28
	v_sqrt_f32_e32 v34, v34
	s_nop 0
	v_mul_f32_e32 v29, v29, v34
	v_add_f32_e32 v34, v42, v31
	v_mul_f32_e32 v34, 0xbfb8aa3b, v34
	v_exp_f32_e32 v34, v34
	v_mul_f32_e32 v25, 0x3fb8aa3b, v25
	v_exp_f32_e32 v25, v25
	v_fmac_f32_e32 v29, 0, v33
	v_add_f32_e32 v34, 1.0, v34
	v_rcp_f32_e32 v34, v34
	v_mul_f32_e32 v28, v71, v28
	v_add_f32_e32 v24, v24, v31
	v_mul_f32_e32 v24, 0xbfb8aa3b, v24
	v_mul_f32_e32 v34, 0xc1000000, v34
	v_mul_f32_e32 v34, v34, v32
	v_mul_f32_e32 v34, 0x3fb8aa3b, v34
	v_exp_f32_e32 v34, v34
	v_exp_f32_e32 v24, v24
	v_add_f32_e32 v27, v27, v30
	v_mul_f32_e32 v27, 0xbfb8aa3b, v27
	v_fma_f32 v35, -v34, v34, 1.0
	v_max_f32_e32 v35, 0, v35
	v_mul_f32_e32 v29, v34, v29
	v_add_f32_e32 v24, 1.0, v24
	v_rcp_f32_e32 v24, v24
	v_exp_f32_e32 v27, v27
	v_mul_f32_e32 v24, 0xc1000000, v24
	v_add_f32_e32 v27, 1.0, v27
	v_mul_f32_e32 v24, v24, v32
	v_rcp_f32_e32 v27, v27
	v_mul_f32_e32 v24, 0x3fb8aa3b, v24
	v_sqrt_f32_e32 v35, v35
	s_nop 0
	v_fmac_f32_e32 v29, v28, v35
	v_mul_f32_e32 v28, v33, v34
	v_fma_f32 v33, -v25, v25, 1.0
	v_max_f32_e32 v33, 0, v33
	v_exp_f32_e32 v24, v24
	v_add_f32_e32 v21, v21, v31
	v_mul_f32_e32 v27, v70, v27
	v_mul_f32_e32 v29, v25, v29
	v_mul_f32_e32 v21, 0xbfb8aa3b, v21
	v_exp_f32_e32 v21, v21
	v_mul_f32_e32 v25, v25, v28
	v_add_f32_e32 v21, 1.0, v21
	v_rcp_f32_e32 v21, v21
	v_sqrt_f32_e32 v33, v33
	s_nop 0
	v_fmac_f32_e32 v29, v27, v33
	v_fma_f32 v27, -v24, v24, 1.0
	v_max_f32_e32 v27, 0, v27
	v_add_f32_e32 v26, v26, v30
	v_mul_f32_e32 v26, 0xbfb8aa3b, v26
	v_exp_f32_e32 v26, v26
	v_mul_f32_e32 v21, 0xc1000000, v21
	v_mul_f32_e32 v21, v21, v32
	v_mul_f32_e32 v21, 0x3fb8aa3b, v21
	v_add_f32_e32 v26, 1.0, v26
	v_exp_f32_e32 v21, v21
	v_rcp_f32_e32 v26, v26
	v_add_f32_e32 v20, v20, v31
	v_mul_f32_e32 v20, 0xbfb8aa3b, v20
	v_sqrt_f32_e32 v27, v27
	v_mul_f32_e32 v28, v24, v29
	v_mul_f32_e32 v24, v24, v25
	v_fma_f32 v25, -v21, v21, 1.0
	v_mul_f32_e32 v26, v68, v26
	v_max_f32_e32 v25, 0, v25
	v_exp_f32_e32 v20, v20
	v_fmac_f32_e32 v28, v26, v27
	v_add_f32_e32 v23, v23, v30
	v_add_f32_e32 v20, 1.0, v20
	v_mul_f32_e32 v23, 0xbfb8aa3b, v23
	v_rcp_f32_e32 v20, v20
	v_exp_f32_e32 v23, v23
	v_mul_f32_e32 v20, 0xc1000000, v20
	v_add_f32_e32 v23, 1.0, v23
	v_mul_f32_e32 v20, v20, v32
	v_rcp_f32_e32 v23, v23
	v_mul_f32_e32 v20, 0x3fb8aa3b, v20
	v_exp_f32_e32 v20, v20
	v_add_f32_e32 v17, v17, v31
	v_mul_f32_e32 v23, v67, v23
	v_sqrt_f32_e32 v25, v25
	v_mul_f32_e32 v26, v21, v28
	v_mul_f32_e32 v17, 0xbfb8aa3b, v17
	v_fmac_f32_e32 v26, v23, v25
	v_fma_f32 v23, -v20, v20, 1.0
	v_exp_f32_e32 v17, v17
	v_max_f32_e32 v23, 0, v23
	v_mul_f32_e32 v21, v21, v24
	v_add_f32_e32 v17, 1.0, v17
	v_rcp_f32_e32 v17, v17
	v_add_f32_e32 v22, v22, v30
	v_mul_f32_e32 v22, 0xbfb8aa3b, v22
	v_exp_f32_e32 v22, v22
	v_mul_f32_e32 v17, 0xc1000000, v17
	v_mul_f32_e32 v17, v17, v32
	v_mul_f32_e32 v17, 0x3fb8aa3b, v17
	v_add_f32_e32 v22, 1.0, v22
	v_exp_f32_e32 v17, v17
	v_rcp_f32_e32 v22, v22
	v_add_f32_e32 v16, v16, v31
	v_mul_f32_e32 v16, 0xbfb8aa3b, v16
	v_sqrt_f32_e32 v23, v23
	v_mul_f32_e32 v24, v20, v26
	v_mul_f32_e32 v20, v20, v21
	v_fma_f32 v21, -v17, v17, 1.0
	v_mul_f32_e32 v22, v66, v22
	v_max_f32_e32 v21, 0, v21
	v_exp_f32_e32 v16, v16
	v_fmac_f32_e32 v24, v22, v23
	v_add_f32_e32 v19, v19, v30
	v_add_f32_e32 v16, 1.0, v16
	v_mul_f32_e32 v19, 0xbfb8aa3b, v19
	v_rcp_f32_e32 v16, v16
	v_exp_f32_e32 v19, v19
	v_mul_f32_e32 v16, 0xc1000000, v16
	v_add_f32_e32 v19, 1.0, v19
	v_mul_f32_e32 v16, v16, v32
	v_rcp_f32_e32 v19, v19
	v_mul_f32_e32 v16, 0x3fb8aa3b, v16
	v_exp_f32_e32 v16, v16
	v_add_f32_e32 v15, v15, v31
	v_mul_f32_e32 v19, v65, v19
	v_sqrt_f32_e32 v21, v21
	v_mul_f32_e32 v22, v17, v24
	v_mul_f32_e32 v15, 0xbfb8aa3b, v15
	v_fmac_f32_e32 v22, v19, v21
	v_fma_f32 v19, -v16, v16, 1.0
	v_exp_f32_e32 v15, v15
	v_max_f32_e32 v19, 0, v19
	v_mul_f32_e32 v17, v17, v20
	v_add_f32_e32 v15, 1.0, v15
	v_rcp_f32_e32 v15, v15
	v_add_f32_e32 v18, v18, v30
	v_mul_f32_e32 v18, 0xbfb8aa3b, v18
	v_exp_f32_e32 v18, v18
	v_mul_f32_e32 v15, 0xc1000000, v15
	v_mul_f32_e32 v15, v15, v32
	v_mul_f32_e32 v15, 0x3fb8aa3b, v15
	v_add_f32_e32 v18, 1.0, v18
	v_exp_f32_e32 v15, v15
	v_rcp_f32_e32 v18, v18
	v_add_f32_e32 v14, v14, v31
	v_mul_f32_e32 v14, 0xbfb8aa3b, v14
	v_sqrt_f32_e32 v19, v19
	v_mul_f32_e32 v20, v16, v22
	v_mul_f32_e32 v16, v16, v17
	v_fma_f32 v17, -v15, v15, 1.0
	v_mul_f32_e32 v18, v64, v18
	v_max_f32_e32 v17, 0, v17
	v_exp_f32_e32 v14, v14
	v_fmac_f32_e32 v20, v18, v19
	v_add_f32_e32 v7, v7, v30
	v_add_f32_e32 v14, 1.0, v14
	v_mul_f32_e32 v7, 0xbfb8aa3b, v7
; DEVI float sigmoidf_(float x) { return __builtin_amdgcn_rcpf(1.f + __expf(-x)); }
; DEVI void lru_item(const Params& p, int l, int item, int pass) {
;     ...
;     for (int q = 0; q < 16; ++q) {
;       const int tt = d == 0 ? q : 15 - q;
;       const float r = sigmoidf_(pre[0][tt] + ba), ig = sigmoidf_(pre[1][tt] + bx);
;       const float la = -8.f * r * sp;
;       const float a = __expf(la);
;       const float om = fmaxf(1.f - a * a, 0.f);
;       const float bb = sqrtf(om) * (ig * uo[tt]);
;       av[d][tt] = a; bv[d][tt] = bb;
;       Bp = a * Bp + bb; Ap *= a;
;     }
;     sm[((d * 8 + tg) * 64 + e) * 2 + 0] = Ap; sm[((d * 8 + tg) * 64 + e) * 2 + 1] = Bp;
;   }
;   __syncthreads();
;   if (!pass) {
;     if (tid < 128) {
;       const int d = tid >> 6, ee = tid & 63;
;       float A = 1.f, Bc = 0.f;
;       if (d == 0) { for (int g2 = 0; g2 < 8; ++g2) { const float a = sm[((0 * 8 + g2) * 64 + ee) * 2], bq = sm[((0 * 8 + g2) * 64 + ee) * 2 + 1]; Bc = a * Bc + bq; A *= a; } }
;     ...
;       SUMM[((size_t)d * 272 + ch) * 256 + n * 64 + ee] = make_float2(A, Bc);
	v_rcp_f32_e32 v14, v14
	v_exp_f32_e32 v7, v7
	v_mul_f32_e32 v14, 0xc1000000, v14
	v_add_f32_e32 v7, 1.0, v7
	v_mul_f32_e32 v14, v14, v32
	v_rcp_f32_e32 v7, v7
	v_mul_f32_e32 v14, 0x3fb8aa3b, v14
	v_exp_f32_e32 v14, v14
	v_mul_f32_e32 v7, v63, v7
	v_add_f32_e32 v6, v6, v30
	v_sqrt_f32_e32 v17, v17
	v_mul_f32_e32 v18, v15, v20
	v_fmac_f32_e32 v18, v7, v17
	v_mul_f32_e32 v7, v15, v16
	v_fma_f32 v15, -v14, v14, 1.0
	v_max_f32_e32 v15, 0, v15
	v_mul_f32_e32 v6, 0xbfb8aa3b, v6
	v_exp_f32_e32 v6, v6
	v_add_f32_e32 v5, v5, v30
	v_mul_f32_e32 v5, 0xbfb8aa3b, v5
	v_add_f32_e32 v6, 1.0, v6
	v_rcp_f32_e32 v6, v6
	v_exp_f32_e32 v5, v5
	v_add_f32_e32 v4, v4, v30
	v_mul_f32_e32 v6, v62, v6
	v_add_f32_e32 v5, 1.0, v5
	v_sqrt_f32_e32 v15, v15
	v_mul_f32_e32 v16, v14, v18
	v_fmac_f32_e32 v16, v6, v15
	v_mul_f32_e32 v6, v14, v7
	v_add_f32_e32 v7, v13, v31
	v_mul_f32_e32 v7, 0xbfb8aa3b, v7
	v_exp_f32_e32 v7, v7
	v_rcp_f32_e32 v5, v5
	v_mul_f32_e32 v4, 0xbfb8aa3b, v4
	v_exp_f32_e32 v4, v4
	v_add_f32_e32 v7, 1.0, v7
	v_rcp_f32_e32 v7, v7
	v_mul_f32_e32 v5, v61, v5
	v_add_f32_e32 v4, 1.0, v4
	v_rcp_f32_e32 v4, v4
	v_mul_f32_e32 v7, 0xc1000000, v7
	v_mul_f32_e32 v7, v7, v32
	v_mul_f32_e32 v7, 0x3fb8aa3b, v7
	v_exp_f32_e32 v7, v7
	v_mul_f32_e32 v4, v60, v4
	v_add_f32_e32 v3, v3, v30
	v_mul_f32_e32 v3, 0xbfb8aa3b, v3
	v_fma_f32 v13, -v7, v7, 1.0
	v_max_f32_e32 v13, 0, v13
	v_exp_f32_e32 v3, v3
	v_add_f32_e32 v2, v2, v30
	v_add_f32_e32 v3, 1.0, v3
	v_rcp_f32_e32 v3, v3
	s_nop 0
	v_mul_f32_e32 v3, v59, v3
	v_mul_f32_e32 v2, 0xbfb8aa3b, v2
	v_exp_f32_e32 v2, v2
	s_nop 0
	v_add_f32_e32 v2, 1.0, v2
	v_rcp_f32_e32 v2, v2
	v_sqrt_f32_e32 v13, v13
	v_mul_f32_e32 v14, v7, v16
	v_fmac_f32_e32 v14, v5, v13
	v_mul_f32_e32 v5, v7, v6
	v_add_f32_e32 v6, v12, v31
	v_mul_f32_e32 v6, 0xbfb8aa3b, v6
	v_exp_f32_e32 v6, v6
	v_mul_f32_e32 v2, v58, v2
	v_add_f32_e32 v1, v1, v30
	v_mul_f32_e32 v1, 0xbfb8aa3b, v1
	v_add_f32_e32 v6, 1.0, v6
	v_rcp_f32_e32 v6, v6
	v_exp_f32_e32 v1, v1
	v_add_f32_e32 v0, v0, v30
	v_mul_f32_e32 v0, 0xbfb8aa3b, v0
	v_mul_f32_e32 v6, 0xc1000000, v6
	v_mul_f32_e32 v6, v6, v32
	v_mul_f32_e32 v6, 0x3fb8aa3b, v6
	v_exp_f32_e32 v6, v6
	v_add_f32_e32 v1, 1.0, v1
	v_rcp_f32_e32 v1, v1
	v_exp_f32_e32 v0, v0
	v_fma_f32 v7, -v6, v6, 1.0
	v_max_f32_e32 v7, 0, v7
	v_mul_f32_e32 v1, v57, v1
	v_add_f32_e32 v0, 1.0, v0
	v_rcp_f32_e32 v0, v0
	s_nop 0
	v_mul_f32_e32 v0, v56, v0
	s_nop 1
	s_nop 1
	v_sqrt_f32_e32 v7, v7
	v_mul_f32_e32 v12, v6, v14
	v_fmac_f32_e32 v12, v4, v7
	v_mul_f32_e32 v4, v6, v5
	v_add_f32_e32 v5, v11, v31
	v_mul_f32_e32 v5, 0xbfb8aa3b, v5
	v_exp_f32_e32 v5, v5
	s_nop 0
	v_add_f32_e32 v5, 1.0, v5
	v_rcp_f32_e32 v5, v5
	s_nop 0
	v_mul_f32_e32 v5, 0xc1000000, v5
	v_mul_f32_e32 v5, v5, v32
	v_mul_f32_e32 v5, 0x3fb8aa3b, v5
	v_exp_f32_e32 v5, v5
	s_nop 0
	v_fma_f32 v6, -v5, v5, 1.0
	v_max_f32_e32 v6, 0, v6
	s_nop 0
	s_nop 0
	s_nop 0
	s_nop 1
	s_nop 1
	v_sqrt_f32_e32 v6, v6
	v_mul_f32_e32 v7, v5, v12
	v_fmac_f32_e32 v7, v3, v6
	v_mul_f32_e32 v3, v5, v4
	v_add_f32_e32 v4, v10, v31
	v_mul_f32_e32 v4, 0xbfb8aa3b, v4
	v_exp_f32_e32 v4, v4
	s_nop 0
	v_add_f32_e32 v4, 1.0, v4
	v_rcp_f32_e32 v4, v4
	s_nop 0
	v_mul_f32_e32 v4, 0xc1000000, v4
	v_mul_f32_e32 v4, v4, v32
	v_mul_f32_e32 v4, 0x3fb8aa3b, v4
	v_exp_f32_e32 v4, v4
	s_nop 0
	v_fma_f32 v5, -v4, v4, 1.0
	v_max_f32_e32 v5, 0, v5
	s_nop 0
	s_nop 0
	s_nop 0
	s_nop 1
	s_nop 1
	v_sqrt_f32_e32 v5, v5
	v_mul_f32_e32 v6, v4, v7
	v_fmac_f32_e32 v6, v2, v5
	v_mul_f32_e32 v2, v4, v3
	v_add_f32_e32 v3, v9, v31
	v_mul_f32_e32 v3, 0xbfb8aa3b, v3
	v_exp_f32_e32 v3, v3
	s_nop 0
	v_add_f32_e32 v3, 1.0, v3
	v_rcp_f32_e32 v3, v3
	s_nop 0
	v_mul_f32_e32 v3, 0xc1000000, v3
	v_mul_f32_e32 v3, v3, v32
	v_mul_f32_e32 v3, 0x3fb8aa3b, v3
	v_exp_f32_e32 v3, v3
	s_nop 0
	v_fma_f32 v4, -v3, v3, 1.0
	v_max_f32_e32 v4, 0, v4
	v_mul_f32_e32 v2, v3, v2
	s_nop 0
	s_nop 0
	s_nop 1
	s_nop 1
	v_sqrt_f32_e32 v4, v4
	v_mul_f32_e32 v5, v3, v6
	v_fmac_f32_e32 v5, v1, v4
	v_add_f32_e32 v1, v8, v31
	v_mul_f32_e32 v1, 0xbfb8aa3b, v1
	v_exp_f32_e32 v1, v1
	s_nop 0
	v_add_f32_e32 v1, 1.0, v1
	v_rcp_f32_e32 v1, v1
	s_nop 0
	v_mul_f32_e32 v1, 0xc1000000, v1
	v_mul_f32_e32 v1, v1, v32
	v_mul_f32_e32 v1, 0x3fb8aa3b, v1
	v_exp_f32_e32 v3, v1
	s_nop 0
	v_fma_f32 v1, -v3, v3, 1.0
	v_max_f32_e32 v1, 0, v1
	s_nop 0
	s_nop 0
	s_nop 0
	s_nop 1
	s_nop 1
	v_sqrt_f32_e32 v4, v1
	v_mul_f32_e32 v1, v3, v5
	v_fmac_f32_e32 v1, v0, v4
	v_mul_f32_e32 v0, v3, v2
	v_add_u32_e32 v2, 0x16b00, v44
	ds_write_b64 v2, v[0:1]
	s_waitcnt lgkmcnt(0)
	s_barrier
	s_and_saveexec_b64 s[4:5], vcc
	s_cbranch_execz .LBB0_1308
	v_cmp_lt_u32_e32 vcc, 63, v54
	v_lshlrev_b32_e32 v0, 3, v55
	s_and_saveexec_b64 s[0:1], vcc
	s_xor_b64 s[6:7], exec, s[0:1]
	s_cbranch_execz .LBB0_1305
	v_readlane_b32 s0, v254, 63
	s_nop 1
	v_add_u32_e32 v1, s0, v0
	ds_read_b64 v[2:3], v1 offset:4096
	v_readlane_b32 s0, v255, 0
	s_waitcnt lgkmcnt(0)
	v_fma_f32 v1, 0, v2, v3
	v_add_u32_e32 v3, s0, v0
	ds_read_b64 v[4:5], v3 offset:4096
	v_readlane_b32 s0, v255, 1
	s_waitcnt lgkmcnt(0)
	v_fmac_f32_e32 v5, v1, v4
	v_add_u32_e32 v1, s0, v0
	ds_read_b64 v[6:7], v1 offset:4096
	v_readlane_b32 s0, v255, 2
	v_mul_f32_e32 v2, v2, v4
	s_waitcnt lgkmcnt(0)
	v_fma_f32 v1, v5, v6, v7
	v_add_u32_e32 v3, s0, v0
	v_readlane_b32 s0, v255, 3
	ds_read_b64 v[4:5], v3 offset:4096
	s_waitcnt lgkmcnt(0)
	v_fma_f32 v1, v1, v4, v5
	v_add_u32_e32 v3, s0, v0
	ds_read_b64 v[8:9], v3 offset:4096
	v_readlane_b32 s0, v255, 4
	s_waitcnt lgkmcnt(0)
	v_fma_f32 v3, v1, v8, v9
	v_add_u32_e32 v1, s0, v0
	ds_read_b64 v[10:11], v1 offset:4096
	v_readlane_b32 s0, v255, 5
	s_waitcnt lgkmcnt(0)
	v_mov_b32_e32 v7, v10
	v_add_u32_e32 v9, s0, v0
	v_pk_mul_f32 v[12:13], v[2:3], v[6:7]
	v_pk_fma_f32 v[2:3], v[2:3], v[6:7], v[10:11]
	ds_read_b64 v[6:7], v9 offset:4096
	v_mov_b32_e32 v5, v11
	s_add_i32 s0, 0, 0x15b00
	v_pk_mul_f32 v[4:5], v[12:13], v[4:5]
	v_add_u32_e32 v14, s0, v0
	v_mov_b32_e32 v2, v4
	s_waitcnt lgkmcnt(0)
	v_mov_b32_e32 v9, v6
	v_mov_b32_e32 v1, v6
	v_pk_fma_f32 v[2:3], v[2:3], v[8:9], v[6:7]
	ds_read_b64 v[6:7], v14 offset:4096
	v_pk_mul_f32 v[4:5], v[4:5], v[8:9]
	s_waitcnt lgkmcnt(0)
	v_pk_mov_b32 v[8:9], v[0:1], v[6:7] op_sel:[1,0]
	v_pk_mul_f32 v[4:5], v[4:5], v[10:11]
	s_nop 0
	v_mov_b32_e32 v2, v4
	v_pk_mul_f32 v[4:5], v[4:5], v[8:9]
	v_pk_fma_f32 v[2:3], v[2:3], v[8:9], v[6:7]
	s_nop 0
	v_mul_f32_e32 v2, v4, v6

; DEVI float sigmoidf_(float x) { return __builtin_amdgcn_rcpf(1.f + __expf(-x)); }
; DEVI void lru_item(const Params& p, int l, int item, int pass) {
;     ...
;     const float exl = __expf(-lam); const float sp = exl < 0.03f ? exl * (1.f - exl * (0.5f - exl * (0.33333334f - 0.25f * exl))) : __logf(1.f + exl);
;     float Ap = 1.f, Bp = 0.f;
; #pragma unroll
;     for (int q = 0; q < 16; ++q) {
;       const int tt = d == 0 ? q : 15 - q;
;       const float r = sigmoidf_(pre[0][tt] + ba), ig = sigmoidf_(pre[1][tt] + bx);
;       const float la = -8.f * r * sp;
;       const float a = __expf(la);
;       const float om = fmaxf(1.f - a * a, 0.f);
;       const float bb = sqrtf(om) * (ig * uo[tt]);
;       av[d][tt] = a; bv[d][tt] = bb;
;       Bp = a * Bp + bb; Ap *= a;
;     }
.LBB0_1557:
	s_andn2_saveexec_b64 s[6:7], s[8:9]
	v_mov_b32_e32 v35, 0x3eaaaaab
	v_fmamk_f32 v35, v77, 0xbe800000, v35
	v_fma_f32 v35, -v77, v35, 0.5
	v_fma_f32 v35, -v77, v35, 1.0
	v_mul_f32_e32 v35, v77, v35
	s_or_b64 exec, exec, s[6:7]
	s_waitcnt vmcnt(1) lgkmcnt(14)
	v_add_f32_e32 v50, v50, v31
	v_mul_f32_e32 v50, 0xbfb8aa3b, v50
	v_exp_f32_e32 v50, v50
	s_waitcnt vmcnt(0) lgkmcnt(7)
	v_add_f32_e32 v52, v52, v33
	v_mul_f32_e32 v52, 0xbfb8aa3b, v52
	v_exp_f32_e32 v52, v52
	v_add_f32_e32 v50, 1.0, v50
	v_rcp_f32_e32 v50, v50
	v_mul_u32_u24_e32 v108, 0x410, v75
	v_add_f32_e32 v52, 1.0, v52
	v_rcp_f32_e32 v75, v52
	v_mul_f32_e32 v50, 0xc1000000, v50
	v_mul_f32_e32 v50, v50, v35
	v_mul_f32_e32 v50, 0x3fb8aa3b, v50
	v_exp_f32_e32 v52, v50
	v_add_f32_e32 v51, v51, v31
	v_mul_f32_e32 v51, 0xbfb8aa3b, v51
	v_exp_f32_e32 v51, v51
	v_fma_f32 v50, -v52, v52, 1.0
	v_max_f32_e32 v50, 0, v50
	v_add_f32_e32 v51, 1.0, v51
	v_rcp_f32_e32 v51, v51
	v_add_f32_e32 v53, v53, v33
	v_mul_f32_e32 v53, 0xbfb8aa3b, v53
	v_exp_f32_e32 v53, v53
	v_mul_f32_e32 v51, 0xc1000000, v51
	v_mul_f32_e32 v51, v51, v35
	v_add_f32_e32 v53, 1.0, v53
	v_mul_f32_e32 v51, 0x3fb8aa3b, v51
	v_sqrt_f32_e32 v50, v50
	v_rcp_f32_e32 v77, v53
	v_exp_f32_e32 v53, v51
	v_add_f32_e32 v46, v46, v31
	v_mul_f32_e32 v46, 0xbfb8aa3b, v46
	v_exp_f32_e32 v46, v46
	v_fma_f32 v51, -v53, v53, 1.0
	v_max_f32_e32 v51, 0, v51
	v_add_f32_e32 v46, 1.0, v46
	v_rcp_f32_e32 v46, v46
	s_waitcnt lgkmcnt(6)
	v_add_f32_e32 v48, v48, v33
	v_mul_f32_e32 v48, 0xbfb8aa3b, v48
	v_exp_f32_e32 v48, v48
	v_mul_f32_e32 v46, 0xc1000000, v46
	v_mul_f32_e32 v46, v46, v35
	v_add_f32_e32 v48, 1.0, v48
	v_mul_f32_e32 v46, 0x3fb8aa3b, v46
	v_sqrt_f32_e32 v51, v51
	v_rcp_f32_e32 v78, v48
	v_exp_f32_e32 v48, v46
	v_add_f32_e32 v47, v47, v31
	v_mul_f32_e32 v47, 0xbfb8aa3b, v47
	v_exp_f32_e32 v47, v47
	v_fma_f32 v46, -v48, v48, 1.0
	v_max_f32_e32 v46, 0, v46
	v_add_f32_e32 v47, 1.0, v47
	v_rcp_f32_e32 v47, v47
	v_add_f32_e32 v49, v49, v33
	v_mul_f32_e32 v49, 0xbfb8aa3b, v49
	v_exp_f32_e32 v49, v49
	v_mul_f32_e32 v47, 0xc1000000, v47
	v_mul_f32_e32 v47, v47, v35
	v_mul_f32_e32 v78, v60, v78
	v_add_f32_e32 v49, 1.0, v49
	v_sqrt_f32_e32 v46, v46
	v_mul_f32_e32 v47, 0x3fb8aa3b, v47
	v_mul_f32_e32 v46, v78, v46
	v_rcp_f32_e32 v78, v49
	v_exp_f32_e32 v49, v47
	v_add_f32_e32 v42, v42, v31
	v_mul_f32_e32 v42, 0xbfb8aa3b, v42
	v_exp_f32_e32 v42, v42
	v_fma_f32 v47, -v49, v49, 1.0
	v_max_f32_e32 v47, 0, v47
	v_add_f32_e32 v42, 1.0, v42
	v_rcp_f32_e32 v42, v42
	v_mul_f32_e32 v75, v58, v75
	v_mul_f32_e32 v50, v75, v50
	v_mul_f32_e32 v77, v59, v77
	v_fma_f32 v75, 0, v52, v50
	v_mul_f32_e32 v51, v77, v51
	v_mul_f32_e32 v42, 0xc1000000, v42
	v_fma_f32 v75, v53, v75, v51
	v_sqrt_f32_e32 v47, v47
	v_mul_f32_e32 v78, v62, v78
	v_mul_f32_e32 v42, v42, v35
	v_fma_f32 v75, v48, v75, v46
	v_mul_f32_e32 v47, v78, v47
	v_mul_f32_e32 v42, 0x3fb8aa3b, v42
	v_fma_f32 v78, v49, v75, v47
	v_exp_f32_e32 v75, v42
	v_add_f32_e32 v43, v43, v31
	s_waitcnt lgkmcnt(5)
	v_add_f32_e32 v44, v44, v33
	v_mul_f32_e32 v43, 0xbfb8aa3b, v43
	v_fma_f32 v42, -v75, v75, 1.0
	v_max_f32_e32 v42, 0, v42
	v_mul_f32_e32 v44, 0xbfb8aa3b, v44
	v_exp_f32_e32 v43, v43
	v_exp_f32_e32 v44, v44
	v_mul_f32_e32 v77, v52, v53
	v_add_f32_e32 v43, 1.0, v43
	v_add_f32_e32 v44, 1.0, v44
	v_rcp_f32_e32 v43, v43
	v_rcp_f32_e32 v44, v44
	v_mul_f32_e32 v77, v48, v77
	v_mul_f32_e32 v43, 0xc1000000, v43
	v_mul_f32_e32 v44, v63, v44
	v_mul_f32_e32 v43, v43, v35
	v_sqrt_f32_e32 v42, v42
	v_mul_f32_e32 v77, v49, v77
	v_mul_f32_e32 v44, v44, v42
	v_mul_f32_e32 v43, 0x3fb8aa3b, v43
	v_fma_f32 v42, v75, v78, v44
	v_mul_f32_e32 v78, v75, v77
	v_exp_f32_e32 v77, v43
	v_add_f32_e32 v24, v24, v31
	v_mul_f32_e32 v24, 0xbfb8aa3b, v24
	v_exp_f32_e32 v24, v24
	v_fma_f32 v43, -v77, v77, 1.0
	v_max_f32_e32 v43, 0, v43
	v_add_f32_e32 v24, 1.0, v24
	v_rcp_f32_e32 v24, v24
	v_add_f32_e32 v45, v45, v33
	v_mul_f32_e32 v45, 0xbfb8aa3b, v45
	v_exp_f32_e32 v45, v45
	v_mul_f32_e32 v24, 0xc1000000, v24
	v_mul_f32_e32 v24, v24, v35
	v_mul_f32_e32 v24, 0x3fb8aa3b, v24
	v_add_f32_e32 v45, 1.0, v45
	v_sqrt_f32_e32 v43, v43
	v_exp_f32_e32 v79, v24
	v_rcp_f32_e32 v45, v45
	v_add_f32_e32 v25, v25, v31
	v_mul_f32_e32 v25, 0xbfb8aa3b, v25
	v_fma_f32 v24, -v79, v79, 1.0
	v_mul_f32_e32 v45, v64, v45
	v_max_f32_e32 v24, 0, v24
	v_exp_f32_e32 v25, v25
	v_mul_f32_e32 v45, v45, v43
	v_mul_f32_e32 v43, v77, v78
	v_add_f32_e32 v25, 1.0, v25
	s_waitcnt lgkmcnt(4)
	v_add_f32_e32 v26, v26, v33
	v_rcp_f32_e32 v25, v25
	v_mul_f32_e32 v26, 0xbfb8aa3b, v26
	v_exp_f32_e32 v26, v26
	v_mul_f32_e32 v25, 0xc1000000, v25
	v_mul_f32_e32 v25, v25, v35
	v_add_f32_e32 v26, 1.0, v26
	v_mul_f32_e32 v25, 0x3fb8aa3b, v25
	v_rcp_f32_e32 v26, v26
	v_exp_f32_e32 v81, v25
	v_add_f32_e32 v20, v20, v31
	v_mul_f32_e32 v20, 0xbfb8aa3b, v20
	v_exp_f32_e32 v20, v20
	v_mul_f32_e32 v26, v65, v26
	v_sqrt_f32_e32 v24, v24
	v_fma_f32 v25, -v81, v81, 1.0
	v_fma_f32 v42, v77, v42, v45
	v_mul_f32_e32 v78, v26, v24
	v_max_f32_e32 v25, 0, v25
	v_fma_f32 v24, v79, v42, v78
	v_add_f32_e32 v20, 1.0, v20
	v_rcp_f32_e32 v20, v20
	v_add_f32_e32 v27, v27, v33
	v_mul_f32_e32 v27, 0xbfb8aa3b, v27
	v_exp_f32_e32 v27, v27
	v_mul_f32_e32 v26, v79, v43
	v_mul_f32_e32 v20, 0xc1000000, v20
	v_mul_f32_e32 v20, v20, v35
	v_mul_f32_e32 v20, 0x3fb8aa3b, v20
	v_add_f32_e32 v27, 1.0, v27
	v_exp_f32_e32 v83, v20
	v_rcp_f32_e32 v27, v27
	v_add_f32_e32 v21, v21, v31
	v_mul_f32_e32 v21, 0xbfb8aa3b, v21
	v_fma_f32 v20, -v83, v83, 1.0
	v_exp_f32_e32 v21, v21
	v_sqrt_f32_e32 v25, v25
	v_mul_f32_e32 v27, v66, v27
	v_max_f32_e32 v20, 0, v20
	v_mul_f32_e32 v80, v27, v25
	v_mul_f32_e32 v25, v81, v26
	v_add_f32_e32 v21, 1.0, v21
	s_waitcnt lgkmcnt(3)
; DEVI float sigmoidf_(float x) { return __builtin_amdgcn_rcpf(1.f + __expf(-x)); }
; DEVI f32x4 mfma16(bf16x8 a, bf16x8 b, f32x4 c) { return __builtin_amdgcn_mfma_f32_16x16x32_bf16(a, b, c, 0, 0, 0); }
; DEVI void lru_item(const Params& p, int l, int item, int pass) {
;     ...
;       const u16* wb = WGT + (size_t)((((l * 2 + d) * 2 + mat) * 4 + n) * 64) * 64 + 8 * g;
;       f32x4 acc[4];
; #pragma unroll
;       for (int nt = 0; nt < 4; ++nt) {
;         const bf16x8 B0 = *(const bf16x8*)(wb + (16 * nt + fr) * 64), B1 = *(const bf16x8*)(wb + (16 * nt + fr) * 64 + 32);
;         f32x4 z = {0.f, 0.f, 0.f, 0.f};
;         z = mfma16(A0, B0, z); z = mfma16(A1, B1, z); acc[nt] = z;
;       }
;       asm volatile("s_waitcnt lgkmcnt(0)" ::: "memory");
; #pragma unroll
;       for (int nt = 0; nt < 4; ++nt)
; #pragma unroll
;         for (int j = 0; j < 4; ++j) exw[(4 * g + j) * 65 + 16 * nt + fr] = acc[nt][j];
;     ...
;     for (int q = 0; q < 16; ++q) {
;       const int tt = d == 0 ? q : 15 - q;
;       const float r = sigmoidf_(pre[0][tt] + ba), ig = sigmoidf_(pre[1][tt] + bx);
;       const float la = -8.f * r * sp;
;       const float a = __expf(la);
;       const float om = fmaxf(1.f - a * a, 0.f);
;       const float bb = sqrtf(om) * (ig * uo[tt]);
;       av[d][tt] = a; bv[d][tt] = bb;
;       Bp = a * Bp + bb; Ap *= a;
;     }
;     sm[((d * 8 + tg) * 64 + e) * 2 + 0] = Ap; sm[((d * 8 + tg) * 64 + e) * 2 + 1] = Bp;
	v_add_f32_e32 v22, v22, v33
	v_rcp_f32_e32 v21, v21
	v_mul_f32_e32 v22, 0xbfb8aa3b, v22
	v_exp_f32_e32 v22, v22
	v_mul_f32_e32 v21, 0xc1000000, v21
	v_mul_f32_e32 v21, v21, v35
	v_add_f32_e32 v22, 1.0, v22
	v_mul_f32_e32 v21, 0x3fb8aa3b, v21
	v_rcp_f32_e32 v22, v22
	v_exp_f32_e32 v85, v21
	v_add_f32_e32 v16, v16, v31
	v_mul_f32_e32 v16, 0xbfb8aa3b, v16
	v_exp_f32_e32 v16, v16
	v_mul_f32_e32 v22, v67, v22
	v_sqrt_f32_e32 v20, v20
	v_fma_f32 v21, -v85, v85, 1.0
	v_fma_f32 v24, v81, v24, v80
	v_mul_f32_e32 v82, v22, v20
	v_max_f32_e32 v21, 0, v21
	v_fma_f32 v20, v83, v24, v82
	v_add_f32_e32 v16, 1.0, v16
	v_rcp_f32_e32 v16, v16
	v_add_f32_e32 v23, v23, v33
	v_mul_f32_e32 v23, 0xbfb8aa3b, v23
	v_exp_f32_e32 v23, v23
	v_mul_f32_e32 v22, v83, v25
	v_mul_f32_e32 v16, 0xc1000000, v16
	v_mul_f32_e32 v16, v16, v35
	v_mul_f32_e32 v16, 0x3fb8aa3b, v16
	v_add_f32_e32 v23, 1.0, v23
	v_exp_f32_e32 v87, v16
	v_rcp_f32_e32 v23, v23
	v_add_f32_e32 v17, v17, v31
	v_mul_f32_e32 v17, 0xbfb8aa3b, v17
	v_fma_f32 v16, -v87, v87, 1.0
	v_exp_f32_e32 v17, v17
	v_sqrt_f32_e32 v21, v21
	v_mul_f32_e32 v23, v68, v23
	v_max_f32_e32 v16, 0, v16
	v_mul_f32_e32 v84, v23, v21
	v_mul_f32_e32 v21, v85, v22
	v_add_f32_e32 v17, 1.0, v17
	s_waitcnt lgkmcnt(2)
	v_add_f32_e32 v18, v18, v33
	v_rcp_f32_e32 v17, v17
	v_mul_f32_e32 v18, 0xbfb8aa3b, v18
	v_exp_f32_e32 v18, v18
	v_mul_f32_e32 v17, 0xc1000000, v17
	v_mul_f32_e32 v17, v17, v35
	v_add_f32_e32 v18, 1.0, v18
	v_mul_f32_e32 v17, 0x3fb8aa3b, v17
	v_rcp_f32_e32 v18, v18
	v_exp_f32_e32 v89, v17
	v_add_f32_e32 v10, v10, v31
	v_mul_f32_e32 v10, 0xbfb8aa3b, v10
	v_exp_f32_e32 v10, v10
	v_mul_f32_e32 v18, v69, v18
	v_sqrt_f32_e32 v16, v16
	v_fma_f32 v17, -v89, v89, 1.0
	v_fma_f32 v20, v85, v20, v84
	v_mul_f32_e32 v86, v18, v16
	v_max_f32_e32 v17, 0, v17
	v_fma_f32 v16, v87, v20, v86
	v_add_f32_e32 v10, 1.0, v10
	v_rcp_f32_e32 v10, v10
	v_add_f32_e32 v19, v19, v33
	v_mul_f32_e32 v19, 0xbfb8aa3b, v19
	v_exp_f32_e32 v19, v19
	v_mul_f32_e32 v18, v87, v21
	v_mul_f32_e32 v10, 0xc1000000, v10
	v_mul_f32_e32 v10, v10, v35
	v_mul_f32_e32 v10, 0x3fb8aa3b, v10
	v_add_f32_e32 v19, 1.0, v19
	v_exp_f32_e32 v92, v10
	v_rcp_f32_e32 v19, v19
	v_add_f32_e32 v11, v11, v31
	v_mul_f32_e32 v11, 0xbfb8aa3b, v11
	v_fma_f32 v10, -v92, v92, 1.0
	v_exp_f32_e32 v11, v11
	v_sqrt_f32_e32 v17, v17
	v_mul_f32_e32 v19, v70, v19
	v_max_f32_e32 v10, 0, v10
	v_mul_f32_e32 v88, v19, v17
	v_mul_f32_e32 v17, v89, v18
	v_add_f32_e32 v11, 1.0, v11
	s_waitcnt lgkmcnt(1)
	v_add_f32_e32 v14, v14, v33
	v_rcp_f32_e32 v11, v11
	v_mul_f32_e32 v14, 0xbfb8aa3b, v14
	v_exp_f32_e32 v14, v14
	v_mul_f32_e32 v11, 0xc1000000, v11
	v_mul_f32_e32 v11, v11, v35
	v_add_f32_e32 v14, 1.0, v14
	v_mul_f32_e32 v11, 0x3fb8aa3b, v11
	v_rcp_f32_e32 v14, v14
	v_exp_f32_e32 v95, v11
	v_add_f32_e32 v8, v8, v31
	v_mul_f32_e32 v8, 0xbfb8aa3b, v8
	v_exp_f32_e32 v8, v8
	v_mul_f32_e32 v14, v71, v14
	v_sqrt_f32_e32 v10, v10
	v_fma_f32 v11, -v95, v95, 1.0
	v_fma_f32 v16, v89, v16, v88
	v_mul_f32_e32 v91, v14, v10
	v_max_f32_e32 v11, 0, v11
	v_fma_f32 v10, v92, v16, v91
	v_add_f32_e32 v8, 1.0, v8
	v_rcp_f32_e32 v8, v8
	v_add_f32_e32 v15, v15, v33
	v_mul_f32_e32 v15, 0xbfb8aa3b, v15
	v_exp_f32_e32 v15, v15
	v_mul_f32_e32 v14, v92, v17
	v_mul_f32_e32 v8, 0xc1000000, v8
	v_mul_f32_e32 v8, v8, v35
	v_mul_f32_e32 v8, 0x3fb8aa3b, v8
	v_add_f32_e32 v15, 1.0, v15
	v_exp_f32_e32 v101, v8
	v_rcp_f32_e32 v15, v15
	v_add_f32_e32 v9, v9, v31
	v_mul_f32_e32 v9, 0xbfb8aa3b, v9
	v_exp_f32_e32 v9, v9
	v_fma_f32 v8, -v101, v101, 1.0
	v_mul_f32_e32 v15, v73, v15
	v_sqrt_f32_e32 v11, v11
	v_max_f32_e32 v8, 0, v8
	v_mul_f32_e32 v93, v15, v11
	v_mul_f32_e32 v11, v95, v14
	v_add_f32_e32 v9, 1.0, v9
	v_rcp_f32_e32 v9, v9
	s_waitcnt lgkmcnt(0)
	v_add_f32_e32 v12, v12, v33
	v_mul_f32_e32 v12, 0xbfb8aa3b, v12
	v_exp_f32_e32 v12, v12
	v_mul_f32_e32 v9, 0xc1000000, v9
	v_mul_f32_e32 v9, v9, v35
	v_mul_f32_e32 v9, 0x3fb8aa3b, v9
	v_add_f32_e32 v12, 1.0, v12
	v_exp_f32_e32 v106, v9
	v_rcp_f32_e32 v12, v12
	v_fma_f32 v10, v95, v10, v93
	v_fma_f32 v9, -v106, v106, 1.0
	v_mul_f32_e32 v12, v74, v12
	v_max_f32_e32 v9, 0, v9
	v_sqrt_f32_e32 v8, v8
	s_nop 0
	v_mul_f32_e32 v94, v12, v8
	v_fma_f32 v8, v101, v10, v94
	v_mul_f32_e32 v10, v101, v11
	v_add_f32_e32 v11, v13, v33
	v_mul_f32_e32 v11, 0xbfb8aa3b, v11
	v_exp_f32_e32 v11, v11
	s_nop 0
	v_add_f32_e32 v11, 1.0, v11
	v_rcp_f32_e32 v11, v11
	s_mov_b64 s[0:1], 0x10000
	v_lshl_add_u64 v[24:25], v[28:29], 0, s[0:1]
	v_mul_f32_e32 v11, v72, v11
	v_lshlrev_b32_e32 v212, 1, v107
	v_sqrt_f32_e32 v9, v9
	s_nop 0
	v_mul_f32_e32 v96, v11, v9
	v_fma_f32 v9, v106, v8, v96
	v_mul_f32_e32 v8, v106, v10
	v_lshlrev_b32_e32 v10, 3, v76
	v_add_u32_e32 v76, 0, v10
	v_add_u32_e32 v10, 0x15b00, v76
	ds_write_b64 v10, v[8:9]
	v_lshl_add_u64 v[12:13], v[24:25], 0, v[212:213]
	global_load_dwordx4 v[8:11], v[12:13], off
	s_nop 0
	global_load_dwordx4 v[12:15], v[12:13], off offset:64
	s_waitcnt vmcnt(1)
	v_mfma_f32_16x16x32_bf16 v[8:11], v[4:7], v[8:11], 0
	v_mov_b32_e32 v35, v213
	v_lshl_add_u64 v[16:17], v[24:25], 0, v[34:35]
	v_mov_b32_e32 v31, v213
	s_waitcnt vmcnt(0)
	v_mfma_f32_16x16x32_bf16 v[8:11], v[0:3], v[12:15], v[8:11]
	global_load_dwordx4 v[12:15], v[16:17], off
	s_nop 0
	global_load_dwordx4 v[16:19], v[16:17], off offset:64
	v_lshl_add_u64 v[20:21], v[24:25], 0, v[30:31]
	v_mov_b32_e32 v33, v213
	s_waitcnt vmcnt(1)
	v_mfma_f32_16x16x32_bf16 v[12:15], v[4:7], v[12:15], 0
	v_lshl_add_u64 v[24:25], v[24:25], 0, v[32:33]
	s_mov_b64 s[0:1], 0x18000
	s_waitcnt vmcnt(0)
	v_mfma_f32_16x16x32_bf16 v[12:15], v[0:3], v[16:19], v[12:15]
	global_load_dwordx4 v[16:19], v[20:21], off
	s_nop 0
	global_load_dwordx4 v[20:23], v[20:21], off offset:64
	s_waitcnt vmcnt(1)
; DEVI f32x4 mfma16(bf16x8 a, bf16x8 b, f32x4 c) { return __builtin_amdgcn_mfma_f32_16x16x32_bf16(a, b, c, 0, 0, 0); }
; DEVI void lru_item(const Params& p, int l, int item, int pass) {
;     ...
;       const u16* wb = WGT + (size_t)((((l * 2 + d) * 2 + mat) * 4 + n) * 64) * 64 + 8 * g;
;       f32x4 acc[4];
; #pragma unroll
;       for (int nt = 0; nt < 4; ++nt) {
;         const bf16x8 B0 = *(const bf16x8*)(wb + (16 * nt + fr) * 64), B1 = *(const bf16x8*)(wb + (16 * nt + fr) * 64 + 32);
;         f32x4 z = {0.f, 0.f, 0.f, 0.f};
;         z = mfma16(A0, B0, z); z = mfma16(A1, B1, z); acc[nt] = z;
;       }
;       asm volatile("s_waitcnt lgkmcnt(0)" ::: "memory");
; #pragma unroll
;       for (int nt = 0; nt < 4; ++nt)
; #pragma unroll
;         for (int j = 0; j < 4; ++j) exw[(4 * g + j) * 65 + 16 * nt + fr] = acc[nt][j];
;       asm volatile("s_waitcnt lgkmcnt(0)" ::: "memory");
; #pragma unroll
;       for (int tt = 0; tt < 16; ++tt) pre[mat][tt] = exw[tt * 65 + lane];
;     }
;     const float ba = p.in[14][(l * 2 + d) * 256 + c], bx = p.in[16][(l * 2 + d) * 256 + c];
;     const float lam = p.in[17][(l * 2 + d) * 256 + c];
;     const float exl = __expf(-lam); const float sp = exl < 0.03f ? exl * (1.f - exl * (0.5f - exl * (0.33333334f - 0.25f * exl))) : __logf(1.f + exl);
	v_mfma_f32_16x16x32_bf16 v[16:19], v[4:7], v[16:19], 0
	s_waitcnt vmcnt(0)
	v_mfma_f32_16x16x32_bf16 v[16:19], v[0:3], v[20:23], v[16:19]
	global_load_dwordx4 v[20:23], v[24:25], off
	s_nop 0
	global_load_dwordx4 v[24:27], v[24:25], off offset:64
	s_waitcnt lgkmcnt(0)
	s_waitcnt vmcnt(1)
	v_mfma_f32_16x16x32_bf16 v[20:23], v[4:7], v[20:23], 0
	s_waitcnt vmcnt(0)
	v_mfma_f32_16x16x32_bf16 v[20:23], v[0:3], v[24:27], v[20:23]
	v_add_u32_e32 v24, v90, v108
	v_add_u32_e32 v90, 0xd800, v24
	v_add_u32_e32 v107, 0xdc00, v24
	ds_write2_b32 v90, v8, v12 offset0:64 offset1:80
	ds_write2_b32 v90, v9, v13 offset0:129 offset1:145
	ds_write2_b32 v90, v10, v14 offset0:194 offset1:210
	ds_write2_b32 v107, v11, v15 offset0:3 offset1:19
	s_nop 0
	ds_write2_b32 v90, v16, v20 offset0:96 offset1:112
	ds_write2_b32 v90, v17, v21 offset0:161 offset1:177
	ds_write2_b32 v90, v18, v22 offset0:226 offset1:242
	ds_write2_b32 v107, v19, v23 offset0:35 offset1:51
	v_lshl_add_u64 v[18:19], v[28:29], 0, s[0:1]
	s_waitcnt lgkmcnt(0)
	v_lshl_add_u64 v[22:23], v[18:19], 0, v[212:213]
	ds_read2_b32 v[8:9], v97 offset0:64 offset1:129
	ds_read2_b32 v[10:11], v98 offset0:66 offset1:131
	ds_read2_b32 v[12:13], v99 offset0:68 offset1:133
	ds_read2_b32 v[14:15], v100 offset0:70 offset1:135
	ds_read2_b32 v[16:17], v102 offset0:72 offset1:137
	ds_read2_b32 v[20:21], v103 offset0:74 offset1:139
	ds_read2_b32 v[24:25], v104 offset0:76 offset1:141
	ds_read2_b32 v[42:43], v105 offset0:78 offset1:143
	global_load_dwordx4 v[26:29], v[22:23], off
	global_load_dwordx4 v[108:111], v[22:23], off offset:64
	s_waitcnt vmcnt(1)
	v_mfma_f32_16x16x32_bf16 v[26:29], v[4:7], v[26:29], 0
	v_lshl_add_u64 v[22:23], v[18:19], 0, v[34:35]
	s_mov_b32 s0, 0x3cf5c28f
	s_waitcnt vmcnt(0)
	v_mfma_f32_16x16x32_bf16 v[26:29], v[0:3], v[108:111], v[26:29]
	global_load_dwordx4 v[108:111], v[22:23], off
	global_load_dwordx4 v[112:115], v[22:23], off offset:64
	v_lshl_add_u64 v[22:23], v[18:19], 0, v[30:31]
	v_lshl_add_u64 v[18:19], v[18:19], 0, v[32:33]
	s_waitcnt vmcnt(1)
	v_mfma_f32_16x16x32_bf16 v[108:111], v[4:7], v[108:111], 0
	s_waitcnt vmcnt(0)
	v_mfma_f32_16x16x32_bf16 v[108:111], v[0:3], v[112:115], v[108:111]
	global_load_dwordx4 v[112:115], v[22:23], off
	global_load_dwordx4 v[116:119], v[22:23], off offset:64
	s_waitcnt vmcnt(1)
	v_mfma_f32_16x16x32_bf16 v[112:115], v[4:7], v[112:115], 0
	s_waitcnt vmcnt(0)
	v_mfma_f32_16x16x32_bf16 v[112:115], v[0:3], v[116:119], v[112:115]
	global_load_dwordx4 v[30:33], v[18:19], off
	global_load_dwordx4 v[116:119], v[18:19], off offset:64
	s_waitcnt lgkmcnt(0)
	s_waitcnt vmcnt(1)
	v_mfma_f32_16x16x32_bf16 v[4:7], v[4:7], v[30:33], 0
	s_waitcnt vmcnt(0)
	v_mfma_f32_16x16x32_bf16 v[0:3], v[0:3], v[116:119], v[4:7]
	ds_write2_b32 v90, v26, v108 offset0:64 offset1:80
	ds_write2_b32 v90, v27, v109 offset0:129 offset1:145
	ds_write2_b32 v90, v28, v110 offset0:194 offset1:210
	ds_write2_b32 v107, v29, v111 offset0:3 offset1:19
	s_nop 3
	ds_write2_b32 v90, v112, v0 offset0:96 offset1:112
	ds_write2_b32 v90, v113, v1 offset0:161 offset1:177
	ds_write2_b32 v90, v114, v2 offset0:226 offset1:242
	ds_write2_b32 v107, v115, v3 offset0:35 offset1:51
	s_waitcnt lgkmcnt(0)
	ds_read2_b32 v[0:1], v97 offset0:64 offset1:129
	ds_read2_b32 v[2:3], v98 offset0:66 offset1:131
	ds_read2_b32 v[4:5], v99 offset0:68 offset1:133
	ds_read2_b32 v[6:7], v100 offset0:70 offset1:135
	ds_read2_b32 v[18:19], v102 offset0:72 offset1:137
	ds_read2_b32 v[22:23], v103 offset0:74 offset1:139
	ds_read2_b32 v[26:27], v104 offset0:76 offset1:141
	ds_read2_b32 v[28:29], v105 offset0:78 offset1:143
	global_load_dword v32, v[36:37], off offset:1024
	global_load_dword v31, v[38:39], off offset:1024
	global_load_dword v30, v[40:41], off offset:1024
	s_waitcnt vmcnt(0)
	v_mul_f32_e32 v30, 0xbfb8aa3b, v30
	v_exp_f32_e32 v30, v30
	s_nop 0
	v_cmp_ngt_f32_e32 vcc, s0, v30
	s_and_saveexec_b64 s[0:1], vcc
	s_xor_b64 s[8:9], exec, s[0:1]
	s_cbranch_execz .LBB0_1561
	v_add_f32_e32 v30, 1.0, v30
	v_cmp_gt_f32_e32 vcc, s63, v30
	s_mov_b32 s0, 0x3f317217
	s_nop 0
	v_cndmask_b32_e64 v33, 0, 32, vcc
	v_ldexp_f32 v30, v30, v33
	v_log_f32_e32 v30, v30
	s_nop 0
	v_mul_f32_e32 v33, 0x3f317217, v30
	v_fma_f32 v33, v30, s0, -v33
	v_fmac_f32_e32 v33, 0x3377d1cf, v30
	s_mov_b32 s0, 0x7f800000
	v_fmac_f32_e32 v33, 0x3f317217, v30
	v_cmp_lt_f32_e64 s[6:7], |v30|, s0
	s_nop 1
	v_cndmask_b32_e64 v30, v30, v33, s[6:7]
	v_cndmask_b32_e32 v33, 0, v225, vcc
	v_sub_f32_e32 v33, v30, v33
; DEVI float sigmoidf_(float x) { return __builtin_amdgcn_rcpf(1.f + __expf(-x)); }
; DEVI void lru_item(const Params& p, int l, int item, int pass) {
;     ...
;     const float exl = __expf(-lam); const float sp = exl < 0.03f ? exl * (1.f - exl * (0.5f - exl * (0.33333334f - 0.25f * exl))) : __logf(1.f + exl);
;     float Ap = 1.f, Bp = 0.f;
; #pragma unroll
;     for (int q = 0; q < 16; ++q) {
;       const int tt = d == 0 ? q : 15 - q;
;       const float r = sigmoidf_(pre[0][tt] + ba), ig = sigmoidf_(pre[1][tt] + bx);
;       const float la = -8.f * r * sp;
;       const float a = __expf(la);
;       const float om = fmaxf(1.f - a * a, 0.f);
;       const float bb = sqrtf(om) * (ig * uo[tt]);
;       av[d][tt] = a; bv[d][tt] = bb;
;       Bp = a * Bp + bb; Ap *= a;
;     }
.LBB0_1561:
	s_andn2_saveexec_b64 s[6:7], s[8:9]
	v_mov_b32_e32 v33, 0x3eaaaaab
	v_fmamk_f32 v33, v30, 0xbe800000, v33
	v_fma_f32 v33, -v30, v33, 0.5
	v_fma_f32 v33, -v30, v33, 1.0
	v_mul_f32_e32 v33, v30, v33
	s_or_b64 exec, exec, s[6:7]
	s_waitcnt lgkmcnt(14)
	v_add_f32_e32 v30, v43, v32
	v_mul_f32_e32 v30, 0xbfb8aa3b, v30
	v_exp_f32_e32 v30, v30
	s_waitcnt lgkmcnt(0)
	v_add_f32_e32 v29, v29, v31
	v_mul_f32_e32 v29, 0xbfb8aa3b, v29
	v_exp_f32_e32 v29, v29
	v_add_f32_e32 v30, 1.0, v30
	v_rcp_f32_e32 v30, v30
	v_add_f32_e32 v28, v28, v31
	v_add_f32_e32 v29, 1.0, v29
	v_rcp_f32_e32 v34, v29
	v_mul_f32_e32 v29, 0xc1000000, v30
	v_mul_f32_e32 v29, v29, v33
	v_mul_f32_e32 v29, 0x3fb8aa3b, v29
	v_exp_f32_e32 v29, v29
	v_mul_f32_e32 v34, v72, v34
	v_mul_f32_e32 v28, 0xbfb8aa3b, v28
	v_exp_f32_e32 v28, v28
	v_fma_f32 v30, -v29, v29, 1.0
	v_max_f32_e32 v30, 0, v30
	v_add_f32_e32 v28, 1.0, v28
	v_add_f32_e32 v25, v25, v32
	v_mul_f32_e32 v25, 0xbfb8aa3b, v25
	v_exp_f32_e32 v25, v25
	s_nop 0
	v_add_f32_e32 v25, 1.0, v25
	v_rcp_f32_e32 v25, v25
	v_add_f32_e32 v24, v24, v32
	v_rcp_f32_e32 v36, v28
	v_mul_f32_e32 v25, 0xc1000000, v25
	v_sqrt_f32_e32 v30, v30
	s_nop 0
	v_mul_f32_e32 v30, v34, v30
	v_add_f32_e32 v34, v42, v32
	v_mul_f32_e32 v34, 0xbfb8aa3b, v34
	v_exp_f32_e32 v34, v34
	v_mul_f32_e32 v25, v25, v33
	v_mul_f32_e32 v25, 0x3fb8aa3b, v25
	v_exp_f32_e32 v25, v25
	v_add_f32_e32 v34, 1.0, v34
	v_rcp_f32_e32 v34, v34
	v_mul_f32_e32 v24, 0xbfb8aa3b, v24
	v_exp_f32_e32 v24, v24
	v_add_f32_e32 v27, v27, v31
	v_mul_f32_e32 v28, 0xc1000000, v34
	v_mul_f32_e32 v28, v28, v33
	v_mul_f32_e32 v28, 0x3fb8aa3b, v28
	v_exp_f32_e32 v28, v28
	v_add_f32_e32 v24, 1.0, v24
	v_mul_f32_e32 v27, 0xbfb8aa3b, v27
	v_rcp_f32_e32 v24, v24
	v_fma_f32 v34, -v28, v28, 1.0
	v_max_f32_e32 v34, 0, v34
	v_exp_f32_e32 v27, v27
	v_mul_f32_e32 v24, 0xc1000000, v24
	v_add_f32_e32 v27, 1.0, v27
	v_mul_f32_e32 v24, v24, v33
	v_rcp_f32_e32 v27, v27
	v_mul_f32_e32 v24, 0x3fb8aa3b, v24
	v_exp_f32_e32 v24, v24
	v_mul_f32_e32 v27, v73, v27
	v_add_f32_e32 v21, v21, v32
	v_sqrt_f32_e32 v34, v34
	v_fma_f32 v37, -v25, v25, 1.0
	v_max_f32_e32 v37, 0, v37
	v_mul_f32_e32 v21, 0xbfb8aa3b, v21
	v_exp_f32_e32 v21, v21
	v_add_f32_e32 v26, v26, v31
	v_mul_f32_e32 v26, 0xbfb8aa3b, v26
	v_add_f32_e32 v21, 1.0, v21
	v_rcp_f32_e32 v21, v21
	v_exp_f32_e32 v26, v26
	v_mul_f32_e32 v21, 0xc1000000, v21
	v_add_f32_e32 v26, 1.0, v26
	v_sqrt_f32_e32 v37, v37
	s_nop 0
	v_mul_f32_e32 v27, v27, v37
	v_fma_f32 v37, -v24, v24, 1.0
	v_max_f32_e32 v37, 0, v37
	v_mul_f32_e32 v21, v21, v33
	v_rcp_f32_e32 v26, v26
	v_mul_f32_e32 v21, 0x3fb8aa3b, v21
	v_exp_f32_e32 v21, v21
	v_mul_f32_e32 v26, v71, v26
	v_add_f32_e32 v20, v20, v32
	v_mul_f32_e32 v20, 0xbfb8aa3b, v20
	v_exp_f32_e32 v20, v20
	v_add_f32_e32 v23, v23, v31
	v_sqrt_f32_e32 v37, v37
	s_nop 0
	v_mul_f32_e32 v26, v26, v37
	v_fma_f32 v37, -v21, v21, 1.0
	v_max_f32_e32 v37, 0, v37
	v_add_f32_e32 v20, 1.0, v20
	v_mul_f32_e32 v23, 0xbfb8aa3b, v23
	v_rcp_f32_e32 v20, v20
	v_exp_f32_e32 v23, v23
	v_mul_f32_e32 v20, 0xc1000000, v20
	v_add_f32_e32 v23, 1.0, v23
	v_mul_f32_e32 v20, v20, v33
	v_rcp_f32_e32 v23, v23
	v_mul_f32_e32 v20, 0x3fb8aa3b, v20
	v_exp_f32_e32 v20, v20
	v_mul_f32_e32 v23, v70, v23
	v_add_f32_e32 v17, v17, v32
	v_sqrt_f32_e32 v37, v37
	s_nop 0
	v_mul_f32_e32 v23, v23, v37
	v_fma_f32 v37, -v20, v20, 1.0
	v_mul_f32_e32 v17, 0xbfb8aa3b, v17
	v_max_f32_e32 v37, 0, v37
	v_exp_f32_e32 v17, v17
	v_add_f32_e32 v22, v22, v31
	v_add_f32_e32 v17, 1.0, v17
	v_mul_f32_e32 v22, 0xbfb8aa3b, v22
	v_rcp_f32_e32 v17, v17
	v_exp_f32_e32 v22, v22
	v_mul_f32_e32 v17, 0xc1000000, v17
	v_add_f32_e32 v22, 1.0, v22
	v_mul_f32_e32 v17, v17, v33
	v_rcp_f32_e32 v22, v22
	v_mul_f32_e32 v17, 0x3fb8aa3b, v17
	v_exp_f32_e32 v17, v17
	v_mul_f32_e32 v22, v69, v22
	v_add_f32_e32 v16, v16, v32
	v_sqrt_f32_e32 v37, v37
	s_nop 0
	v_mul_f32_e32 v22, v22, v37
	v_fma_f32 v37, -v17, v17, 1.0
	v_mul_f32_e32 v16, 0xbfb8aa3b, v16
	v_max_f32_e32 v37, 0, v37
	v_exp_f32_e32 v16, v16
	v_add_f32_e32 v19, v19, v31
	v_add_f32_e32 v16, 1.0, v16
	v_mul_f32_e32 v19, 0xbfb8aa3b, v19
	v_rcp_f32_e32 v16, v16
	v_exp_f32_e32 v19, v19
	v_mul_f32_e32 v16, 0xc1000000, v16
	v_add_f32_e32 v19, 1.0, v19
	v_mul_f32_e32 v16, v16, v33
	v_rcp_f32_e32 v19, v19
	v_mul_f32_e32 v16, 0x3fb8aa3b, v16
	v_exp_f32_e32 v16, v16
	v_mul_f32_e32 v19, v68, v19
	v_add_f32_e32 v18, v18, v31
	v_sqrt_f32_e32 v37, v37
	s_nop 0
	v_mul_f32_e32 v19, v19, v37
	v_fma_f32 v37, -v16, v16, 1.0
	v_max_f32_e32 v37, 0, v37
	v_mul_f32_e32 v18, 0xbfb8aa3b, v18
	v_add_f32_e32 v15, v15, v32
	v_exp_f32_e32 v18, v18
	v_mul_f32_e32 v15, 0xbfb8aa3b, v15
	v_exp_f32_e32 v15, v15
	v_add_f32_e32 v7, v7, v31
	v_add_f32_e32 v18, 1.0, v18
	v_mul_f32_e32 v7, 0xbfb8aa3b, v7
	v_rcp_f32_e32 v18, v18
	v_add_f32_e32 v15, 1.0, v15
	v_exp_f32_e32 v7, v7
	v_rcp_f32_e32 v15, v15
	v_mul_f32_e32 v18, v67, v18
	v_add_f32_e32 v7, 1.0, v7
	v_sqrt_f32_e32 v37, v37
	s_nop 0
	v_mul_f32_e32 v18, v18, v37
	v_rcp_f32_e32 v37, v7
	v_mul_f32_e32 v7, 0xc1000000, v15
	v_mul_f32_e32 v7, v7, v33
	v_mul_f32_e32 v7, 0x3fb8aa3b, v7
	v_exp_f32_e32 v7, v7
	v_add_f32_e32 v14, v14, v32
	v_mul_f32_e32 v14, 0xbfb8aa3b, v14
	v_exp_f32_e32 v14, v14
	v_fma_f32 v15, -v7, v7, 1.0
; DEVI float sigmoidf_(float x) { return __builtin_amdgcn_rcpf(1.f + __expf(-x)); }
; DEVI void lru_item(const Params& p, int l, int item, int pass) {
;     ...
;     for (int q = 0; q < 16; ++q) {
;       const int tt = d == 0 ? q : 15 - q;
;       const float r = sigmoidf_(pre[0][tt] + ba), ig = sigmoidf_(pre[1][tt] + bx);
;       const float la = -8.f * r * sp;
;       const float a = __expf(la);
;       const float om = fmaxf(1.f - a * a, 0.f);
;       const float bb = sqrtf(om) * (ig * uo[tt]);
;       av[d][tt] = a; bv[d][tt] = bb;
;       Bp = a * Bp + bb; Ap *= a;
;     }
;     sm[((d * 8 + tg) * 64 + e) * 2 + 0] = Ap; sm[((d * 8 + tg) * 64 + e) * 2 + 1] = Bp;
;   }
;   __syncthreads();
;   if (!pass) {
;     if (tid < 128) {
;       const int d = tid >> 6, ee = tid & 63;
;       float A = 1.f, Bc = 0.f;
;       if (d == 0) { for (int g2 = 0; g2 < 8; ++g2) { const float a = sm[((0 * 8 + g2) * 64 + ee) * 2], bq = sm[((0 * 8 + g2) * 64 + ee) * 2 + 1]; Bc = a * Bc + bq; A *= a; } }
;     ...
;       SUMM[((size_t)d * 272 + ch) * 256 + n * 64 + ee] = make_float2(A, Bc);
;     }
;   } else {
;     float hs[16];
;     { float h = hc[e];
;       for (int g2 = 0; g2 < tg; ++g2) { const float a = sm[((0 * 8 + g2) * 64 + e) * 2], bq = sm[((0 * 8 + g2) * 64 + e) * 2 + 1]; h = a * h + bq; }
	v_max_f32_e32 v15, 0, v15
	v_add_f32_e32 v14, 1.0, v14
	v_rcp_f32_e32 v14, v14
	v_mul_f32_e32 v36, v74, v36
	v_fma_f32 v35, 0, v29, v30
	v_mul_f32_e32 v34, v36, v34
	v_fma_f32 v35, v28, v35, v34
	v_mul_f32_e32 v14, 0xc1000000, v14
	v_fma_f32 v35, v25, v35, v27
	v_mul_f32_e32 v14, v14, v33
	v_fma_f32 v35, v24, v35, v26
	v_mul_f32_e32 v14, 0x3fb8aa3b, v14
	v_fma_f32 v35, v21, v35, v23
	v_exp_f32_e32 v14, v14
	v_fma_f32 v35, v20, v35, v22
	v_fma_f32 v35, v17, v35, v19
	v_mul_f32_e32 v37, v66, v37
	v_sqrt_f32_e32 v15, v15
	v_fma_f32 v35, v16, v35, v18
	v_mul_f32_e32 v15, v37, v15
	v_fma_f32 v37, v7, v35, v15
	v_fma_f32 v35, -v14, v14, 1.0
	v_add_f32_e32 v13, v13, v32
	v_max_f32_e32 v35, 0, v35
	v_mul_f32_e32 v13, 0xbfb8aa3b, v13
	v_exp_f32_e32 v13, v13
	v_add_f32_e32 v6, v6, v31
	v_mul_f32_e32 v6, 0xbfb8aa3b, v6
	v_add_f32_e32 v13, 1.0, v13
	v_exp_f32_e32 v6, v6
	v_rcp_f32_e32 v13, v13
	v_mul_f32_e32 v36, v29, v28
	v_mul_f32_e32 v36, v25, v36
	v_add_f32_e32 v6, 1.0, v6
	v_mul_f32_e32 v13, 0xc1000000, v13
	v_mul_f32_e32 v36, v24, v36
	v_rcp_f32_e32 v6, v6
	v_mul_f32_e32 v13, v13, v33
	v_mul_f32_e32 v36, v21, v36
	v_mul_f32_e32 v13, 0x3fb8aa3b, v13
	v_mul_f32_e32 v36, v20, v36
	v_exp_f32_e32 v13, v13
	v_mul_f32_e32 v36, v17, v36
	v_mul_f32_e32 v36, v16, v36
	v_mul_f32_e32 v6, v65, v6
	v_sqrt_f32_e32 v35, v35
	v_mul_f32_e32 v36, v7, v36
	v_mul_f32_e32 v35, v6, v35
	v_fma_f32 v6, v14, v37, v35
	v_mul_f32_e32 v37, v14, v36
	v_fma_f32 v36, -v13, v13, 1.0
	v_add_f32_e32 v12, v12, v32
	v_max_f32_e32 v36, 0, v36
	v_mul_f32_e32 v12, 0xbfb8aa3b, v12
	v_exp_f32_e32 v12, v12
	v_add_f32_e32 v5, v5, v31
	v_mul_f32_e32 v5, 0xbfb8aa3b, v5
	v_add_f32_e32 v12, 1.0, v12
	v_exp_f32_e32 v5, v5
	v_rcp_f32_e32 v12, v12
	v_add_f32_e32 v5, 1.0, v5
	v_mul_f32_e32 v12, 0xc1000000, v12
	v_rcp_f32_e32 v5, v5
	v_mul_f32_e32 v12, v12, v33
	v_mul_f32_e32 v12, 0x3fb8aa3b, v12
	v_exp_f32_e32 v12, v12
	v_mul_f32_e32 v5, v64, v5
	v_add_f32_e32 v4, v4, v31
	v_sqrt_f32_e32 v36, v36
	s_nop 0
	v_mul_f32_e32 v36, v5, v36
	v_fma_f32 v5, v13, v6, v36
	v_mul_f32_e32 v6, v13, v37
	v_fma_f32 v37, -v12, v12, 1.0
	v_max_f32_e32 v37, 0, v37
	v_mul_f32_e32 v4, 0xbfb8aa3b, v4
	v_exp_f32_e32 v4, v4
	v_add_f32_e32 v3, v3, v31
	v_mul_f32_e32 v3, 0xbfb8aa3b, v3
	v_add_f32_e32 v4, 1.0, v4
	v_rcp_f32_e32 v4, v4
	v_exp_f32_e32 v3, v3
	v_add_f32_e32 v2, v2, v31
	v_mul_f32_e32 v4, v63, v4
	v_add_f32_e32 v3, 1.0, v3
	v_sqrt_f32_e32 v37, v37
	s_nop 0
	v_mul_f32_e32 v37, v4, v37
	v_fma_f32 v4, v12, v5, v37
	v_mul_f32_e32 v5, v12, v6
	v_add_f32_e32 v6, v11, v32
	v_mul_f32_e32 v6, 0xbfb8aa3b, v6
	v_exp_f32_e32 v6, v6
	v_rcp_f32_e32 v11, v3
	v_mul_f32_e32 v2, 0xbfb8aa3b, v2
	v_exp_f32_e32 v2, v2
	v_add_f32_e32 v6, 1.0, v6
	v_rcp_f32_e32 v6, v6
	v_mul_f32_e32 v11, v62, v11
	v_add_f32_e32 v2, 1.0, v2
	v_add_f32_e32 v1, v1, v31
	v_mul_f32_e32 v3, 0xc1000000, v6
	v_mul_f32_e32 v3, v3, v33
	v_mul_f32_e32 v3, 0x3fb8aa3b, v3
	v_exp_f32_e32 v3, v3
	v_mul_f32_e32 v1, 0xbfb8aa3b, v1
	v_exp_f32_e32 v1, v1
	v_add_f32_e32 v0, v0, v31
	v_fma_f32 v6, -v3, v3, 1.0
	v_max_f32_e32 v6, 0, v6
	v_add_f32_e32 v1, 1.0, v1
	v_mul_f32_e32 v5, v3, v5
	v_mul_f32_e32 v0, 0xbfb8aa3b, v0
	v_exp_f32_e32 v0, v0
	s_nop 0
	v_add_f32_e32 v0, 1.0, v0
	s_nop 1
	s_nop 1
	v_sqrt_f32_e32 v6, v6
	s_nop 0
	v_mul_f32_e32 v38, v11, v6
	v_add_f32_e32 v6, v10, v32
	v_mul_f32_e32 v6, 0xbfb8aa3b, v6
	v_exp_f32_e32 v6, v6
	v_rcp_f32_e32 v10, v2
	v_fma_f32 v4, v3, v4, v38
	v_add_f32_e32 v6, 1.0, v6
	v_rcp_f32_e32 v6, v6
	v_mul_f32_e32 v10, v60, v10
	v_mul_f32_e32 v2, 0xc1000000, v6
	v_mul_f32_e32 v2, v2, v33
	v_mul_f32_e32 v2, 0x3fb8aa3b, v2
	v_exp_f32_e32 v2, v2
	s_nop 0
	v_fma_f32 v6, -v2, v2, 1.0
	v_max_f32_e32 v6, 0, v6
	v_mul_f32_e32 v5, v2, v5
	s_nop 0
	s_nop 0
	s_nop 1
	s_nop 1
	v_sqrt_f32_e32 v6, v6
	s_nop 0
	v_mul_f32_e32 v39, v10, v6
	v_add_f32_e32 v6, v9, v32
	v_mul_f32_e32 v6, 0xbfb8aa3b, v6
	v_exp_f32_e32 v6, v6
	v_rcp_f32_e32 v9, v1
	v_fma_f32 v4, v2, v4, v39
	v_add_f32_e32 v6, 1.0, v6
	v_rcp_f32_e32 v6, v6
	v_mul_f32_e32 v9, v59, v9
	v_mul_f32_e32 v1, 0xc1000000, v6
	v_mul_f32_e32 v1, v1, v33
	v_mul_f32_e32 v1, 0x3fb8aa3b, v1
	v_exp_f32_e32 v1, v1
	s_nop 0
	v_fma_f32 v6, -v1, v1, 1.0
	v_max_f32_e32 v6, 0, v6
	s_nop 0
	s_nop 0
	s_nop 0
	s_nop 1
	s_nop 1
	v_sqrt_f32_e32 v6, v6
	s_nop 0
	v_mul_f32_e32 v40, v9, v6
	v_mul_f32_e32 v6, v1, v5
	v_add_f32_e32 v5, v8, v32
	v_mul_f32_e32 v5, 0xbfb8aa3b, v5
	v_exp_f32_e32 v5, v5
	v_rcp_f32_e32 v8, v0
	v_fma_f32 v4, v1, v4, v40
	v_add_f32_e32 v5, 1.0, v5
	v_rcp_f32_e32 v5, v5
	v_mul_f32_e32 v8, v58, v8
	v_mul_f32_e32 v0, 0xc1000000, v5
	v_mul_f32_e32 v0, v0, v33
	v_mul_f32_e32 v0, 0x3fb8aa3b, v0
	v_exp_f32_e32 v0, v0
	s_nop 0
	v_fma_f32 v5, -v0, v0, 1.0
	v_max_f32_e32 v5, 0, v5
	s_nop 0
	s_nop 0
	s_nop 0
	s_nop 1
	s_nop 1
	v_sqrt_f32_e32 v5, v5
	s_nop 0
	v_mul_f32_e32 v31, v8, v5
	v_fma_f32 v5, v0, v4, v31
	v_mul_f32_e32 v4, v0, v6
	v_add_u32_e32 v6, 0x16b00, v76
	ds_write_b64 v6, v[4:5]
	v_lshl_add_u32 v4, v57, 2, 0
	v_add_u32_e32 v4, 0x17b00, v4
	s_waitcnt lgkmcnt(0)
	s_barrier
	ds_read_b32 v5, v4
	v_cmp_lt_i32_e32 vcc, 0, v56
	s_and_saveexec_b64 s[6:7], vcc
	s_cbranch_execz .LBB0_1567
	v_readlane_b32 s0, v255, 8
	s_mov_b64 s[8:9], 0
	v_mov_b32_e32 v8, v56
	v_lshl_add_u32 v6, v57, 3, s0
